# speedup vs baseline: 1.0073x; 1.0059x over previous
; #define LDA(dst, b, h) _Pragma("unroll") for (int m = 0; m < 4; ++m) _Pragma("unroll") for (int k = 0; k < 2; ++k) \
;     dst[m][k] = *reinterpret_cast<const bf16x8*>((char*)SA(b, h) + lds_byte(wr * 64 + m * 16 + fr, k * 32 + fq * 8))
; #define LDB(dst, b, h) _Pragma("unroll") for (int n = 0; n < 2; ++n) _Pragma("unroll") for (int k = 0; k < 2; ++k) \
;     dst[n][k] = *reinterpret_cast<const bf16x8*>((char*)SB(b, h) + lds_byte(wc * 32 + n * 16 + fr, k * 32 + fq * 8))
; #define WAIT_L(n) asm volatile("s_waitcnt lgkmcnt(" #n ")" ::: "memory")
; #define BAR __builtin_amdgcn_s_barrier()
; #define SCHED __builtin_amdgcn_sched_barrier(0)
; template <int MODE>
; __device__ __forceinline__ void gemm_phase(int s, char* lds, const int wave) {
;     ...
;         LDB(B0, 0, 0); SCHED; LDA(At, 0, 0); STAGE(SA(1, 1), Acur, HALF, t + 1);
;         WAIT_L(8); BAR; WAIT_L(0); MMA(0, 0, At, B0); BAR; SCHED;
;         LDB(B1, 0, 1); STAGE(SB(0, 0), B2, 0, k2);
;         BAR; WAIT_L(0); MMA(0, 1, At, B1); BAR;
;         LDA(At, 0, 1); STAGE(SA(0, 0), A2, 0, k2);
;         BAR; WAIT_L(0); MMA(1, 0, At, B0); BAR; SCHED;
.LBB0_33:
	ds_read_b128 v[166:169], v157
	ds_read_b128 v[170:173], v157 offset:1024
	ds_read_b128 v[174:177], v157 offset:2048
	ds_read_b128 v[178:181], v157 offset:3072
	s_add_i32 s5, s5, 2
	s_cmp_gt_u32 s5, 29
	s_cselect_b64 s[40:41], -1, 0
	s_and_b64 vcc, s[40:41], exec
	s_cselect_b32 s44, s9, s15
	s_cselect_b32 s45, s8, s14
	v_add_u32_e32 v0, 0xc000, v145
	ds_read_b128 v[182:185], v158
	ds_read_b128 v[198:201], v158 offset:1024
	ds_read_b128 v[202:205], v159
	ds_read_b128 v[206:209], v159 offset:1024
	ds_read_b128 v[210:213], v160
	ds_read_b128 v[214:217], v160 offset:1024
	ds_read_b128 v[218:221], v161
	ds_read_b128 v[222:225], v161 offset:1024
	v_readfirstlane_b32 s30, v0
	v_add_u32_e32 v0, 0xe000, v145
	s_mov_b32 m0, s30
	v_readfirstlane_b32 s30, v0
	global_load_lds_dwordx4 v[140:141], off
	s_mov_b32 m0, s30
	s_nop 0
	global_load_lds_dwordx4 v[138:139], off
	s_waitcnt lgkmcnt(8)
	s_barrier
	s_waitcnt lgkmcnt(0)
	s_waitcnt lgkmcnt(0)
	v_mfma_f32_16x16x32_bf16 v[126:129], v[166:169], v[182:185], v[126:129]
	v_mfma_f32_16x16x32_bf16 v[118:121], v[174:177], v[182:185], v[118:121]
	v_mfma_f32_16x16x32_bf16 v[110:113], v[166:169], v[202:205], v[110:113]
	v_mfma_f32_16x16x32_bf16 v[102:105], v[174:177], v[202:205], v[102:105]
	v_mfma_f32_16x16x32_bf16 v[94:97], v[166:169], v[210:213], v[94:97]
	v_mfma_f32_16x16x32_bf16 v[86:89], v[174:177], v[210:213], v[86:89]
	v_mfma_f32_16x16x32_bf16 v[78:81], v[166:169], v[218:221], v[78:81]
	v_mfma_f32_16x16x32_bf16 v[70:73], v[174:177], v[218:221], v[70:73]
	v_mfma_f32_16x16x32_bf16 v[126:129], v[170:173], v[198:201], v[126:129]
	v_mfma_f32_16x16x32_bf16 v[118:121], v[178:181], v[198:201], v[118:121]
	v_mfma_f32_16x16x32_bf16 v[110:113], v[170:173], v[206:209], v[110:113]
	v_mfma_f32_16x16x32_bf16 v[102:105], v[178:181], v[206:209], v[102:105]
	v_mfma_f32_16x16x32_bf16 v[94:97], v[170:173], v[214:217], v[94:97]
	v_mfma_f32_16x16x32_bf16 v[86:89], v[178:181], v[214:217], v[86:89]
	v_mfma_f32_16x16x32_bf16 v[78:81], v[170:173], v[222:225], v[78:81]
	v_mfma_f32_16x16x32_bf16 v[70:73], v[178:181], v[222:225], v[70:73]
	s_barrier
	s_cselect_b32 s30, 0, s7
	s_cselect_b32 s46, s11, s51
	s_cselect_b32 s47, s10, s50
	s_lshl_b64 s[40:41], s[30:31], 1
	s_add_u32 s42, s47, s40
	s_addc_u32 s43, s46, s41
	v_readfirstlane_b32 s52, v143
	v_lshl_add_u64 v[242:243], s[42:43], 0, v[130:131]
	s_mov_b32 m0, s52
	v_lshl_add_u64 v[244:245], s[42:43], 0, v[132:133]
	v_readfirstlane_b32 s42, v144
	ds_read_b128 v[226:229], v162
	ds_read_b128 v[230:233], v162 offset:1024
	ds_read_b128 v[234:237], v162 offset:2048
	ds_read_b128 v[238:241], v162 offset:3072
	global_load_lds_dwordx4 v[242:243], off
	s_mov_b32 m0, s42
	s_nop 0
	global_load_lds_dwordx4 v[244:245], off
	s_barrier
	s_waitcnt lgkmcnt(0)
	s_waitcnt lgkmcnt(0)
	v_mfma_f32_16x16x32_bf16 v[122:125], v[226:229], v[182:185], v[122:125]
	v_mfma_f32_16x16x32_bf16 v[114:117], v[234:237], v[182:185], v[114:117]
	v_mfma_f32_16x16x32_bf16 v[106:109], v[226:229], v[202:205], v[106:109]
	v_mfma_f32_16x16x32_bf16 v[98:101], v[234:237], v[202:205], v[98:101]
	v_mfma_f32_16x16x32_bf16 v[90:93], v[226:229], v[210:213], v[90:93]
	v_mfma_f32_16x16x32_bf16 v[82:85], v[234:237], v[210:213], v[82:85]
	v_mfma_f32_16x16x32_bf16 v[74:77], v[226:229], v[218:221], v[74:77]
	v_mfma_f32_16x16x32_bf16 v[66:69], v[234:237], v[218:221], v[66:69]
	v_mfma_f32_16x16x32_bf16 v[122:125], v[230:233], v[198:201], v[122:125]
	v_mfma_f32_16x16x32_bf16 v[114:117], v[238:241], v[198:201], v[114:117]
	v_mfma_f32_16x16x32_bf16 v[106:109], v[230:233], v[206:209], v[106:109]
	v_mfma_f32_16x16x32_bf16 v[98:101], v[238:241], v[206:209], v[98:101]
	v_mfma_f32_16x16x32_bf16 v[90:93], v[230:233], v[214:217], v[90:93]
	v_mfma_f32_16x16x32_bf16 v[82:85], v[238:241], v[214:217], v[82:85]
	v_mfma_f32_16x16x32_bf16 v[74:77], v[230:233], v[222:225], v[74:77]
	v_mfma_f32_16x16x32_bf16 v[66:69], v[238:241], v[222:225], v[66:69]
	s_add_u32 s42, s45, s40
	s_addc_u32 s43, s44, s41
	v_readfirstlane_b32 s44, v145
	v_lshl_add_u64 v[246:247], s[42:43], 0, v[130:131]
	s_mov_b32 m0, s44
	v_readfirstlane_b32 s44, v146
	s_barrier
	ds_read_b128 v[182:185], v158 offset:16384
	ds_read_b128 v[198:201], v158 offset:17408
	ds_read_b128 v[202:205], v159 offset:16384
	ds_read_b128 v[206:209], v159 offset:17408
	ds_read_b128 v[210:213], v160 offset:16384
	ds_read_b128 v[214:217], v160 offset:17408
	ds_read_b128 v[218:221], v161 offset:16384
	ds_read_b128 v[222:225], v161 offset:17408
	global_load_lds_dwordx4 v[246:247], off
	v_lshl_add_u64 v[248:249], s[42:43], 0, v[132:133]
	s_mov_b32 m0, s44
	s_nop 0
	global_load_lds_dwordx4 v[248:249], off
	s_barrier
	s_waitcnt lgkmcnt(0)
	s_waitcnt lgkmcnt(0)
	v_mfma_f32_16x16x32_bf16 v[62:65], v[166:169], v[182:185], v[62:65]
	v_mfma_f32_16x16x32_bf16 v[54:57], v[174:177], v[182:185], v[54:57]
	v_mfma_f32_16x16x32_bf16 v[46:49], v[166:169], v[202:205], v[46:49]
	v_mfma_f32_16x16x32_bf16 v[38:41], v[174:177], v[202:205], v[38:41]
	v_mfma_f32_16x16x32_bf16 v[30:33], v[166:169], v[210:213], v[30:33]
	v_mfma_f32_16x16x32_bf16 v[22:25], v[174:177], v[210:213], v[22:25]
	v_mfma_f32_16x16x32_bf16 v[14:17], v[166:169], v[218:221], v[14:17]
	v_mfma_f32_16x16x32_bf16 v[6:9], v[174:177], v[218:221], v[6:9]
	v_mfma_f32_16x16x32_bf16 v[62:65], v[170:173], v[198:201], v[62:65]
	v_mfma_f32_16x16x32_bf16 v[54:57], v[178:181], v[198:201], v[54:57]
	v_mfma_f32_16x16x32_bf16 v[46:49], v[170:173], v[206:209], v[46:49]
	v_mfma_f32_16x16x32_bf16 v[38:41], v[178:181], v[206:209], v[38:41]
	v_mfma_f32_16x16x32_bf16 v[30:33], v[170:173], v[214:217], v[30:33]
	v_mfma_f32_16x16x32_bf16 v[22:25], v[178:181], v[214:217], v[22:25]
	v_mfma_f32_16x16x32_bf16 v[14:17], v[170:173], v[222:225], v[14:17]
	v_mfma_f32_16x16x32_bf16 v[6:9], v[178:181], v[222:225], v[6:9]
	s_barrier
; #define LDA(dst, b, h) _Pragma("unroll") for (int m = 0; m < 4; ++m) _Pragma("unroll") for (int k = 0; k < 2; ++k) \
;     dst[m][k] = *reinterpret_cast<const bf16x8*>((char*)SA(b, h) + lds_byte(wr * 64 + m * 16 + fr, k * 32 + fq * 8))
; #define LDB(dst, b, h) _Pragma("unroll") for (int n = 0; n < 2; ++n) _Pragma("unroll") for (int k = 0; k < 2; ++k) \
;     dst[n][k] = *reinterpret_cast<const bf16x8*>((char*)SB(b, h) + lds_byte(wc * 32 + n * 16 + fr, k * 32 + fq * 8))
; #define WAIT_V(n) asm volatile("s_waitcnt vmcnt(" #n ")" ::: "memory")
; #define WAIT_L(n) asm volatile("s_waitcnt lgkmcnt(" #n ")" ::: "memory")
; #define BAR __builtin_amdgcn_s_barrier()
; #define SCHED __builtin_amdgcn_sched_barrier(0)
; template <int MODE>
; __device__ __forceinline__ void gemm_phase(int s, char* lds, const int wave) {
;     ...
;         STAGE(SB(0, 1), B2, HALF, k2);
;         WAIT_V(6); BAR; MMA(1, 1, At, B1); BAR;
;         LDB(B0, 1, 0); SCHED; LDA(At, 1, 0); STAGE(SA(0, 1), A2, HALF, k2);
;         WAIT_L(8); BAR; WAIT_L(0); MMA(0, 0, At, B0); BAR; SCHED;
;         LDB(B1, 1, 1); STAGE(SB(1, 0), B2, 0, k2 + 1);
;         BAR; WAIT_L(0); MMA(0, 1, At, B1); BAR;
	s_add_u32 s52, s47, 0x80000
	s_addc_u32 s53, s46, 0
	s_add_u32 s40, s52, s40
	s_addc_u32 s41, s53, s41
	v_readfirstlane_b32 s44, v147
	v_lshl_add_u64 v[166:167], s[40:41], 0, v[130:131]
	s_mov_b32 m0, s44
	s_nop 0
	global_load_lds_dwordx4 v[166:167], off
	v_lshl_add_u64 v[166:167], s[40:41], 0, v[132:133]
	v_readfirstlane_b32 s40, v148
	s_mov_b32 m0, s40
	s_nop 0
	global_load_lds_dwordx4 v[166:167], off
	s_waitcnt vmcnt(6)
	s_barrier
	v_mfma_f32_16x16x32_bf16 v[58:61], v[226:229], v[182:185], v[58:61]
	v_mfma_f32_16x16x32_bf16 v[50:53], v[234:237], v[182:185], v[50:53]
	v_mfma_f32_16x16x32_bf16 v[42:45], v[226:229], v[202:205], v[42:45]
	v_mfma_f32_16x16x32_bf16 v[34:37], v[234:237], v[202:205], v[34:37]
	v_mfma_f32_16x16x32_bf16 v[26:29], v[226:229], v[210:213], v[26:29]
	v_mfma_f32_16x16x32_bf16 v[18:21], v[234:237], v[210:213], v[18:21]
	v_mfma_f32_16x16x32_bf16 v[10:13], v[226:229], v[218:221], v[10:13]
	v_mfma_f32_16x16x32_bf16 v[2:5], v[234:237], v[218:221], v[2:5]
	v_mfma_f32_16x16x32_bf16 v[58:61], v[230:233], v[198:201], v[58:61]
	v_mfma_f32_16x16x32_bf16 v[50:53], v[238:241], v[198:201], v[50:53]
	v_mfma_f32_16x16x32_bf16 v[42:45], v[230:233], v[206:209], v[42:45]
	v_mfma_f32_16x16x32_bf16 v[34:37], v[238:241], v[206:209], v[34:37]
	v_mfma_f32_16x16x32_bf16 v[26:29], v[230:233], v[214:217], v[26:29]
	v_mfma_f32_16x16x32_bf16 v[18:21], v[238:241], v[214:217], v[18:21]
	v_mfma_f32_16x16x32_bf16 v[10:13], v[230:233], v[222:225], v[10:13]
	v_mfma_f32_16x16x32_bf16 v[2:5], v[238:241], v[222:225], v[2:5]
	s_barrier
	ds_read_b128 v[166:169], v163
	ds_read_b128 v[170:173], v163 offset:1024
	ds_read_b128 v[174:177], v163 offset:2048
	ds_read_b128 v[178:181], v163 offset:3072
	s_add_u32 s40, s42, 0x80000
	s_addc_u32 s41, s43, 0
	v_readfirstlane_b32 s42, v149
	v_lshl_add_u64 v[226:227], s[40:41], 0, v[130:131]
	s_mov_b32 m0, s42
	ds_read_b128 v[182:185], v158 offset:32768
	ds_read_b128 v[198:201], v158 offset:33792
	ds_read_b128 v[202:205], v159 offset:32768
	ds_read_b128 v[206:209], v159 offset:33792
	ds_read_b128 v[210:213], v160 offset:32768
	ds_read_b128 v[214:217], v160 offset:33792
	ds_read_b128 v[218:221], v161 offset:32768
	ds_read_b128 v[222:225], v161 offset:33792
	global_load_lds_dwordx4 v[226:227], off
	v_lshl_add_u64 v[226:227], s[40:41], 0, v[132:133]
	v_readfirstlane_b32 s40, v150
	s_mov_b32 m0, s40
	s_nop 0
	global_load_lds_dwordx4 v[226:227], off
	s_waitcnt lgkmcnt(8)
	s_barrier
	s_waitcnt lgkmcnt(0)
	s_waitcnt lgkmcnt(0)
	v_mfma_f32_16x16x32_bf16 v[126:129], v[166:169], v[182:185], v[126:129]
	v_mfma_f32_16x16x32_bf16 v[118:121], v[174:177], v[182:185], v[118:121]
	v_mfma_f32_16x16x32_bf16 v[110:113], v[166:169], v[202:205], v[110:113]
	v_mfma_f32_16x16x32_bf16 v[102:105], v[174:177], v[202:205], v[102:105]
	v_mfma_f32_16x16x32_bf16 v[94:97], v[166:169], v[210:213], v[94:97]
	v_mfma_f32_16x16x32_bf16 v[86:89], v[174:177], v[210:213], v[86:89]
	v_mfma_f32_16x16x32_bf16 v[78:81], v[166:169], v[218:221], v[78:81]
	v_mfma_f32_16x16x32_bf16 v[70:73], v[174:177], v[218:221], v[70:73]
	v_mfma_f32_16x16x32_bf16 v[126:129], v[170:173], v[198:201], v[126:129]
	v_mfma_f32_16x16x32_bf16 v[118:121], v[178:181], v[198:201], v[118:121]
	v_mfma_f32_16x16x32_bf16 v[110:113], v[170:173], v[206:209], v[110:113]
	v_mfma_f32_16x16x32_bf16 v[102:105], v[178:181], v[206:209], v[102:105]
	v_mfma_f32_16x16x32_bf16 v[94:97], v[170:173], v[214:217], v[94:97]
	v_mfma_f32_16x16x32_bf16 v[86:89], v[178:181], v[214:217], v[86:89]
	v_mfma_f32_16x16x32_bf16 v[78:81], v[170:173], v[222:225], v[78:81]
	v_mfma_f32_16x16x32_bf16 v[70:73], v[178:181], v[222:225], v[70:73]
	s_barrier
	v_readfirstlane_b32 s40, v151
	v_lshl_add_u64 v[242:243], v[242:243], 0, s[18:19]
	s_mov_b32 m0, s40
	v_readfirstlane_b32 s40, v152
	ds_read_b128 v[226:229], v164
	ds_read_b128 v[230:233], v164 offset:1024
	ds_read_b128 v[234:237], v164 offset:2048
	ds_read_b128 v[238:241], v164 offset:3072
	global_load_lds_dwordx4 v[242:243], off
	v_lshl_add_u64 v[242:243], v[244:245], 0, s[18:19]
	s_mov_b32 m0, s40
	s_or_b32 s30, s30, 64
	global_load_lds_dwordx4 v[242:243], off
	s_barrier
	s_waitcnt lgkmcnt(0)
	s_waitcnt lgkmcnt(0)
	v_mfma_f32_16x16x32_bf16 v[122:125], v[226:229], v[182:185], v[122:125]
	v_mfma_f32_16x16x32_bf16 v[114:117], v[234:237], v[182:185], v[114:117]
	v_mfma_f32_16x16x32_bf16 v[106:109], v[226:229], v[202:205], v[106:109]
	v_mfma_f32_16x16x32_bf16 v[98:101], v[234:237], v[202:205], v[98:101]
	v_mfma_f32_16x16x32_bf16 v[90:93], v[226:229], v[210:213], v[90:93]
	v_mfma_f32_16x16x32_bf16 v[82:85], v[234:237], v[210:213], v[82:85]
	v_mfma_f32_16x16x32_bf16 v[74:77], v[226:229], v[218:221], v[74:77]
	v_mfma_f32_16x16x32_bf16 v[66:69], v[234:237], v[218:221], v[66:69]
	v_mfma_f32_16x16x32_bf16 v[122:125], v[230:233], v[198:201], v[122:125]
	v_mfma_f32_16x16x32_bf16 v[114:117], v[238:241], v[198:201], v[114:117]
	v_mfma_f32_16x16x32_bf16 v[106:109], v[230:233], v[206:209], v[106:109]
	v_mfma_f32_16x16x32_bf16 v[98:101], v[238:241], v[206:209], v[98:101]
	v_mfma_f32_16x16x32_bf16 v[90:93], v[230:233], v[214:217], v[90:93]
	v_mfma_f32_16x16x32_bf16 v[82:85], v[238:241], v[214:217], v[82:85]
	v_mfma_f32_16x16x32_bf16 v[74:77], v[230:233], v[222:225], v[74:77]
	v_mfma_f32_16x16x32_bf16 v[66:69], v[238:241], v[222:225], v[66:69]
	v_readfirstlane_b32 s40, v153
	v_lshl_add_u64 v[242:243], v[246:247], 0, s[18:19]
	s_mov_b32 m0, s40
	v_readfirstlane_b32 s40, v154
	s_barrier
; __device__ __forceinline__ float sigmoidf_(float x) { return __builtin_amdgcn_rcpf(1.f + __expf(-x)); }
; #define LDA(dst, b, h) _Pragma("unroll") for (int m = 0; m < 4; ++m) _Pragma("unroll") for (int k = 0; k < 2; ++k) \
;     dst[m][k] = *reinterpret_cast<const bf16x8*>((char*)SA(b, h) + lds_byte(wr * 64 + m * 16 + fr, k * 32 + fq * 8))
; #define WAIT_V(n) asm volatile("s_waitcnt vmcnt(" #n ")" ::: "memory")
; #define WAIT_L(n) asm volatile("s_waitcnt lgkmcnt(" #n ")" ::: "memory")
; #define BAR __builtin_amdgcn_s_barrier()
; #define SCHED __builtin_amdgcn_sched_barrier(0)
; template <int MODE>
; __device__ __forceinline__ void gemm_epilogue(char* ws, const float* __restrict__ xseq, float* __restrict__ oseq, const int pm, const int pn,
;                                               f32x4 (&acc)[2][2][4][2], const int wave) {
;     ...
;     if (MODE == G_GU) {
;       u32x2 w[2];
; #pragma unroll
;       for (int n = 0; n < 2; ++n) { const f32x4 g = acc[ai][0][m][n], u = acc[ai][1][m][n];
;         w[n] = u32x2{cvtpk(g[0] * sigmoidf_(g[0]) * u[0], g[1] * sigmoidf_(g[1]) * u[1]), cvtpk(g[2] * sigmoidf_(g[2]) * u[2], g[3] * sigmoidf_(g[3]) * u[3])}; }
;       store_pair16((bf16*)(ws + OFF_ACT) + (long)row * DFF + pn * 128 + wc * 32, w[0], w[1], fq);
; template <int MODE>
; __device__ __forceinline__ void gemm_phase(int s, char* lds, const int wave) {
;     ...
;         LDA(At, 1, 1); STAGE(SA(1, 0), A2, 0, k2 + 1);
;         BAR; WAIT_L(0); MMA(1, 0, At, B0); BAR; SCHED;
;         STAGE(SB(1, 1), B2, HALF, k2 + 1);
;         WAIT_V(6); BAR; MMA(1, 1, At, B1); BAR;
;       }
;       gemm_epilogue<MODE>(ws, xseq, oseq, pm, pn, acc, wave);
	ds_read_b128 v[182:185], v158 offset:49152
	ds_read_b128 v[198:201], v158 offset:50176
	ds_read_b128 v[202:205], v159 offset:49152
	ds_read_b128 v[206:209], v159 offset:50176
	ds_read_b128 v[210:213], v160 offset:49152
	ds_read_b128 v[214:217], v160 offset:50176
	ds_read_b128 v[218:221], v161 offset:49152
	ds_read_b128 v[222:225], v161 offset:50176
	global_load_lds_dwordx4 v[242:243], off
	v_lshl_add_u64 v[242:243], v[248:249], 0, s[18:19]
	s_mov_b32 m0, s40
	s_nop 0
	global_load_lds_dwordx4 v[242:243], off
	s_barrier
	s_waitcnt lgkmcnt(0)
	s_waitcnt lgkmcnt(0)
	v_mfma_f32_16x16x32_bf16 v[62:65], v[166:169], v[182:185], v[62:65]
	v_mfma_f32_16x16x32_bf16 v[54:57], v[174:177], v[182:185], v[54:57]
	v_mfma_f32_16x16x32_bf16 v[46:49], v[166:169], v[202:205], v[46:49]
	v_mfma_f32_16x16x32_bf16 v[38:41], v[174:177], v[202:205], v[38:41]
	v_mfma_f32_16x16x32_bf16 v[30:33], v[166:169], v[210:213], v[30:33]
	v_mfma_f32_16x16x32_bf16 v[22:25], v[174:177], v[210:213], v[22:25]
	v_mfma_f32_16x16x32_bf16 v[14:17], v[166:169], v[218:221], v[14:17]
	v_mfma_f32_16x16x32_bf16 v[6:9], v[174:177], v[218:221], v[6:9]
	v_mfma_f32_16x16x32_bf16 v[62:65], v[170:173], v[198:201], v[62:65]
	v_mfma_f32_16x16x32_bf16 v[54:57], v[178:181], v[198:201], v[54:57]
	v_mfma_f32_16x16x32_bf16 v[46:49], v[170:173], v[206:209], v[46:49]
	v_mfma_f32_16x16x32_bf16 v[38:41], v[178:181], v[206:209], v[38:41]
	v_mfma_f32_16x16x32_bf16 v[30:33], v[170:173], v[214:217], v[30:33]
	v_mfma_f32_16x16x32_bf16 v[22:25], v[178:181], v[214:217], v[22:25]
	v_mfma_f32_16x16x32_bf16 v[14:17], v[170:173], v[222:225], v[14:17]
	v_mfma_f32_16x16x32_bf16 v[6:9], v[178:181], v[222:225], v[6:9]
	s_barrier
	v_lshl_add_u64 v[166:167], s[52:53], 0, v[130:131]
	s_lshl_b64 s[40:41], s[30:31], 1
	v_readfirstlane_b32 s30, v155
	v_lshl_add_u64 v[166:167], v[166:167], 0, s[40:41]
	s_mov_b32 m0, s30
	v_readfirstlane_b32 s30, v156
	global_load_lds_dwordx4 v[166:167], off
	v_lshl_add_u64 v[166:167], s[52:53], 0, v[132:133]
	v_lshl_add_u64 v[166:167], v[166:167], 0, s[40:41]
	s_mov_b32 m0, s30
	s_nop 0
	global_load_lds_dwordx4 v[166:167], off
	s_waitcnt vmcnt(6)
	s_barrier
	v_mfma_f32_16x16x32_bf16 v[58:61], v[226:229], v[182:185], v[58:61]
	v_mfma_f32_16x16x32_bf16 v[50:53], v[234:237], v[182:185], v[50:53]
	v_mfma_f32_16x16x32_bf16 v[42:45], v[226:229], v[202:205], v[42:45]
	v_mfma_f32_16x16x32_bf16 v[34:37], v[234:237], v[202:205], v[34:37]
	v_mfma_f32_16x16x32_bf16 v[26:29], v[226:229], v[210:213], v[26:29]
	v_mfma_f32_16x16x32_bf16 v[18:21], v[234:237], v[210:213], v[18:21]
	v_mfma_f32_16x16x32_bf16 v[10:13], v[226:229], v[218:221], v[10:13]
	v_mfma_f32_16x16x32_bf16 v[2:5], v[234:237], v[218:221], v[2:5]
	v_mfma_f32_16x16x32_bf16 v[58:61], v[230:233], v[198:201], v[58:61]
	v_mfma_f32_16x16x32_bf16 v[50:53], v[238:241], v[198:201], v[50:53]
	v_mfma_f32_16x16x32_bf16 v[42:45], v[230:233], v[206:209], v[42:45]
	v_mfma_f32_16x16x32_bf16 v[34:37], v[238:241], v[206:209], v[34:37]
	v_mfma_f32_16x16x32_bf16 v[26:29], v[230:233], v[214:217], v[26:29]
	v_mfma_f32_16x16x32_bf16 v[18:21], v[238:241], v[214:217], v[18:21]
	v_mfma_f32_16x16x32_bf16 v[10:13], v[230:233], v[222:225], v[10:13]
	v_mfma_f32_16x16x32_bf16 v[2:5], v[238:241], v[222:225], v[2:5]
	v_lshl_add_u64 v[138:139], v[138:139], 0, s[38:39]
	v_lshl_add_u64 v[140:141], v[140:141], 0, s[38:39]
	s_addk_i32 s7, 0x80
	s_barrier
	s_cbranch_vccz .LBB0_33
	s_lshl_b32 s14, s2, 7
	v_mov_b32_e32 v141, v187
	s_ashr_i32 s15, s14, 31
	s_lshl_b32 s5, s12, 8
	v_ashrrev_i32_e32 v0, 2, v141
	s_lshl_b64 s[14:15], s[14:15], 1
	v_and_b32_e32 v0, 0xffffffc0, v0
	v_and_or_b32 v138, v141, 15, s5
	s_add_u32 s14, s59, s14
	v_add_u32_e32 v140, v138, v0
	s_addc_u32 s15, s60, s15
	v_and_b32_e32 v0, 0xc0, v141
	v_lshl_add_u64 v[138:139], s[14:15], 0, v[0:1]
	v_and_b32_e32 v0, 16, v141
	v_lshrrev_b32_e32 v141, 2, v141
	v_and_b32_e32 v141, 12, v141
	v_add_u32_e32 v165, 12, v141
	v_cmp_eq_u32_e32 vcc, 0, v0
	s_cmpk_gt_i32 s54, 0x20ff
	s_mov_b64 s[50:51], s[10:11]
	v_cndmask_b32_e32 v0, v165, v141, vcc
	v_mul_f32_e32 v141, 0xbfb8aa3b, v126
	v_exp_f32_e32 v141, v141
	v_mul_f32_e32 v165, 0xbfb8aa3b, v127
	v_exp_f32_e32 v165, v165
	v_lshlrev_b32_e32 v0, 1, v0
	v_add_f32_e32 v141, 1.0, v141
	v_rcp_f32_e32 v141, v141
	v_add_f32_e32 v165, 1.0, v165
	v_rcp_f32_e32 v165, v165
	v_lshl_add_u64 v[138:139], v[138:139], 0, v[0:1]
	v_mul_f32_e32 v0, v126, v141
	v_mul_f32_e32 v126, 0xbfb8aa3b, v128
	v_exp_f32_e32 v126, v126
	v_mul_f32_e32 v0, v0, v122
	v_mul_f32_e32 v122, v127, v165
	v_mul_f32_e32 v127, 0xbfb8aa3b, v129
	v_exp_f32_e32 v127, v127
	v_mul_f32_e32 v122, v122, v123
	v_add_f32_e32 v123, 1.0, v126
	v_rcp_f32_e32 v123, v123
	v_add_f32_e32 v126, 1.0, v127
	v_rcp_f32_e32 v126, v126
	v_cvt_pk_bf16_f32 v122, v0, v122
	v_mul_f32_e32 v0, v128, v123
	v_mul_f32_e32 v0, v0, v124
	v_mul_f32_e32 v124, 0xbfb8aa3b, v118
	v_mul_f32_e32 v123, v129, v126
	v_exp_f32_e32 v124, v124
	v_mul_f32_e32 v126, 0xbfb8aa3b, v119
	v_exp_f32_e32 v126, v126
	v_mul_f32_e32 v123, v123, v125
	v_add_f32_e32 v124, 1.0, v124
	v_rcp_f32_e32 v124, v124
	v_add_f32_e32 v125, 1.0, v126
	v_rcp_f32_e32 v125, v125
	v_cvt_pk_bf16_f32 v123, v0, v123
	v_mul_f32_e32 v0, v118, v124
	v_mul_f32_e32 v118, 0xbfb8aa3b, v120
	v_mul_f32_e32 v0, v0, v114
	v_mul_f32_e32 v114, v119, v125
	v_exp_f32_e32 v118, v118
	v_mul_f32_e32 v119, 0xbfb8aa3b, v121
	v_exp_f32_e32 v119, v119
	v_mul_f32_e32 v114, v114, v115
	v_add_f32_e32 v115, 1.0, v118
	v_rcp_f32_e32 v115, v115
	v_add_f32_e32 v118, 1.0, v119
	v_rcp_f32_e32 v118, v118
	v_cvt_pk_bf16_f32 v124, v0, v114
	v_mul_f32_e32 v0, v120, v115
	v_mul_f32_e32 v0, v0, v116
	v_mul_f32_e32 v114, v121, v118
; __device__ __forceinline__ float sigmoidf_(float x) { return __builtin_amdgcn_rcpf(1.f + __expf(-x)); }
; template <int MODE>
; __device__ __forceinline__ void gemm_epilogue(char* ws, const float* __restrict__ xseq, float* __restrict__ oseq, const int pm, const int pn,
;                                               f32x4 (&acc)[2][2][4][2], const int wave) {
;     ...
;     if (MODE == G_GU) {
;       u32x2 w[2];
; #pragma unroll
;       for (int n = 0; n < 2; ++n) { const f32x4 g = acc[ai][0][m][n], u = acc[ai][1][m][n];
;         w[n] = u32x2{cvtpk(g[0] * sigmoidf_(g[0]) * u[0], g[1] * sigmoidf_(g[1]) * u[1]), cvtpk(g[2] * sigmoidf_(g[2]) * u[2], g[3] * sigmoidf_(g[3]) * u[3])}; }
;       store_pair16((bf16*)(ws + OFF_ACT) + (long)row * DFF + pn * 128 + wc * 32, w[0], w[1], fq);
	v_mul_f32_e32 v114, v114, v117
	v_cvt_pk_bf16_f32 v125, v0, v114
	v_mul_f32_e32 v0, 0xbfb8aa3b, v110
	v_exp_f32_e32 v0, v0
	v_mul_f32_e32 v114, 0xbfb8aa3b, v111
	v_exp_f32_e32 v116, v114
	v_mad_i64_i32 v[114:115], s[14:15], v140, s91, v[138:139]
	v_add_f32_e32 v0, 1.0, v0
	v_rcp_f32_e32 v0, v0
	v_add_f32_e32 v116, 1.0, v116
	v_rcp_f32_e32 v116, v116
	v_permlane16_swap_b32_e32 v122, v124
	v_mul_f32_e32 v0, v110, v0
	v_mul_f32_e32 v110, 0xbfb8aa3b, v112
	v_exp_f32_e32 v110, v110
	v_mul_f32_e32 v0, v0, v106
	v_mul_f32_e32 v106, v111, v116
	v_mul_f32_e32 v111, 0xbfb8aa3b, v113
	v_exp_f32_e32 v111, v111
	v_mul_f32_e32 v106, v106, v107
	v_add_f32_e32 v107, 1.0, v110
	v_rcp_f32_e32 v107, v107
	v_add_f32_e32 v110, 1.0, v111
	v_rcp_f32_e32 v110, v110
	v_cvt_pk_bf16_f32 v106, v0, v106
	v_mul_f32_e32 v0, v112, v107
	v_mul_f32_e32 v0, v0, v108
	v_mul_f32_e32 v108, 0xbfb8aa3b, v102
	v_mul_f32_e32 v107, v113, v110
	v_exp_f32_e32 v108, v108
	v_mul_f32_e32 v110, 0xbfb8aa3b, v103
	v_exp_f32_e32 v110, v110
	v_mul_f32_e32 v107, v107, v109
	v_add_f32_e32 v108, 1.0, v108
	v_rcp_f32_e32 v108, v108
	v_add_f32_e32 v109, 1.0, v110
	v_rcp_f32_e32 v109, v109
	v_cvt_pk_bf16_f32 v107, v0, v107
	v_mul_f32_e32 v0, v102, v108
	v_mul_f32_e32 v0, v0, v98
	v_mul_f32_e32 v98, v103, v109
	v_mul_f32_e32 v102, 0xbfb8aa3b, v104
	v_mul_f32_e32 v103, 0xbfb8aa3b, v105
	v_exp_f32_e32 v102, v102
	v_exp_f32_e32 v103, v103
	v_mul_f32_e32 v98, v98, v99
	v_cvt_pk_bf16_f32 v108, v0, v98
	v_add_f32_e32 v99, 1.0, v102
	v_add_f32_e32 v102, 1.0, v103
	v_rcp_f32_e32 v102, v102
	v_rcp_f32_e32 v99, v99
	v_permlane16_swap_b32_e32 v123, v125
	v_mul_f32_e32 v98, v105, v102
	v_mul_f32_e32 v0, v104, v99
	v_mul_f32_e32 v98, v98, v101
	v_mul_f32_e32 v0, v0, v100
	v_cvt_pk_bf16_f32 v109, v0, v98
	v_mul_f32_e32 v98, 0xbfb8aa3b, v94
	v_exp_f32_e32 v100, v98
	v_mul_f32_e32 v98, 0xbfb8aa3b, v95
	v_exp_f32_e32 v101, v98
	v_or_b32_e32 v0, 16, v140
	v_mad_i64_i32 v[98:99], s[14:15], v0, s91, v[138:139]
	v_add_f32_e32 v0, 1.0, v100
	v_rcp_f32_e32 v0, v0
	v_add_f32_e32 v100, 1.0, v101
	v_rcp_f32_e32 v100, v100
	v_permlane16_swap_b32_e32 v106, v108
	v_mul_f32_e32 v0, v94, v0
	v_mul_f32_e32 v94, 0xbfb8aa3b, v96
	v_exp_f32_e32 v94, v94
	v_mul_f32_e32 v0, v0, v90
	v_mul_f32_e32 v90, v95, v100
	v_mul_f32_e32 v95, 0xbfb8aa3b, v97
	v_exp_f32_e32 v95, v95
	v_mul_f32_e32 v90, v90, v91
	v_add_f32_e32 v91, 1.0, v94
	v_rcp_f32_e32 v91, v91
	v_add_f32_e32 v94, 1.0, v95
	v_rcp_f32_e32 v94, v94
	v_cvt_pk_bf16_f32 v90, v0, v90
	v_mul_f32_e32 v0, v96, v91
	v_mul_f32_e32 v0, v0, v92
	v_mul_f32_e32 v92, 0xbfb8aa3b, v86
	v_mul_f32_e32 v91, v97, v94
	v_exp_f32_e32 v92, v92
	v_mul_f32_e32 v94, 0xbfb8aa3b, v87
	v_exp_f32_e32 v94, v94
	v_mul_f32_e32 v91, v91, v93
	v_add_f32_e32 v92, 1.0, v92
	v_rcp_f32_e32 v92, v92
	v_add_f32_e32 v93, 1.0, v94
	v_rcp_f32_e32 v93, v93
	v_cvt_pk_bf16_f32 v91, v0, v91
	v_mul_f32_e32 v0, v86, v92
	v_mul_f32_e32 v0, v0, v82
	v_mul_f32_e32 v82, v87, v93
	v_mul_f32_e32 v86, 0xbfb8aa3b, v88
	v_mul_f32_e32 v87, 0xbfb8aa3b, v89
	v_exp_f32_e32 v86, v86
	v_exp_f32_e32 v87, v87
	v_mul_f32_e32 v82, v82, v83
	v_cvt_pk_bf16_f32 v92, v0, v82
	v_add_f32_e32 v83, 1.0, v86
	v_add_f32_e32 v86, 1.0, v87
	v_rcp_f32_e32 v86, v86
	v_rcp_f32_e32 v83, v83
	v_permlane16_swap_b32_e32 v107, v109
	v_mul_f32_e32 v82, v89, v86
	v_mul_f32_e32 v0, v88, v83
	v_mul_f32_e32 v82, v82, v85
	v_mul_f32_e32 v0, v0, v84
	v_cvt_pk_bf16_f32 v93, v0, v82
	v_mul_f32_e32 v82, 0xbfb8aa3b, v78
	v_exp_f32_e32 v84, v82
	v_mul_f32_e32 v82, 0xbfb8aa3b, v79
	v_exp_f32_e32 v85, v82
	v_or_b32_e32 v0, 32, v140
	v_mad_i64_i32 v[82:83], s[14:15], v0, s91, v[138:139]
	v_add_f32_e32 v0, 1.0, v84
	v_rcp_f32_e32 v0, v0
	v_add_f32_e32 v84, 1.0, v85
	v_rcp_f32_e32 v84, v84
	v_permlane16_swap_b32_e32 v90, v92
	v_mul_f32_e32 v0, v78, v0
	v_mul_f32_e32 v78, 0xbfb8aa3b, v80
	v_exp_f32_e32 v78, v78
	v_mul_f32_e32 v0, v0, v74
	v_mul_f32_e32 v74, v79, v84
	v_mul_f32_e32 v79, 0xbfb8aa3b, v81
	v_exp_f32_e32 v79, v79
	v_mul_f32_e32 v74, v74, v75
	v_add_f32_e32 v75, 1.0, v78
	v_rcp_f32_e32 v75, v75
	v_add_f32_e32 v78, 1.0, v79
	v_rcp_f32_e32 v78, v78
	v_cvt_pk_bf16_f32 v74, v0, v74
	v_mul_f32_e32 v0, v80, v75
	v_mul_f32_e32 v0, v0, v76
	v_mul_f32_e32 v76, 0xbfb8aa3b, v70
	v_mul_f32_e32 v75, v81, v78
	v_exp_f32_e32 v76, v76
	v_mul_f32_e32 v78, 0xbfb8aa3b, v71
	v_exp_f32_e32 v78, v78
	v_mul_f32_e32 v75, v75, v77
	v_add_f32_e32 v76, 1.0, v76
	v_rcp_f32_e32 v76, v76
	v_add_f32_e32 v77, 1.0, v78
	v_rcp_f32_e32 v77, v77
	v_cvt_pk_bf16_f32 v75, v0, v75
	v_mul_f32_e32 v0, v70, v76
	v_mul_f32_e32 v70, 0xbfb8aa3b, v72
	v_mul_f32_e32 v0, v0, v66
	v_mul_f32_e32 v66, v71, v77
	v_exp_f32_e32 v70, v70
	v_mul_f32_e32 v71, 0xbfb8aa3b, v73
	v_exp_f32_e32 v71, v71
	v_mul_f32_e32 v66, v66, v67
	v_add_f32_e32 v67, 1.0, v70
	v_rcp_f32_e32 v67, v67
	v_add_f32_e32 v70, 1.0, v71
	v_rcp_f32_e32 v70, v70
	v_cvt_pk_bf16_f32 v76, v0, v66
	v_mul_f32_e32 v0, v72, v67
	v_mul_f32_e32 v0, v0, v68
	v_mul_f32_e32 v66, v73, v70
	v_mul_f32_e32 v66, v66, v69
	v_cvt_pk_bf16_f32 v77, v0, v66
	v_or_b32_e32 v0, 48, v140
	v_mad_i64_i32 v[66:67], s[14:15], v0, s91, v[138:139]
	v_mul_f32_e32 v0, 0xbfb8aa3b, v62
	v_exp_f32_e32 v0, v0
	v_mul_f32_e32 v68, 0xbfb8aa3b, v63
	v_exp_f32_e32 v68, v68
	v_permlane16_swap_b32_e32 v74, v76
	v_add_f32_e32 v0, 1.0, v0
	v_permlane16_swap_b32_e32 v75, v77
	v_rcp_f32_e32 v0, v0
	global_store_dwordx4 v[66:67], v[74:77], off
	v_add_f32_e32 v66, 1.0, v68
	v_rcp_f32_e32 v66, v66
	v_mul_f32_e32 v0, v62, v0
	v_mul_f32_e32 v62, 0xbfb8aa3b, v64
	v_exp_f32_e32 v62, v62
	v_mul_f32_e32 v0, v0, v58
	v_mul_f32_e32 v58, v63, v66
	v_mul_f32_e32 v63, 0xbfb8aa3b, v65
	v_exp_f32_e32 v63, v63
; __device__ __forceinline__ float sigmoidf_(float x) { return __builtin_amdgcn_rcpf(1.f + __expf(-x)); }
; #define WAIT_V(n) asm volatile("s_waitcnt vmcnt(" #n ")" ::: "memory")
; #define BAR __builtin_amdgcn_s_barrier()
; template <int MODE>
; __device__ __forceinline__ void gemm_epilogue(char* ws, const float* __restrict__ xseq, float* __restrict__ oseq, const int pm, const int pn,
;                                               f32x4 (&acc)[2][2][4][2], const int wave) {
;     ...
;     if (MODE == G_GU) {
;       u32x2 w[2];
; #pragma unroll
;       for (int n = 0; n < 2; ++n) { const f32x4 g = acc[ai][0][m][n], u = acc[ai][1][m][n];
;         w[n] = u32x2{cvtpk(g[0] * sigmoidf_(g[0]) * u[0], g[1] * sigmoidf_(g[1]) * u[1]), cvtpk(g[2] * sigmoidf_(g[2]) * u[2], g[3] * sigmoidf_(g[3]) * u[3])}; }
;       store_pair16((bf16*)(ws + OFF_ACT) + (long)row * DFF + pn * 128 + wc * 32, w[0], w[1], fq);
; template <int MODE>
; __device__ __forceinline__ void gemm_phase(int s, char* lds, const int wave) {
;     ...
;       gemm_epilogue<MODE>(ws, xseq, oseq, pm, pn, acc, wave);
;       if (ntile >= nwg) break;
;       tile = ntile; pm = pm2; pn = pn2; Acur = Anext; Bcur = Bnext;
;     }
;     WAIT_V(0);
;     if (wr == 0) BAR;
;   }
	v_mul_f32_e32 v58, v58, v59
	v_add_f32_e32 v59, 1.0, v62
	v_rcp_f32_e32 v59, v59
	v_add_f32_e32 v62, 1.0, v63
	v_rcp_f32_e32 v62, v62
	v_cvt_pk_bf16_f32 v58, v0, v58
	v_mul_f32_e32 v0, v64, v59
	v_mul_f32_e32 v0, v0, v60
	v_mul_f32_e32 v60, 0xbfb8aa3b, v54
	v_mul_f32_e32 v59, v65, v62
	v_exp_f32_e32 v60, v60
	v_mul_f32_e32 v62, 0xbfb8aa3b, v55
	v_exp_f32_e32 v62, v62
	v_mul_f32_e32 v59, v59, v61
	v_add_f32_e32 v60, 1.0, v60
	v_rcp_f32_e32 v60, v60
	v_add_f32_e32 v61, 1.0, v62
	v_rcp_f32_e32 v61, v61
	v_cvt_pk_bf16_f32 v59, v0, v59
	v_mul_f32_e32 v0, v54, v60
	v_mul_f32_e32 v54, 0xbfb8aa3b, v56
	v_mul_f32_e32 v0, v0, v50
	v_mul_f32_e32 v50, v55, v61
	v_exp_f32_e32 v54, v54
	v_mul_f32_e32 v55, 0xbfb8aa3b, v57
	v_exp_f32_e32 v55, v55
	v_mul_f32_e32 v50, v50, v51
	v_add_f32_e32 v51, 1.0, v54
	v_rcp_f32_e32 v51, v51
	v_add_f32_e32 v54, 1.0, v55
	v_rcp_f32_e32 v54, v54
	v_cvt_pk_bf16_f32 v60, v0, v50
	v_mul_f32_e32 v0, v56, v51
	v_mul_f32_e32 v0, v0, v52
	v_mul_f32_e32 v50, v57, v54
	v_mul_f32_e32 v50, v50, v53
	v_cvt_pk_bf16_f32 v61, v0, v50
	v_mul_f32_e32 v0, 0xbfb8aa3b, v46
	v_exp_f32_e32 v0, v0
	v_mul_f32_e32 v50, 0xbfb8aa3b, v47
	v_exp_f32_e32 v52, v50
	v_add_u32_e32 v67, 0x80, v140
	v_add_f32_e32 v0, 1.0, v0
	v_rcp_f32_e32 v0, v0
	v_add_f32_e32 v52, 1.0, v52
	v_rcp_f32_e32 v52, v52
	v_mad_i64_i32 v[50:51], s[14:15], v67, s91, v[138:139]
	v_mul_f32_e32 v0, v46, v0
	v_mul_f32_e32 v46, 0xbfb8aa3b, v48
	v_exp_f32_e32 v46, v46
	v_mul_f32_e32 v0, v0, v42
	v_mul_f32_e32 v42, v47, v52
	v_mul_f32_e32 v47, 0xbfb8aa3b, v49
	v_exp_f32_e32 v47, v47
	v_mul_f32_e32 v42, v42, v43
	v_add_f32_e32 v43, 1.0, v46
	v_rcp_f32_e32 v43, v43
	v_add_f32_e32 v46, 1.0, v47
	v_rcp_f32_e32 v46, v46
	v_cvt_pk_bf16_f32 v42, v0, v42
	v_mul_f32_e32 v0, v48, v43
	v_mul_f32_e32 v0, v0, v44
	v_mul_f32_e32 v44, 0xbfb8aa3b, v38
	v_mul_f32_e32 v43, v49, v46
	v_exp_f32_e32 v44, v44
	v_mul_f32_e32 v46, 0xbfb8aa3b, v39
	v_exp_f32_e32 v46, v46
	v_mul_f32_e32 v43, v43, v45
	v_add_f32_e32 v44, 1.0, v44
	v_rcp_f32_e32 v44, v44
	v_add_f32_e32 v45, 1.0, v46
	v_rcp_f32_e32 v45, v45
	v_cvt_pk_bf16_f32 v43, v0, v43
	v_mul_f32_e32 v0, v38, v44
	v_mul_f32_e32 v0, v0, v34
	v_mul_f32_e32 v34, v39, v45
	v_mul_f32_e32 v38, 0xbfb8aa3b, v40
	v_mul_f32_e32 v39, 0xbfb8aa3b, v41
	v_exp_f32_e32 v38, v38
	v_exp_f32_e32 v39, v39
	v_mul_f32_e32 v34, v34, v35
	v_cvt_pk_bf16_f32 v44, v0, v34
	v_add_f32_e32 v35, 1.0, v38
	v_add_f32_e32 v38, 1.0, v39
	v_rcp_f32_e32 v38, v38
	v_rcp_f32_e32 v35, v35
	v_permlane16_swap_b32_e32 v91, v93
	v_mul_f32_e32 v34, v41, v38
	v_mul_f32_e32 v0, v40, v35
	v_mul_f32_e32 v34, v34, v37
	v_mul_f32_e32 v0, v0, v36
	v_cvt_pk_bf16_f32 v45, v0, v34
	v_mul_f32_e32 v34, 0xbfb8aa3b, v30
	v_exp_f32_e32 v36, v34
	v_mul_f32_e32 v34, 0xbfb8aa3b, v31
	v_exp_f32_e32 v37, v34
	v_add_u32_e32 v0, 0x90, v140
	v_mad_i64_i32 v[34:35], s[14:15], v0, s91, v[138:139]
	v_add_f32_e32 v0, 1.0, v36
	v_rcp_f32_e32 v0, v0
	v_add_f32_e32 v36, 1.0, v37
	v_rcp_f32_e32 v36, v36
	v_permlane16_swap_b32_e32 v58, v60
	v_mul_f32_e32 v0, v30, v0
	v_mul_f32_e32 v30, 0xbfb8aa3b, v32
	v_exp_f32_e32 v30, v30
	v_mul_f32_e32 v0, v0, v26
	v_mul_f32_e32 v26, v31, v36
	v_mul_f32_e32 v31, 0xbfb8aa3b, v33
	v_exp_f32_e32 v31, v31
	v_mul_f32_e32 v26, v26, v27
	v_add_f32_e32 v27, 1.0, v30
	v_rcp_f32_e32 v27, v27
	v_add_f32_e32 v30, 1.0, v31
	v_rcp_f32_e32 v30, v30
	v_cvt_pk_bf16_f32 v26, v0, v26
	v_mul_f32_e32 v0, v32, v27
	v_mul_f32_e32 v0, v0, v28
	v_mul_f32_e32 v28, 0xbfb8aa3b, v22
	v_mul_f32_e32 v27, v33, v30
	v_exp_f32_e32 v28, v28
	v_mul_f32_e32 v30, 0xbfb8aa3b, v23
	v_exp_f32_e32 v30, v30
	v_mul_f32_e32 v27, v27, v29
	v_add_f32_e32 v28, 1.0, v28
	v_rcp_f32_e32 v28, v28
	v_add_f32_e32 v29, 1.0, v30
	v_rcp_f32_e32 v29, v29
	v_cvt_pk_bf16_f32 v27, v0, v27
	v_mul_f32_e32 v0, v22, v28
	v_mul_f32_e32 v0, v0, v18
	v_mul_f32_e32 v18, v23, v29
	v_mul_f32_e32 v22, 0xbfb8aa3b, v24
	v_mul_f32_e32 v23, 0xbfb8aa3b, v25
	v_exp_f32_e32 v22, v22
	v_exp_f32_e32 v23, v23
	v_mul_f32_e32 v18, v18, v19
	v_cvt_pk_bf16_f32 v28, v0, v18
	v_add_f32_e32 v19, 1.0, v22
	v_add_f32_e32 v22, 1.0, v23
	v_rcp_f32_e32 v22, v22
	v_rcp_f32_e32 v19, v19
	v_permlane16_swap_b32_e32 v59, v61
	v_mul_f32_e32 v18, v25, v22
	v_mul_f32_e32 v0, v24, v19
	v_mul_f32_e32 v18, v18, v21
	v_mul_f32_e32 v0, v0, v20
	v_cvt_pk_bf16_f32 v29, v0, v18
	v_mul_f32_e32 v18, 0xbfb8aa3b, v14
	v_exp_f32_e32 v20, v18
	v_mul_f32_e32 v18, 0xbfb8aa3b, v15
	v_exp_f32_e32 v21, v18
	v_add_u32_e32 v0, 0xa0, v140
	v_mad_i64_i32 v[18:19], s[14:15], v0, s91, v[138:139]
	v_add_f32_e32 v0, 1.0, v20
	v_rcp_f32_e32 v0, v0
	v_add_f32_e32 v20, 1.0, v21
	v_rcp_f32_e32 v20, v20
	v_permlane16_swap_b32_e32 v42, v44
	v_mul_f32_e32 v0, v14, v0
	v_mul_f32_e32 v14, 0xbfb8aa3b, v16
	v_exp_f32_e32 v14, v14
	v_mul_f32_e32 v0, v0, v10
	v_mul_f32_e32 v10, v15, v20
	v_mul_f32_e32 v15, 0xbfb8aa3b, v17
	v_exp_f32_e32 v15, v15
	v_mul_f32_e32 v10, v10, v11
	v_add_f32_e32 v11, 1.0, v14
	v_rcp_f32_e32 v11, v11
	v_add_f32_e32 v14, 1.0, v15
	v_rcp_f32_e32 v14, v14
	v_cvt_pk_bf16_f32 v10, v0, v10
	v_mul_f32_e32 v0, v16, v11
	v_mul_f32_e32 v0, v0, v12
	v_mul_f32_e32 v12, 0xbfb8aa3b, v6
	v_mul_f32_e32 v11, v17, v14
	v_exp_f32_e32 v12, v12
	v_mul_f32_e32 v14, 0xbfb8aa3b, v7
	v_exp_f32_e32 v14, v14
	v_mul_f32_e32 v11, v11, v13
	v_add_f32_e32 v12, 1.0, v12
	v_rcp_f32_e32 v12, v12
	v_add_f32_e32 v13, 1.0, v14
	v_rcp_f32_e32 v13, v13
	v_cvt_pk_bf16_f32 v11, v0, v11
	v_mul_f32_e32 v0, v6, v12
	v_mul_f32_e32 v6, 0xbfb8aa3b, v8
	v_mul_f32_e32 v0, v0, v2
	v_mul_f32_e32 v2, v7, v13
	v_exp_f32_e32 v6, v6
	v_mul_f32_e32 v7, 0xbfb8aa3b, v9
	v_exp_f32_e32 v7, v7
	v_mul_f32_e32 v2, v2, v3
	v_add_f32_e32 v3, 1.0, v6
	v_rcp_f32_e32 v3, v3
	v_add_f32_e32 v6, 1.0, v7
	v_rcp_f32_e32 v6, v6
	v_cvt_pk_bf16_f32 v12, v0, v2
	v_mul_f32_e32 v0, v8, v3
	v_mul_f32_e32 v0, v0, v4
	v_mul_f32_e32 v2, v9, v6
	v_mul_f32_e32 v2, v2, v5
	v_cvt_pk_bf16_f32 v13, v0, v2
	v_add_u32_e32 v0, 0xb0, v140
	v_mad_i64_i32 v[2:3], s[14:15], v0, s91, v[138:139]
	v_permlane16_swap_b32_e32 v43, v45
	v_permlane16_swap_b32_e32 v26, v28
	v_permlane16_swap_b32_e32 v27, v29
	v_permlane16_swap_b32_e32 v10, v12
	v_permlane16_swap_b32_e32 v11, v13
	s_mov_b64 s[14:15], s[8:9]
	s_mov_b32 s2, s6
	s_mov_b32 s12, s4
	global_store_dwordx4 v[114:115], v[122:125], off
	global_store_dwordx4 v[98:99], v[106:109], off
	global_store_dwordx4 v[82:83], v[90:93], off
	global_store_dwordx4 v[50:51], v[58:61], off
	global_store_dwordx4 v[34:35], v[42:45], off
	global_store_dwordx4 v[18:19], v[26:29], off
	global_store_dwordx4 v[2:3], v[10:13], off
	s_cbranch_scc0 .LBB0_30
	s_waitcnt vmcnt(0)
	s_movk_i32 s2, 0x100
	v_cmp_gt_u32_e32 vcc, s2, v142
	s_and_saveexec_b64 s[4:5], vcc
	s_cbranch_execz .LBB0_37
	s_barrier

; #define LDA(dst, b, h) _Pragma("unroll") for (int m = 0; m < 4; ++m) _Pragma("unroll") for (int k = 0; k < 2; ++k) \
;     dst[m][k] = *reinterpret_cast<const bf16x8*>((char*)SA(b, h) + lds_byte(wr * 64 + m * 16 + fr, k * 32 + fq * 8))
; #define LDB(dst, b, h) _Pragma("unroll") for (int n = 0; n < 2; ++n) _Pragma("unroll") for (int k = 0; k < 2; ++k) \
;     dst[n][k] = *reinterpret_cast<const bf16x8*>((char*)SB(b, h) + lds_byte(wc * 32 + n * 16 + fr, k * 32 + fq * 8))
; #define WAIT_L(n) asm volatile("s_waitcnt lgkmcnt(" #n ")" ::: "memory")
; #define BAR __builtin_amdgcn_s_barrier()
; #define SCHED __builtin_amdgcn_sched_barrier(0)
; template <int MODE>
; __device__ __forceinline__ void gemm_phase(int s, char* lds, const int wave) {
;     ...
;         LDB(B0, 0, 0); SCHED; LDA(At, 0, 0); STAGE(SA(1, 1), Acur, HALF, t + 1);
;         WAIT_L(8); BAR; WAIT_L(0); MMA(0, 0, At, B0); BAR; SCHED;
;         LDB(B1, 0, 1); STAGE(SB(0, 0), B2, 0, k2);
;         BAR; WAIT_L(0); MMA(0, 1, At, B1); BAR;
;         LDA(At, 0, 1); STAGE(SA(0, 0), A2, 0, k2);
;         BAR; WAIT_L(0); MMA(1, 0, At, B0); BAR; SCHED;
.LBB0_70:
	ds_read_b128 v[142:145], v169
	ds_read_b128 v[146:149], v169 offset:1024
	ds_read_b128 v[150:153], v169 offset:2048
	ds_read_b128 v[178:181], v169 offset:3072
	s_add_i32 s9, s9, 2
	s_cmp_gt_u32 s9, 13
	s_cselect_b64 s[40:41], -1, 0
	s_and_b64 vcc, s[40:41], exec
	s_cselect_b32 s44, s15, s55
	s_cselect_b32 s45, s14, s54
	v_add_u32_e32 v0, 0xc000, v157
	ds_read_b128 v[182:185], v170
	ds_read_b128 v[198:201], v170 offset:1024
	ds_read_b128 v[202:205], v171
	ds_read_b128 v[206:209], v171 offset:1024
	ds_read_b128 v[210:213], v172
	ds_read_b128 v[214:217], v172 offset:1024
	ds_read_b128 v[218:221], v173
	ds_read_b128 v[222:225], v173 offset:1024
	v_readfirstlane_b32 s30, v0
	v_add_u32_e32 v0, 0xe000, v157
	s_mov_b32 m0, s30
	v_readfirstlane_b32 s30, v0
	global_load_lds_dwordx4 v[132:133], off
	s_mov_b32 m0, s30
	s_nop 0
	global_load_lds_dwordx4 v[130:131], off
	s_waitcnt lgkmcnt(8)
	s_barrier
	s_waitcnt lgkmcnt(0)
	s_waitcnt lgkmcnt(0)
	v_mfma_f32_16x16x32_bf16 v[126:129], v[142:145], v[182:185], v[126:129]
	v_mfma_f32_16x16x32_bf16 v[122:125], v[150:153], v[182:185], v[122:125]
	v_mfma_f32_16x16x32_bf16 v[110:113], v[142:145], v[202:205], v[110:113]
	v_mfma_f32_16x16x32_bf16 v[106:109], v[150:153], v[202:205], v[106:109]
	v_mfma_f32_16x16x32_bf16 v[94:97], v[142:145], v[210:213], v[94:97]
	v_mfma_f32_16x16x32_bf16 v[90:93], v[150:153], v[210:213], v[90:93]
	v_mfma_f32_16x16x32_bf16 v[78:81], v[142:145], v[218:221], v[78:81]
	v_mfma_f32_16x16x32_bf16 v[74:77], v[150:153], v[218:221], v[74:77]
	v_mfma_f32_16x16x32_bf16 v[126:129], v[146:149], v[198:201], v[126:129]
	v_mfma_f32_16x16x32_bf16 v[122:125], v[178:181], v[198:201], v[122:125]
	v_mfma_f32_16x16x32_bf16 v[110:113], v[146:149], v[206:209], v[110:113]
	v_mfma_f32_16x16x32_bf16 v[106:109], v[178:181], v[206:209], v[106:109]
	v_mfma_f32_16x16x32_bf16 v[94:97], v[146:149], v[214:217], v[94:97]
	v_mfma_f32_16x16x32_bf16 v[90:93], v[178:181], v[214:217], v[90:93]
	v_mfma_f32_16x16x32_bf16 v[78:81], v[146:149], v[222:225], v[78:81]
	v_mfma_f32_16x16x32_bf16 v[74:77], v[178:181], v[222:225], v[74:77]
	s_barrier
	s_cselect_b32 s30, 0, s11
	s_cselect_b32 s46, s53, s57
	s_cselect_b32 s47, s52, s56
	s_lshl_b64 s[40:41], s[30:31], 1
	s_add_u32 s42, s47, s40
	s_addc_u32 s43, s46, s41
	v_readfirstlane_b32 s59, v155
	v_lshl_add_u64 v[242:243], s[42:43], 0, v[134:135]
	s_mov_b32 m0, s59
	v_lshl_add_u64 v[244:245], s[42:43], 0, v[136:137]
	v_readfirstlane_b32 s42, v156
	ds_read_b128 v[226:229], v174
	ds_read_b128 v[230:233], v174 offset:1024
	ds_read_b128 v[234:237], v174 offset:2048
	ds_read_b128 v[238:241], v174 offset:3072
	global_load_lds_dwordx4 v[242:243], off
	s_mov_b32 m0, s42
	s_nop 0
	global_load_lds_dwordx4 v[244:245], off
	s_barrier
	s_waitcnt lgkmcnt(0)
	s_waitcnt lgkmcnt(0)
	v_mfma_f32_16x16x32_bf16 v[118:121], v[226:229], v[182:185], v[118:121]
	v_mfma_f32_16x16x32_bf16 v[114:117], v[234:237], v[182:185], v[114:117]
	v_mfma_f32_16x16x32_bf16 v[102:105], v[226:229], v[202:205], v[102:105]
	v_mfma_f32_16x16x32_bf16 v[98:101], v[234:237], v[202:205], v[98:101]
	v_mfma_f32_16x16x32_bf16 v[86:89], v[226:229], v[210:213], v[86:89]
	v_mfma_f32_16x16x32_bf16 v[82:85], v[234:237], v[210:213], v[82:85]
	v_mfma_f32_16x16x32_bf16 v[70:73], v[226:229], v[218:221], v[70:73]
	v_mfma_f32_16x16x32_bf16 v[66:69], v[234:237], v[218:221], v[66:69]
	v_mfma_f32_16x16x32_bf16 v[118:121], v[230:233], v[198:201], v[118:121]
	v_mfma_f32_16x16x32_bf16 v[114:117], v[238:241], v[198:201], v[114:117]
	v_mfma_f32_16x16x32_bf16 v[102:105], v[230:233], v[206:209], v[102:105]
	v_mfma_f32_16x16x32_bf16 v[98:101], v[238:241], v[206:209], v[98:101]
	v_mfma_f32_16x16x32_bf16 v[86:89], v[230:233], v[214:217], v[86:89]
	v_mfma_f32_16x16x32_bf16 v[82:85], v[238:241], v[214:217], v[82:85]
	v_mfma_f32_16x16x32_bf16 v[70:73], v[230:233], v[222:225], v[70:73]
	v_mfma_f32_16x16x32_bf16 v[66:69], v[238:241], v[222:225], v[66:69]
	s_add_u32 s42, s45, s40
	s_addc_u32 s43, s44, s41
	v_readfirstlane_b32 s44, v157
	v_lshl_add_u64 v[246:247], s[42:43], 0, v[134:135]
	s_mov_b32 m0, s44
	v_readfirstlane_b32 s44, v158
	s_barrier
	ds_read_b128 v[182:185], v170 offset:16384
	ds_read_b128 v[198:201], v170 offset:17408
	ds_read_b128 v[202:205], v171 offset:16384
	ds_read_b128 v[206:209], v171 offset:17408
	ds_read_b128 v[210:213], v172 offset:16384
	ds_read_b128 v[214:217], v172 offset:17408
	ds_read_b128 v[218:221], v173 offset:16384
	ds_read_b128 v[222:225], v173 offset:17408
	global_load_lds_dwordx4 v[246:247], off
	v_lshl_add_u64 v[248:249], s[42:43], 0, v[136:137]
	s_mov_b32 m0, s44
	s_nop 0
	global_load_lds_dwordx4 v[248:249], off
	s_barrier
	s_waitcnt lgkmcnt(0)
	s_waitcnt lgkmcnt(0)
	v_mfma_f32_16x16x32_bf16 v[62:65], v[142:145], v[182:185], v[62:65]
	v_mfma_f32_16x16x32_bf16 v[58:61], v[150:153], v[182:185], v[58:61]
	v_mfma_f32_16x16x32_bf16 v[46:49], v[142:145], v[202:205], v[46:49]
	v_mfma_f32_16x16x32_bf16 v[42:45], v[150:153], v[202:205], v[42:45]
	v_mfma_f32_16x16x32_bf16 v[30:33], v[142:145], v[210:213], v[30:33]
	v_mfma_f32_16x16x32_bf16 v[26:29], v[150:153], v[210:213], v[26:29]
	v_mfma_f32_16x16x32_bf16 v[14:17], v[142:145], v[218:221], v[14:17]
	v_mfma_f32_16x16x32_bf16 v[10:13], v[150:153], v[218:221], v[10:13]
	v_mfma_f32_16x16x32_bf16 v[62:65], v[146:149], v[198:201], v[62:65]
	v_mfma_f32_16x16x32_bf16 v[58:61], v[178:181], v[198:201], v[58:61]
	v_mfma_f32_16x16x32_bf16 v[46:49], v[146:149], v[206:209], v[46:49]
	v_mfma_f32_16x16x32_bf16 v[42:45], v[178:181], v[206:209], v[42:45]
	v_mfma_f32_16x16x32_bf16 v[30:33], v[146:149], v[214:217], v[30:33]
	v_mfma_f32_16x16x32_bf16 v[26:29], v[178:181], v[214:217], v[26:29]
	v_mfma_f32_16x16x32_bf16 v[14:17], v[146:149], v[222:225], v[14:17]
	v_mfma_f32_16x16x32_bf16 v[10:13], v[178:181], v[222:225], v[10:13]
	s_barrier
; #define LDA(dst, b, h) _Pragma("unroll") for (int m = 0; m < 4; ++m) _Pragma("unroll") for (int k = 0; k < 2; ++k) \
;     dst[m][k] = *reinterpret_cast<const bf16x8*>((char*)SA(b, h) + lds_byte(wr * 64 + m * 16 + fr, k * 32 + fq * 8))
; #define LDB(dst, b, h) _Pragma("unroll") for (int n = 0; n < 2; ++n) _Pragma("unroll") for (int k = 0; k < 2; ++k) \
;     dst[n][k] = *reinterpret_cast<const bf16x8*>((char*)SB(b, h) + lds_byte(wc * 32 + n * 16 + fr, k * 32 + fq * 8))
; #define WAIT_V(n) asm volatile("s_waitcnt vmcnt(" #n ")" ::: "memory")
; #define WAIT_L(n) asm volatile("s_waitcnt lgkmcnt(" #n ")" ::: "memory")
; #define BAR __builtin_amdgcn_s_barrier()
; #define SCHED __builtin_amdgcn_sched_barrier(0)
; template <int MODE>
; __device__ __forceinline__ void gemm_phase(int s, char* lds, const int wave) {
;     ...
;         STAGE(SB(0, 1), B2, HALF, k2);
;         WAIT_V(6); BAR; MMA(1, 1, At, B1); BAR;
;         LDB(B0, 1, 0); SCHED; LDA(At, 1, 0); STAGE(SA(0, 1), A2, HALF, k2);
;         WAIT_L(8); BAR; WAIT_L(0); MMA(0, 0, At, B0); BAR; SCHED;
;         LDB(B1, 1, 1); STAGE(SB(1, 0), B2, 0, k2 + 1);
;         BAR; WAIT_L(0); MMA(0, 1, At, B1); BAR;
	s_add_u32 s60, s47, 0x40000
	s_addc_u32 s61, s46, 0
	s_add_u32 s40, s60, s40
	s_addc_u32 s41, s61, s41
	v_readfirstlane_b32 s44, v159
	v_lshl_add_u64 v[142:143], s[40:41], 0, v[134:135]
	s_mov_b32 m0, s44
	s_nop 0
	global_load_lds_dwordx4 v[142:143], off
	v_lshl_add_u64 v[142:143], s[40:41], 0, v[136:137]
	v_readfirstlane_b32 s40, v160
	s_mov_b32 m0, s40
	s_nop 0
	global_load_lds_dwordx4 v[142:143], off
	s_waitcnt vmcnt(6)
	s_barrier
	v_mfma_f32_16x16x32_bf16 v[54:57], v[226:229], v[182:185], v[54:57]
	v_mfma_f32_16x16x32_bf16 v[50:53], v[234:237], v[182:185], v[50:53]
	v_mfma_f32_16x16x32_bf16 v[38:41], v[226:229], v[202:205], v[38:41]
	v_mfma_f32_16x16x32_bf16 v[34:37], v[234:237], v[202:205], v[34:37]
	v_mfma_f32_16x16x32_bf16 v[22:25], v[226:229], v[210:213], v[22:25]
	v_mfma_f32_16x16x32_bf16 v[18:21], v[234:237], v[210:213], v[18:21]
	v_mfma_f32_16x16x32_bf16 v[6:9], v[226:229], v[218:221], v[6:9]
	v_mfma_f32_16x16x32_bf16 v[2:5], v[234:237], v[218:221], v[2:5]
	v_mfma_f32_16x16x32_bf16 v[54:57], v[230:233], v[198:201], v[54:57]
	v_mfma_f32_16x16x32_bf16 v[50:53], v[238:241], v[198:201], v[50:53]
	v_mfma_f32_16x16x32_bf16 v[38:41], v[230:233], v[206:209], v[38:41]
	v_mfma_f32_16x16x32_bf16 v[34:37], v[238:241], v[206:209], v[34:37]
	v_mfma_f32_16x16x32_bf16 v[22:25], v[230:233], v[214:217], v[22:25]
	v_mfma_f32_16x16x32_bf16 v[18:21], v[238:241], v[214:217], v[18:21]
	v_mfma_f32_16x16x32_bf16 v[6:9], v[230:233], v[222:225], v[6:9]
	v_mfma_f32_16x16x32_bf16 v[2:5], v[238:241], v[222:225], v[2:5]
	s_barrier
	ds_read_b128 v[142:145], v175
	ds_read_b128 v[146:149], v175 offset:1024
	ds_read_b128 v[150:153], v175 offset:2048
	ds_read_b128 v[178:181], v175 offset:3072
	s_add_u32 s40, s42, 0x40000
	s_addc_u32 s41, s43, 0
	v_readfirstlane_b32 s42, v161
	v_lshl_add_u64 v[226:227], s[40:41], 0, v[134:135]
	s_mov_b32 m0, s42
	ds_read_b128 v[182:185], v170 offset:32768
	ds_read_b128 v[198:201], v170 offset:33792
	ds_read_b128 v[202:205], v171 offset:32768
	ds_read_b128 v[206:209], v171 offset:33792
	ds_read_b128 v[210:213], v172 offset:32768
	ds_read_b128 v[214:217], v172 offset:33792
	ds_read_b128 v[218:221], v173 offset:32768
	ds_read_b128 v[222:225], v173 offset:33792
	global_load_lds_dwordx4 v[226:227], off
	v_lshl_add_u64 v[226:227], s[40:41], 0, v[136:137]
	v_readfirstlane_b32 s40, v162
	s_mov_b32 m0, s40
	s_nop 0
	global_load_lds_dwordx4 v[226:227], off
	s_waitcnt lgkmcnt(8)
	s_barrier
	s_waitcnt lgkmcnt(0)
	s_waitcnt lgkmcnt(0)
	v_mfma_f32_16x16x32_bf16 v[126:129], v[142:145], v[182:185], v[126:129]
	v_mfma_f32_16x16x32_bf16 v[122:125], v[150:153], v[182:185], v[122:125]
	v_mfma_f32_16x16x32_bf16 v[110:113], v[142:145], v[202:205], v[110:113]
	v_mfma_f32_16x16x32_bf16 v[106:109], v[150:153], v[202:205], v[106:109]
	v_mfma_f32_16x16x32_bf16 v[94:97], v[142:145], v[210:213], v[94:97]
	v_mfma_f32_16x16x32_bf16 v[90:93], v[150:153], v[210:213], v[90:93]
	v_mfma_f32_16x16x32_bf16 v[78:81], v[142:145], v[218:221], v[78:81]
	v_mfma_f32_16x16x32_bf16 v[74:77], v[150:153], v[218:221], v[74:77]
	v_mfma_f32_16x16x32_bf16 v[126:129], v[146:149], v[198:201], v[126:129]
	v_mfma_f32_16x16x32_bf16 v[122:125], v[178:181], v[198:201], v[122:125]
	v_mfma_f32_16x16x32_bf16 v[110:113], v[146:149], v[206:209], v[110:113]
	v_mfma_f32_16x16x32_bf16 v[106:109], v[178:181], v[206:209], v[106:109]
	v_mfma_f32_16x16x32_bf16 v[94:97], v[146:149], v[214:217], v[94:97]
	v_mfma_f32_16x16x32_bf16 v[90:93], v[178:181], v[214:217], v[90:93]
	v_mfma_f32_16x16x32_bf16 v[78:81], v[146:149], v[222:225], v[78:81]
	v_mfma_f32_16x16x32_bf16 v[74:77], v[178:181], v[222:225], v[74:77]
	s_barrier
	v_readfirstlane_b32 s40, v163
	v_lshl_add_u64 v[242:243], v[242:243], 0, s[18:19]
	s_mov_b32 m0, s40
	v_readfirstlane_b32 s40, v164
	ds_read_b128 v[226:229], v176
	ds_read_b128 v[230:233], v176 offset:1024
	ds_read_b128 v[234:237], v176 offset:2048
	ds_read_b128 v[238:241], v176 offset:3072
	global_load_lds_dwordx4 v[242:243], off
	v_lshl_add_u64 v[242:243], v[244:245], 0, s[18:19]
	s_mov_b32 m0, s40
	s_or_b32 s30, s30, 64
	global_load_lds_dwordx4 v[242:243], off
	s_barrier
	s_waitcnt lgkmcnt(0)
	s_waitcnt lgkmcnt(0)
	v_mfma_f32_16x16x32_bf16 v[118:121], v[226:229], v[182:185], v[118:121]
	v_mfma_f32_16x16x32_bf16 v[114:117], v[234:237], v[182:185], v[114:117]
	v_mfma_f32_16x16x32_bf16 v[102:105], v[226:229], v[202:205], v[102:105]
	v_mfma_f32_16x16x32_bf16 v[98:101], v[234:237], v[202:205], v[98:101]
	v_mfma_f32_16x16x32_bf16 v[86:89], v[226:229], v[210:213], v[86:89]
	v_mfma_f32_16x16x32_bf16 v[82:85], v[234:237], v[210:213], v[82:85]
	v_mfma_f32_16x16x32_bf16 v[70:73], v[226:229], v[218:221], v[70:73]
	v_mfma_f32_16x16x32_bf16 v[66:69], v[234:237], v[218:221], v[66:69]
	v_mfma_f32_16x16x32_bf16 v[118:121], v[230:233], v[198:201], v[118:121]
	v_mfma_f32_16x16x32_bf16 v[114:117], v[238:241], v[198:201], v[114:117]
	v_mfma_f32_16x16x32_bf16 v[102:105], v[230:233], v[206:209], v[102:105]
	v_mfma_f32_16x16x32_bf16 v[98:101], v[238:241], v[206:209], v[98:101]
	v_mfma_f32_16x16x32_bf16 v[86:89], v[230:233], v[214:217], v[86:89]
	v_mfma_f32_16x16x32_bf16 v[82:85], v[238:241], v[214:217], v[82:85]
	v_mfma_f32_16x16x32_bf16 v[70:73], v[230:233], v[222:225], v[70:73]
	v_mfma_f32_16x16x32_bf16 v[66:69], v[238:241], v[222:225], v[66:69]
	v_readfirstlane_b32 s40, v165
	v_lshl_add_u64 v[242:243], v[246:247], 0, s[18:19]
	s_mov_b32 m0, s40
	v_readfirstlane_b32 s40, v166
	s_barrier
; #define LDA(dst, b, h) _Pragma("unroll") for (int m = 0; m < 4; ++m) _Pragma("unroll") for (int k = 0; k < 2; ++k) \
;     dst[m][k] = *reinterpret_cast<const bf16x8*>((char*)SA(b, h) + lds_byte(wr * 64 + m * 16 + fr, k * 32 + fq * 8))
; #define WAIT_V(n) asm volatile("s_waitcnt vmcnt(" #n ")" ::: "memory")
; #define BAR __builtin_amdgcn_s_barrier()
; template <int MODE>
; __device__ __forceinline__ void gemm_epilogue(char* ws, const float* __restrict__ xseq, float* __restrict__ oseq, const int pm, const int pn,
;                                               f32x4 (&acc)[2][2][4][2], const int wave) {
;     ...
;     } else if (MODE == G_PROJ || MODE == G_MERGE1 || MODE == G_MERGE2) {
; #pragma unroll
;       for (int bj = 0; bj < 2; ++bj) {
;         const int cb = bcol + bj * HALF + wc * 32;
;         u32x2 w[2], gg[2], tt[2];
;         if (MODE == G_MERGE1) load_pair16(gates + (long)row * GWID + cb, fq, gg[0], gg[1]);
;         if (MODE == G_MERGE2) { load_pair16(gates + (long)row * GWID + 2048 + cb, fq, gg[0], gg[1]);
;                                 load_pair16((const bf16*)(ws + OFF_TMP) + (long)row * DM + cb, fq, tt[0], tt[1]); }
; template <int MODE>
; __device__ __forceinline__ void gemm_phase(int s, char* lds, const int wave) {
;     ...
;       for (int t = 0; t < nt; t += 2) {
;         const bool lastit = t + 2 >= nt;
;         const bf16* A2 = lastit ? Anext : Acur; const bf16* B2 = lastit ? Bnext : Bcur; const int k2 = lastit ? 0 : t + 2;
;         LDB(B0, 0, 0); SCHED; LDA(At, 0, 0); STAGE(SA(1, 1), Acur, HALF, t + 1);
;         WAIT_L(8); BAR; WAIT_L(0); MMA(0, 0, At, B0); BAR; SCHED;
;         LDB(B1, 0, 1); STAGE(SB(0, 0), B2, 0, k2);
;         BAR; WAIT_L(0); MMA(0, 1, At, B1); BAR;
;         LDA(At, 0, 1); STAGE(SA(0, 0), A2, 0, k2);
;         BAR; WAIT_L(0); MMA(1, 0, At, B0); BAR; SCHED;
;         STAGE(SB(0, 1), B2, HALF, k2);
;         WAIT_V(6); BAR; MMA(1, 1, At, B1); BAR;
;         LDB(B0, 1, 0); SCHED; LDA(At, 1, 0); STAGE(SA(0, 1), A2, HALF, k2);
;         WAIT_L(8); BAR; WAIT_L(0); MMA(0, 0, At, B0); BAR; SCHED;
;         LDB(B1, 1, 1); STAGE(SB(1, 0), B2, 0, k2 + 1);
;         BAR; WAIT_L(0); MMA(0, 1, At, B1); BAR;
;         LDA(At, 1, 1); STAGE(SA(1, 0), A2, 0, k2 + 1);
;         BAR; WAIT_L(0); MMA(1, 0, At, B0); BAR; SCHED;
;         STAGE(SB(1, 1), B2, HALF, k2 + 1);
;         WAIT_V(6); BAR; MMA(1, 1, At, B1); BAR;
;       }
	ds_read_b128 v[182:185], v170 offset:49152
	ds_read_b128 v[198:201], v170 offset:50176
	ds_read_b128 v[202:205], v171 offset:49152
	ds_read_b128 v[206:209], v171 offset:50176
	ds_read_b128 v[210:213], v172 offset:49152
	ds_read_b128 v[214:217], v172 offset:50176
	ds_read_b128 v[218:221], v173 offset:49152
	ds_read_b128 v[222:225], v173 offset:50176
	global_load_lds_dwordx4 v[242:243], off
	v_lshl_add_u64 v[242:243], v[248:249], 0, s[18:19]
	s_mov_b32 m0, s40
	s_nop 0
	global_load_lds_dwordx4 v[242:243], off
	s_barrier
	s_waitcnt lgkmcnt(0)
	s_waitcnt lgkmcnt(0)
	v_mfma_f32_16x16x32_bf16 v[62:65], v[142:145], v[182:185], v[62:65]
	v_mfma_f32_16x16x32_bf16 v[58:61], v[150:153], v[182:185], v[58:61]
	v_mfma_f32_16x16x32_bf16 v[46:49], v[142:145], v[202:205], v[46:49]
	v_mfma_f32_16x16x32_bf16 v[42:45], v[150:153], v[202:205], v[42:45]
	v_mfma_f32_16x16x32_bf16 v[30:33], v[142:145], v[210:213], v[30:33]
	v_mfma_f32_16x16x32_bf16 v[26:29], v[150:153], v[210:213], v[26:29]
	v_mfma_f32_16x16x32_bf16 v[14:17], v[142:145], v[218:221], v[14:17]
	v_mfma_f32_16x16x32_bf16 v[10:13], v[150:153], v[218:221], v[10:13]
	v_mfma_f32_16x16x32_bf16 v[62:65], v[146:149], v[198:201], v[62:65]
	v_mfma_f32_16x16x32_bf16 v[58:61], v[178:181], v[198:201], v[58:61]
	v_mfma_f32_16x16x32_bf16 v[46:49], v[146:149], v[206:209], v[46:49]
	v_mfma_f32_16x16x32_bf16 v[42:45], v[178:181], v[206:209], v[42:45]
	v_mfma_f32_16x16x32_bf16 v[30:33], v[146:149], v[214:217], v[30:33]
	v_mfma_f32_16x16x32_bf16 v[26:29], v[178:181], v[214:217], v[26:29]
	v_mfma_f32_16x16x32_bf16 v[14:17], v[146:149], v[222:225], v[14:17]
	v_mfma_f32_16x16x32_bf16 v[10:13], v[178:181], v[222:225], v[10:13]
	s_barrier
	v_lshl_add_u64 v[142:143], s[60:61], 0, v[134:135]
	s_lshl_b64 s[40:41], s[30:31], 1
	v_readfirstlane_b32 s30, v167
	v_lshl_add_u64 v[142:143], v[142:143], 0, s[40:41]
	s_mov_b32 m0, s30
	v_readfirstlane_b32 s30, v168
	global_load_lds_dwordx4 v[142:143], off
	v_lshl_add_u64 v[142:143], s[60:61], 0, v[136:137]
	v_lshl_add_u64 v[142:143], v[142:143], 0, s[40:41]
	s_mov_b32 m0, s30
	s_nop 0
	global_load_lds_dwordx4 v[142:143], off
	s_waitcnt vmcnt(6)
	s_barrier
	v_mfma_f32_16x16x32_bf16 v[54:57], v[226:229], v[182:185], v[54:57]
	v_mfma_f32_16x16x32_bf16 v[50:53], v[234:237], v[182:185], v[50:53]
	v_mfma_f32_16x16x32_bf16 v[38:41], v[226:229], v[202:205], v[38:41]
	v_mfma_f32_16x16x32_bf16 v[34:37], v[234:237], v[202:205], v[34:37]
	v_mfma_f32_16x16x32_bf16 v[22:25], v[226:229], v[210:213], v[22:25]
	v_mfma_f32_16x16x32_bf16 v[18:21], v[234:237], v[210:213], v[18:21]
	v_mfma_f32_16x16x32_bf16 v[6:9], v[226:229], v[218:221], v[6:9]
	v_mfma_f32_16x16x32_bf16 v[2:5], v[234:237], v[218:221], v[2:5]
	v_mfma_f32_16x16x32_bf16 v[54:57], v[230:233], v[198:201], v[54:57]
	v_mfma_f32_16x16x32_bf16 v[50:53], v[238:241], v[198:201], v[50:53]
	v_mfma_f32_16x16x32_bf16 v[38:41], v[230:233], v[206:209], v[38:41]
	v_mfma_f32_16x16x32_bf16 v[34:37], v[238:241], v[206:209], v[34:37]
	v_mfma_f32_16x16x32_bf16 v[22:25], v[230:233], v[214:217], v[22:25]
	v_mfma_f32_16x16x32_bf16 v[18:21], v[238:241], v[214:217], v[18:21]
	v_mfma_f32_16x16x32_bf16 v[6:9], v[230:233], v[222:225], v[6:9]
	v_mfma_f32_16x16x32_bf16 v[2:5], v[238:241], v[222:225], v[2:5]
	v_lshl_add_u64 v[130:131], v[130:131], 0, s[38:39]
	v_lshl_add_u64 v[132:133], v[132:133], 0, s[38:39]
	s_addk_i32 s11, 0x80
	s_barrier
	s_cbranch_vccz .LBB0_70
	v_mov_b32_e32 v0, v187
	s_lshl_b32 s9, s58, 8
	v_ashrrev_i32_e32 v130, 2, v0
	v_and_b32_e32 v130, 0xffffffc0, v130
	v_and_or_b32 v131, v0, 15, s9
	v_add_u32_e32 v146, v131, v130
	v_lshrrev_b32_e32 v130, 1, v0
	v_and_b32_e32 v131, 16, v0
	v_lshrrev_b32_e32 v0, 2, v0
	v_and_b32_e32 v0, 12, v0
	v_add_u32_e32 v132, 12, v0
	v_cmp_eq_u32_e32 vcc, 0, v131
	v_and_b32_e32 v130, 0x60, v130
	v_lshl_or_b32 v130, s2, 8, v130
	v_cndmask_b32_e32 v0, v132, v0, vcc
	v_lshlrev_b32_e32 v0, 1, v0
	v_ashrrev_i32_e32 v147, 31, v146
	v_lshl_add_u64 v[148:149], s[4:5], 0, v[0:1]
	v_lshlrev_b64 v[132:133], 13, v[146:147]
	v_ashrrev_i32_e32 v131, 31, v130
	v_lshl_add_u64 v[132:133], v[148:149], 0, v[132:133]
	v_lshlrev_b64 v[142:143], 1, v[130:131]
	v_lshl_add_u64 v[144:145], v[132:133], 0, v[142:143]
	global_load_dwordx4 v[130:133], v[144:145], off
	global_load_dwordx4 v[178:181], v[144:145], off offset:256
	v_or_b32_e32 v150, 16, v146
	v_ashrrev_i32_e32 v151, 31, v150
	v_lshlrev_b64 v[152:153], 12, v[146:147]
	v_lshl_add_u64 v[144:145], s[6:7], 0, v[0:1]
	v_lshlrev_b64 v[182:183], 13, v[150:151]
	v_lshl_add_u64 v[152:153], v[144:145], 0, v[152:153]
	v_lshl_add_u64 v[182:183], v[148:149], 0, v[182:183]
	v_lshl_add_u64 v[184:185], v[152:153], 0, v[142:143]
	v_lshl_add_u64 v[152:153], v[182:183], 0, v[142:143]
	s_mov_b64 s[56:57], s[52:53]
	s_mov_b64 s[54:55], s[14:15]
	s_cmpk_gt_i32 s62, 0x1ff
	s_mov_b32 s2, s10
	s_mov_b32 s58, s8
	s_waitcnt vmcnt(0)
; __device__ __forceinline__ float bflo(unsigned u) { return __uint_as_float(u << 16); }
; __device__ __forceinline__ float bfhi(unsigned u) { return __uint_as_float(u & 0xffff0000u); }
; template <int MODE>
; __device__ __forceinline__ void gemm_epilogue(char* ws, const float* __restrict__ xseq, float* __restrict__ oseq, const int pm, const int pn,
;                                               f32x4 (&acc)[2][2][4][2], const int wave) {
;     ...
;     } else if (MODE == G_PROJ || MODE == G_MERGE1 || MODE == G_MERGE2) {
; #pragma unroll
;       for (int bj = 0; bj < 2; ++bj) {
;         const int cb = bcol + bj * HALF + wc * 32;
;         u32x2 w[2], gg[2], tt[2];
;         if (MODE == G_MERGE1) load_pair16(gates + (long)row * GWID + cb, fq, gg[0], gg[1]);
;         if (MODE == G_MERGE2) { load_pair16(gates + (long)row * GWID + 2048 + cb, fq, gg[0], gg[1]);
;                                 load_pair16((const bf16*)(ws + OFF_TMP) + (long)row * DM + cb, fq, tt[0], tt[1]); }
; #pragma unroll
;         for (int n = 0; n < 2; ++n) {
;           f32x4 v = acc[ai][bj][m][n];
;           if (MODE == G_PROJ) {
;             if (bcol >= AQKV + BQKV) { v[0] = sigmoidf_(v[0]); v[1] = sigmoidf_(v[1]); v[2] = sigmoidf_(v[2]); v[3] = sigmoidf_(v[3]); }
;             w[n] = u32x2{cvtpk(v[0], v[1]), cvtpk(v[2], v[3])};
;           } else if (MODE == G_MERGE1) {
;             const u32x2 ga = gg[n];
;             w[n] = u32x2{cvtpk(v[0] * bflo(ga[0]), v[1] * bfhi(ga[0])), cvtpk(v[2] * bflo(ga[1]), v[3] * bfhi(ga[1]))};
;           } else {
;             const u32x2 gb = gg[n], tv = tt[n];
;             w[n] = u32x2{cvtpk(bflo(tv[0]) + v[0] * bflo(gb[0]), bfhi(tv[0]) + v[1] * bfhi(gb[0])), cvtpk(bflo(tv[1]) + v[2] * bflo(gb[1]), bfhi(tv[1]) + v[3] * bfhi(gb[1]))};
;           }
;         }
;         bf16* dst;
;         if (MODE == G_PROJ) {
;           if (bcol < AQKV) dst = (bf16*)(ws + OFF_QKVA) + (long)row * AQKV + cb;
;           else if (bcol < AQKV + BQKV) dst = (bf16*)(ws + OFF_QKVB) + (long)row * BQKV + (cb - AQKV);
;           else dst = gates + (long)row * GWID + (cb - AQKV - BQKV);
;         } else if (MODE == G_MERGE1) dst = (bf16*)(ws + OFF_TMP) + (long)row * DM + cb;
;         else dst = (bf16*)(ws + OFF_H) + (long)row * DM + cb;
;         store_pair16(dst, w[0], w[1], fq);
	v_mov_b32_e32 v0, v132
	v_mov_b32_e32 v132, v133
	v_mov_b32_e32 v133, v180
	v_mov_b32_e32 v147, v181
	s_nop 0
	v_permlane16_swap_b32_e32 v178, v133
	v_permlane16_swap_b32_e32 v179, v147
	v_permlane16_swap_b32_e32 v130, v0
	v_permlane16_swap_b32_e32 v131, v132
	v_lshlrev_b32_e32 v183, 16, v178
	v_and_b32_e32 v178, 0xffff0000, v178
	v_lshlrev_b32_e32 v198, 16, v179
	v_and_b32_e32 v179, 0xffff0000, v179
	v_lshlrev_b32_e32 v177, 16, v130
	v_and_b32_e32 v130, 0xffff0000, v130
	v_lshlrev_b32_e32 v180, 16, v131
	v_and_b32_e32 v131, 0xffff0000, v131
	v_lshlrev_b32_e32 v181, 16, v0
	v_and_b32_e32 v0, 0xffff0000, v0
	v_lshlrev_b32_e32 v182, 16, v132
	v_and_b32_e32 v132, 0xffff0000, v132
	v_lshlrev_b32_e32 v199, 16, v133
	v_and_b32_e32 v133, 0xffff0000, v133
	v_lshlrev_b32_e32 v200, 16, v147
	v_and_b32_e32 v147, 0xffff0000, v147
	v_mul_f32_e32 v118, v118, v183
	v_mul_f32_e32 v119, v119, v178
	v_mul_f32_e32 v120, v120, v198
	v_mul_f32_e32 v121, v121, v179
	v_mul_f32_e32 v126, v126, v177
	v_mul_f32_e32 v127, v127, v130
	v_mul_f32_e32 v128, v128, v180
	v_mul_f32_e32 v129, v129, v131
	v_mul_f32_e32 v122, v122, v181
	v_mul_f32_e32 v0, v123, v0
	v_mul_f32_e32 v123, v124, v182
	v_mul_f32_e32 v124, v125, v132
	v_mul_f32_e32 v125, v114, v199
	v_mul_f32_e32 v130, v115, v133
	v_mul_f32_e32 v131, v116, v200
	v_mul_f32_e32 v132, v117, v147
	v_cvt_pk_bf16_f32 v114, v126, v127
	v_cvt_pk_bf16_f32 v115, v128, v129
	v_cvt_pk_bf16_f32 v116, v122, v0
	v_cvt_pk_bf16_f32 v117, v123, v124
	v_cvt_pk_bf16_f32 v118, v118, v119
	v_cvt_pk_bf16_f32 v119, v120, v121
	v_cvt_pk_bf16_f32 v120, v125, v130
	v_cvt_pk_bf16_f32 v121, v131, v132
	s_nop 0
	v_permlane16_swap_b32_e32 v114, v116
	v_permlane16_swap_b32_e32 v115, v117
	v_permlane16_swap_b32_e32 v118, v120
	v_permlane16_swap_b32_e32 v119, v121
	global_store_dwordx4 v[184:185], v[114:117], off
	global_store_dwordx4 v[184:185], v[118:121], off offset:256
	global_load_dwordx4 v[114:117], v[152:153], off
	s_nop 0
	global_load_dwordx4 v[122:125], v[152:153], off offset:256
	v_or_b32_e32 v118, 32, v146
	v_ashrrev_i32_e32 v119, 31, v118
	v_lshlrev_b64 v[120:121], 12, v[150:151]
	v_lshlrev_b64 v[126:127], 13, v[118:119]
	v_lshl_add_u64 v[120:121], v[144:145], 0, v[120:121]
	v_lshl_add_u64 v[126:127], v[148:149], 0, v[126:127]
	v_lshl_add_u64 v[128:129], v[120:121], 0, v[142:143]
	v_lshl_add_u64 v[120:121], v[126:127], 0, v[142:143]
	s_waitcnt vmcnt(0)
	v_mov_b32_e32 v0, v116
	v_mov_b32_e32 v116, v117
	v_mov_b32_e32 v117, v124
	v_mov_b32_e32 v124, v125
	s_nop 0
	v_permlane16_swap_b32_e32 v122, v117
	v_permlane16_swap_b32_e32 v123, v124
	v_permlane16_swap_b32_e32 v114, v0
	v_permlane16_swap_b32_e32 v115, v116
	v_lshlrev_b32_e32 v131, 16, v122
	v_and_b32_e32 v122, 0xffff0000, v122
	v_lshlrev_b32_e32 v132, 16, v123
	v_and_b32_e32 v123, 0xffff0000, v123
	v_lshlrev_b32_e32 v125, 16, v114
	v_and_b32_e32 v114, 0xffff0000, v114
	v_lshlrev_b32_e32 v126, 16, v115
	v_and_b32_e32 v115, 0xffff0000, v115
	v_lshlrev_b32_e32 v127, 16, v0
	v_and_b32_e32 v0, 0xffff0000, v0
	v_lshlrev_b32_e32 v130, 16, v116
	v_and_b32_e32 v116, 0xffff0000, v116
	v_lshlrev_b32_e32 v133, 16, v117
	v_and_b32_e32 v117, 0xffff0000, v117
	v_lshlrev_b32_e32 v147, 16, v124
	v_and_b32_e32 v124, 0xffff0000, v124
	v_mul_f32_e32 v102, v102, v131
	v_mul_f32_e32 v103, v103, v122
	v_mul_f32_e32 v104, v104, v132
	v_mul_f32_e32 v105, v105, v123
	v_mul_f32_e32 v110, v110, v125
	v_mul_f32_e32 v111, v111, v114
	v_mul_f32_e32 v112, v112, v126
	v_mul_f32_e32 v113, v113, v115
	v_mul_f32_e32 v106, v106, v127
	v_mul_f32_e32 v0, v107, v0
	v_mul_f32_e32 v107, v108, v130
	v_mul_f32_e32 v108, v109, v116
	v_mul_f32_e32 v109, v98, v133
	v_mul_f32_e32 v114, v99, v117
	v_mul_f32_e32 v115, v100, v147
	v_mul_f32_e32 v116, v101, v124
	v_cvt_pk_bf16_f32 v98, v110, v111
	v_cvt_pk_bf16_f32 v99, v112, v113
	v_cvt_pk_bf16_f32 v100, v106, v0
	v_cvt_pk_bf16_f32 v101, v107, v108
	v_cvt_pk_bf16_f32 v102, v102, v103
	v_cvt_pk_bf16_f32 v103, v104, v105
	v_cvt_pk_bf16_f32 v104, v109, v114
	v_cvt_pk_bf16_f32 v105, v115, v116
	s_nop 0
	v_permlane16_swap_b32_e32 v98, v100
	v_permlane16_swap_b32_e32 v99, v101
	v_permlane16_swap_b32_e32 v102, v104
	v_permlane16_swap_b32_e32 v103, v105
	global_store_dwordx4 v[128:129], v[98:101], off
	global_store_dwordx4 v[128:129], v[102:105], off offset:256
	global_load_dwordx4 v[98:101], v[120:121], off
	s_nop 0
	global_load_dwordx4 v[106:109], v[120:121], off offset:256
	v_or_b32_e32 v102, 48, v146
	v_ashrrev_i32_e32 v103, 31, v102
	v_lshlrev_b64 v[104:105], 12, v[118:119]
	v_lshlrev_b64 v[110:111], 13, v[102:103]
	v_lshl_add_u64 v[104:105], v[144:145], 0, v[104:105]
	v_lshl_add_u64 v[110:111], v[148:149], 0, v[110:111]
	v_lshl_add_u64 v[112:113], v[104:105], 0, v[142:143]
	v_lshl_add_u64 v[104:105], v[110:111], 0, v[142:143]
	s_waitcnt vmcnt(0)
; __device__ __forceinline__ float bflo(unsigned u) { return __uint_as_float(u << 16); }
; __device__ __forceinline__ float bfhi(unsigned u) { return __uint_as_float(u & 0xffff0000u); }
; template <int MODE>
; __device__ __forceinline__ void gemm_epilogue(char* ws, const float* __restrict__ xseq, float* __restrict__ oseq, const int pm, const int pn,
;                                               f32x4 (&acc)[2][2][4][2], const int wave) {
;     ...
;     } else if (MODE == G_PROJ || MODE == G_MERGE1 || MODE == G_MERGE2) {
; #pragma unroll
;       for (int bj = 0; bj < 2; ++bj) {
;         const int cb = bcol + bj * HALF + wc * 32;
;         u32x2 w[2], gg[2], tt[2];
;         if (MODE == G_MERGE1) load_pair16(gates + (long)row * GWID + cb, fq, gg[0], gg[1]);
;         if (MODE == G_MERGE2) { load_pair16(gates + (long)row * GWID + 2048 + cb, fq, gg[0], gg[1]);
;                                 load_pair16((const bf16*)(ws + OFF_TMP) + (long)row * DM + cb, fq, tt[0], tt[1]); }
; #pragma unroll
;         for (int n = 0; n < 2; ++n) {
;           f32x4 v = acc[ai][bj][m][n];
;           if (MODE == G_PROJ) {
;             if (bcol >= AQKV + BQKV) { v[0] = sigmoidf_(v[0]); v[1] = sigmoidf_(v[1]); v[2] = sigmoidf_(v[2]); v[3] = sigmoidf_(v[3]); }
;             w[n] = u32x2{cvtpk(v[0], v[1]), cvtpk(v[2], v[3])};
;           } else if (MODE == G_MERGE1) {
;             const u32x2 ga = gg[n];
;             w[n] = u32x2{cvtpk(v[0] * bflo(ga[0]), v[1] * bfhi(ga[0])), cvtpk(v[2] * bflo(ga[1]), v[3] * bfhi(ga[1]))};
;           } else {
;             const u32x2 gb = gg[n], tv = tt[n];
;             w[n] = u32x2{cvtpk(bflo(tv[0]) + v[0] * bflo(gb[0]), bfhi(tv[0]) + v[1] * bfhi(gb[0])), cvtpk(bflo(tv[1]) + v[2] * bflo(gb[1]), bfhi(tv[1]) + v[3] * bfhi(gb[1]))};
;           }
;         }
;         bf16* dst;
;         if (MODE == G_PROJ) {
;           if (bcol < AQKV) dst = (bf16*)(ws + OFF_QKVA) + (long)row * AQKV + cb;
;           else if (bcol < AQKV + BQKV) dst = (bf16*)(ws + OFF_QKVB) + (long)row * BQKV + (cb - AQKV);
;           else dst = gates + (long)row * GWID + (cb - AQKV - BQKV);
;         } else if (MODE == G_MERGE1) dst = (bf16*)(ws + OFF_TMP) + (long)row * DM + cb;
;         else dst = (bf16*)(ws + OFF_H) + (long)row * DM + cb;
;         store_pair16(dst, w[0], w[1], fq);
	v_mov_b32_e32 v0, v100
	v_mov_b32_e32 v100, v101
	v_mov_b32_e32 v101, v108
	v_mov_b32_e32 v108, v109
	s_nop 0
	v_permlane16_swap_b32_e32 v106, v101
	v_permlane16_swap_b32_e32 v107, v108
	v_permlane16_swap_b32_e32 v98, v0
	v_permlane16_swap_b32_e32 v99, v100
	v_lshlrev_b32_e32 v115, 16, v106
	v_and_b32_e32 v106, 0xffff0000, v106
	v_lshlrev_b32_e32 v116, 16, v107
	v_and_b32_e32 v107, 0xffff0000, v107
	v_lshlrev_b32_e32 v109, 16, v98
	v_and_b32_e32 v98, 0xffff0000, v98
	v_lshlrev_b32_e32 v110, 16, v99
	v_and_b32_e32 v99, 0xffff0000, v99
	v_lshlrev_b32_e32 v111, 16, v0
	v_and_b32_e32 v0, 0xffff0000, v0
	v_lshlrev_b32_e32 v114, 16, v100
	v_and_b32_e32 v100, 0xffff0000, v100
	v_lshlrev_b32_e32 v117, 16, v101
	v_and_b32_e32 v101, 0xffff0000, v101
	v_lshlrev_b32_e32 v118, 16, v108
	v_and_b32_e32 v108, 0xffff0000, v108
	v_mul_f32_e32 v86, v86, v115
	v_mul_f32_e32 v87, v87, v106
	v_mul_f32_e32 v88, v88, v116
	v_mul_f32_e32 v89, v89, v107
	v_mul_f32_e32 v94, v94, v109
	v_mul_f32_e32 v95, v95, v98
	v_mul_f32_e32 v96, v96, v110
	v_mul_f32_e32 v97, v97, v99
	v_mul_f32_e32 v90, v90, v111
	v_mul_f32_e32 v0, v91, v0
	v_mul_f32_e32 v91, v92, v114
	v_mul_f32_e32 v92, v93, v100
	v_mul_f32_e32 v93, v82, v117
	v_mul_f32_e32 v98, v83, v101
	v_mul_f32_e32 v99, v84, v118
	v_mul_f32_e32 v100, v85, v108
	v_cvt_pk_bf16_f32 v82, v94, v95
	v_cvt_pk_bf16_f32 v83, v96, v97
	v_cvt_pk_bf16_f32 v84, v90, v0
	v_cvt_pk_bf16_f32 v85, v91, v92
	v_cvt_pk_bf16_f32 v86, v86, v87
	v_cvt_pk_bf16_f32 v87, v88, v89
	v_cvt_pk_bf16_f32 v88, v93, v98
	v_cvt_pk_bf16_f32 v89, v99, v100
	s_nop 0
	v_permlane16_swap_b32_e32 v82, v84
	v_permlane16_swap_b32_e32 v83, v85
	v_permlane16_swap_b32_e32 v86, v88
	v_permlane16_swap_b32_e32 v87, v89
	global_store_dwordx4 v[112:113], v[82:85], off
	global_store_dwordx4 v[112:113], v[86:89], off offset:256
	global_load_dwordx4 v[82:85], v[104:105], off
	s_nop 0
	global_load_dwordx4 v[90:93], v[104:105], off offset:256
	v_add_u32_e32 v86, 0x80, v146
	v_ashrrev_i32_e32 v87, 31, v86
	v_lshlrev_b64 v[88:89], 12, v[102:103]
	v_lshlrev_b64 v[94:95], 13, v[86:87]
	v_lshl_add_u64 v[88:89], v[144:145], 0, v[88:89]
	v_lshl_add_u64 v[94:95], v[148:149], 0, v[94:95]
	v_lshl_add_u64 v[96:97], v[88:89], 0, v[142:143]
	v_lshl_add_u64 v[88:89], v[94:95], 0, v[142:143]
	s_waitcnt vmcnt(0)
	v_mov_b32_e32 v0, v84
	v_mov_b32_e32 v84, v85
	v_mov_b32_e32 v85, v92
	v_mov_b32_e32 v92, v93
	s_nop 0
	v_permlane16_swap_b32_e32 v90, v85
	v_permlane16_swap_b32_e32 v91, v92
	v_permlane16_swap_b32_e32 v82, v0
	v_permlane16_swap_b32_e32 v83, v84
	v_lshlrev_b32_e32 v99, 16, v90
	v_and_b32_e32 v90, 0xffff0000, v90
	v_lshlrev_b32_e32 v100, 16, v91
	v_and_b32_e32 v91, 0xffff0000, v91
	v_lshlrev_b32_e32 v93, 16, v82
	v_and_b32_e32 v82, 0xffff0000, v82
	v_lshlrev_b32_e32 v94, 16, v83
	v_and_b32_e32 v83, 0xffff0000, v83
	v_lshlrev_b32_e32 v95, 16, v0
	v_and_b32_e32 v0, 0xffff0000, v0
	v_lshlrev_b32_e32 v98, 16, v84
	v_and_b32_e32 v84, 0xffff0000, v84
	v_lshlrev_b32_e32 v101, 16, v85
	v_and_b32_e32 v85, 0xffff0000, v85
	v_lshlrev_b32_e32 v102, 16, v92
	v_and_b32_e32 v92, 0xffff0000, v92
	v_mul_f32_e32 v70, v70, v99
	v_mul_f32_e32 v71, v71, v90
	v_mul_f32_e32 v72, v72, v100
	v_mul_f32_e32 v73, v73, v91
	v_mul_f32_e32 v78, v78, v93
	v_mul_f32_e32 v79, v79, v82
	v_mul_f32_e32 v80, v80, v94
	v_mul_f32_e32 v81, v81, v83
	v_mul_f32_e32 v74, v74, v95
	v_mul_f32_e32 v0, v75, v0
	v_mul_f32_e32 v75, v76, v98
	v_mul_f32_e32 v76, v77, v84
	v_mul_f32_e32 v77, v66, v101
	v_mul_f32_e32 v82, v67, v85
	v_mul_f32_e32 v83, v68, v102
	v_mul_f32_e32 v84, v69, v92
	v_cvt_pk_bf16_f32 v66, v78, v79
	v_cvt_pk_bf16_f32 v67, v80, v81
	v_cvt_pk_bf16_f32 v68, v74, v0
	v_cvt_pk_bf16_f32 v69, v75, v76
	v_cvt_pk_bf16_f32 v70, v70, v71
	v_cvt_pk_bf16_f32 v71, v72, v73
	v_cvt_pk_bf16_f32 v72, v77, v82
	v_cvt_pk_bf16_f32 v73, v83, v84
	s_nop 0
	v_permlane16_swap_b32_e32 v66, v68
	v_permlane16_swap_b32_e32 v67, v69
	v_permlane16_swap_b32_e32 v70, v72
	v_permlane16_swap_b32_e32 v71, v73
	global_store_dwordx4 v[96:97], v[66:69], off
	global_store_dwordx4 v[96:97], v[70:73], off offset:256
	global_load_dwordx4 v[66:69], v[88:89], off
	s_nop 0
	global_load_dwordx4 v[74:77], v[88:89], off offset:256
	v_add_u32_e32 v70, 0x90, v146
	v_ashrrev_i32_e32 v71, 31, v70
	v_lshlrev_b64 v[72:73], 12, v[86:87]
	v_lshlrev_b64 v[78:79], 13, v[70:71]
	v_lshl_add_u64 v[72:73], v[144:145], 0, v[72:73]
	v_lshl_add_u64 v[78:79], v[148:149], 0, v[78:79]
	v_lshl_add_u64 v[80:81], v[72:73], 0, v[142:143]
	v_lshl_add_u64 v[72:73], v[78:79], 0, v[142:143]
	s_waitcnt vmcnt(0)
; __device__ __forceinline__ float bflo(unsigned u) { return __uint_as_float(u << 16); }
; __device__ __forceinline__ float bfhi(unsigned u) { return __uint_as_float(u & 0xffff0000u); }
; template <int MODE>
; __device__ __forceinline__ void gemm_epilogue(char* ws, const float* __restrict__ xseq, float* __restrict__ oseq, const int pm, const int pn,
;                                               f32x4 (&acc)[2][2][4][2], const int wave) {
;     ...
;     } else if (MODE == G_PROJ || MODE == G_MERGE1 || MODE == G_MERGE2) {
; #pragma unroll
;       for (int bj = 0; bj < 2; ++bj) {
;         const int cb = bcol + bj * HALF + wc * 32;
;         u32x2 w[2], gg[2], tt[2];
;         if (MODE == G_MERGE1) load_pair16(gates + (long)row * GWID + cb, fq, gg[0], gg[1]);
;         if (MODE == G_MERGE2) { load_pair16(gates + (long)row * GWID + 2048 + cb, fq, gg[0], gg[1]);
;                                 load_pair16((const bf16*)(ws + OFF_TMP) + (long)row * DM + cb, fq, tt[0], tt[1]); }
; #pragma unroll
;         for (int n = 0; n < 2; ++n) {
;           f32x4 v = acc[ai][bj][m][n];
;           if (MODE == G_PROJ) {
;             if (bcol >= AQKV + BQKV) { v[0] = sigmoidf_(v[0]); v[1] = sigmoidf_(v[1]); v[2] = sigmoidf_(v[2]); v[3] = sigmoidf_(v[3]); }
;             w[n] = u32x2{cvtpk(v[0], v[1]), cvtpk(v[2], v[3])};
;           } else if (MODE == G_MERGE1) {
;             const u32x2 ga = gg[n];
;             w[n] = u32x2{cvtpk(v[0] * bflo(ga[0]), v[1] * bfhi(ga[0])), cvtpk(v[2] * bflo(ga[1]), v[3] * bfhi(ga[1]))};
;           } else {
;             const u32x2 gb = gg[n], tv = tt[n];
;             w[n] = u32x2{cvtpk(bflo(tv[0]) + v[0] * bflo(gb[0]), bfhi(tv[0]) + v[1] * bfhi(gb[0])), cvtpk(bflo(tv[1]) + v[2] * bflo(gb[1]), bfhi(tv[1]) + v[3] * bfhi(gb[1]))};
;           }
;         }
;         bf16* dst;
;         if (MODE == G_PROJ) {
;           if (bcol < AQKV) dst = (bf16*)(ws + OFF_QKVA) + (long)row * AQKV + cb;
;           else if (bcol < AQKV + BQKV) dst = (bf16*)(ws + OFF_QKVB) + (long)row * BQKV + (cb - AQKV);
;           else dst = gates + (long)row * GWID + (cb - AQKV - BQKV);
;         } else if (MODE == G_MERGE1) dst = (bf16*)(ws + OFF_TMP) + (long)row * DM + cb;
;         else dst = (bf16*)(ws + OFF_H) + (long)row * DM + cb;
;         store_pair16(dst, w[0], w[1], fq);
	v_mov_b32_e32 v0, v68
	v_mov_b32_e32 v68, v69
	v_mov_b32_e32 v69, v76
	v_mov_b32_e32 v76, v77
	s_nop 0
	v_permlane16_swap_b32_e32 v74, v69
	v_permlane16_swap_b32_e32 v75, v76
	v_permlane16_swap_b32_e32 v66, v0
	v_permlane16_swap_b32_e32 v67, v68
	v_lshlrev_b32_e32 v83, 16, v74
	v_and_b32_e32 v74, 0xffff0000, v74
	v_lshlrev_b32_e32 v84, 16, v75
	v_and_b32_e32 v75, 0xffff0000, v75
	v_lshlrev_b32_e32 v77, 16, v66
	v_and_b32_e32 v66, 0xffff0000, v66
	v_lshlrev_b32_e32 v78, 16, v67
	v_and_b32_e32 v67, 0xffff0000, v67
	v_lshlrev_b32_e32 v79, 16, v0
	v_and_b32_e32 v0, 0xffff0000, v0
	v_lshlrev_b32_e32 v82, 16, v68
	v_and_b32_e32 v68, 0xffff0000, v68
	v_lshlrev_b32_e32 v85, 16, v69
	v_and_b32_e32 v69, 0xffff0000, v69
	v_lshlrev_b32_e32 v86, 16, v76
	v_and_b32_e32 v76, 0xffff0000, v76
	v_mul_f32_e32 v54, v54, v83
	v_mul_f32_e32 v55, v55, v74
	v_mul_f32_e32 v56, v56, v84
	v_mul_f32_e32 v57, v57, v75
	v_mul_f32_e32 v62, v62, v77
	v_mul_f32_e32 v63, v63, v66
	v_mul_f32_e32 v64, v64, v78
	v_mul_f32_e32 v65, v65, v67
	v_mul_f32_e32 v58, v58, v79
	v_mul_f32_e32 v0, v59, v0
	v_mul_f32_e32 v59, v60, v82
	v_mul_f32_e32 v60, v61, v68
	v_mul_f32_e32 v61, v50, v85
	v_mul_f32_e32 v66, v51, v69
	v_mul_f32_e32 v67, v52, v86
	v_mul_f32_e32 v68, v53, v76
	v_cvt_pk_bf16_f32 v50, v62, v63
	v_cvt_pk_bf16_f32 v51, v64, v65
	v_cvt_pk_bf16_f32 v52, v58, v0
	v_cvt_pk_bf16_f32 v53, v59, v60
	v_cvt_pk_bf16_f32 v54, v54, v55
	v_cvt_pk_bf16_f32 v55, v56, v57
	v_cvt_pk_bf16_f32 v56, v61, v66
	v_cvt_pk_bf16_f32 v57, v67, v68
	s_nop 0
	v_permlane16_swap_b32_e32 v50, v52
	v_permlane16_swap_b32_e32 v51, v53
	v_permlane16_swap_b32_e32 v54, v56
	v_permlane16_swap_b32_e32 v55, v57
	global_store_dwordx4 v[80:81], v[50:53], off
	global_store_dwordx4 v[80:81], v[54:57], off offset:256
	global_load_dwordx4 v[50:53], v[72:73], off
	s_nop 0
	global_load_dwordx4 v[58:61], v[72:73], off offset:256
	v_add_u32_e32 v54, 0xa0, v146
	v_ashrrev_i32_e32 v55, 31, v54
	v_lshlrev_b64 v[56:57], 12, v[70:71]
	v_lshlrev_b64 v[62:63], 13, v[54:55]
	v_lshl_add_u64 v[56:57], v[144:145], 0, v[56:57]
	v_lshl_add_u64 v[62:63], v[148:149], 0, v[62:63]
	v_lshl_add_u64 v[64:65], v[56:57], 0, v[142:143]
	v_lshl_add_u64 v[56:57], v[62:63], 0, v[142:143]
	s_waitcnt vmcnt(0)
	v_mov_b32_e32 v0, v52
	v_mov_b32_e32 v52, v53
	v_mov_b32_e32 v53, v60
	v_mov_b32_e32 v60, v61
	s_nop 0
	v_permlane16_swap_b32_e32 v58, v53
	v_permlane16_swap_b32_e32 v59, v60
	v_permlane16_swap_b32_e32 v50, v0
	v_permlane16_swap_b32_e32 v51, v52
	v_lshlrev_b32_e32 v67, 16, v58
	v_and_b32_e32 v58, 0xffff0000, v58
	v_lshlrev_b32_e32 v68, 16, v59
	v_and_b32_e32 v59, 0xffff0000, v59
	v_lshlrev_b32_e32 v61, 16, v50
	v_and_b32_e32 v50, 0xffff0000, v50
	v_lshlrev_b32_e32 v62, 16, v51
	v_and_b32_e32 v51, 0xffff0000, v51
	v_lshlrev_b32_e32 v63, 16, v0
	v_and_b32_e32 v0, 0xffff0000, v0
	v_lshlrev_b32_e32 v66, 16, v52
	v_and_b32_e32 v52, 0xffff0000, v52
	v_lshlrev_b32_e32 v69, 16, v53
	v_and_b32_e32 v53, 0xffff0000, v53
	v_lshlrev_b32_e32 v70, 16, v60
	v_and_b32_e32 v60, 0xffff0000, v60
	v_mul_f32_e32 v38, v38, v67
	v_mul_f32_e32 v39, v39, v58
	v_mul_f32_e32 v40, v40, v68
	v_mul_f32_e32 v41, v41, v59
	v_mul_f32_e32 v46, v46, v61
	v_mul_f32_e32 v47, v47, v50
	v_mul_f32_e32 v48, v48, v62
	v_mul_f32_e32 v49, v49, v51
	v_mul_f32_e32 v42, v42, v63
	v_mul_f32_e32 v0, v43, v0
	v_mul_f32_e32 v43, v44, v66
	v_mul_f32_e32 v44, v45, v52
	v_mul_f32_e32 v45, v34, v69
	v_mul_f32_e32 v50, v35, v53
	v_mul_f32_e32 v51, v36, v70
	v_mul_f32_e32 v52, v37, v60
	v_cvt_pk_bf16_f32 v34, v46, v47
	v_cvt_pk_bf16_f32 v35, v48, v49
	v_cvt_pk_bf16_f32 v36, v42, v0
	v_cvt_pk_bf16_f32 v37, v43, v44
	v_cvt_pk_bf16_f32 v38, v38, v39
	v_cvt_pk_bf16_f32 v39, v40, v41
	v_cvt_pk_bf16_f32 v40, v45, v50
	v_cvt_pk_bf16_f32 v41, v51, v52
	s_nop 0
	v_permlane16_swap_b32_e32 v34, v36
	v_permlane16_swap_b32_e32 v35, v37
	v_permlane16_swap_b32_e32 v38, v40
	v_permlane16_swap_b32_e32 v39, v41
	global_store_dwordx4 v[64:65], v[34:37], off
	global_store_dwordx4 v[64:65], v[38:41], off offset:256
	global_load_dwordx4 v[34:37], v[56:57], off
	s_nop 0
	global_load_dwordx4 v[42:45], v[56:57], off offset:256
	v_add_u32_e32 v38, 0xb0, v146
	v_ashrrev_i32_e32 v39, 31, v38
	v_lshlrev_b64 v[40:41], 12, v[54:55]
	v_lshlrev_b64 v[46:47], 13, v[38:39]
	v_lshl_add_u64 v[40:41], v[144:145], 0, v[40:41]
	v_lshl_add_u64 v[46:47], v[148:149], 0, v[46:47]
	v_lshl_add_u64 v[48:49], v[40:41], 0, v[142:143]
	v_lshl_add_u64 v[40:41], v[46:47], 0, v[142:143]
	s_waitcnt vmcnt(0)
; __device__ __forceinline__ float bflo(unsigned u) { return __uint_as_float(u << 16); }
; __device__ __forceinline__ float bfhi(unsigned u) { return __uint_as_float(u & 0xffff0000u); }
; template <int MODE>
; __device__ __forceinline__ void gemm_epilogue(char* ws, const float* __restrict__ xseq, float* __restrict__ oseq, const int pm, const int pn,
;                                               f32x4 (&acc)[2][2][4][2], const int wave) {
;     ...
;     } else if (MODE == G_PROJ || MODE == G_MERGE1 || MODE == G_MERGE2) {
; #pragma unroll
;       for (int bj = 0; bj < 2; ++bj) {
;         const int cb = bcol + bj * HALF + wc * 32;
;         u32x2 w[2], gg[2], tt[2];
;         if (MODE == G_MERGE1) load_pair16(gates + (long)row * GWID + cb, fq, gg[0], gg[1]);
;         if (MODE == G_MERGE2) { load_pair16(gates + (long)row * GWID + 2048 + cb, fq, gg[0], gg[1]);
;                                 load_pair16((const bf16*)(ws + OFF_TMP) + (long)row * DM + cb, fq, tt[0], tt[1]); }
; #pragma unroll
;         for (int n = 0; n < 2; ++n) {
;           f32x4 v = acc[ai][bj][m][n];
;           if (MODE == G_PROJ) {
;             if (bcol >= AQKV + BQKV) { v[0] = sigmoidf_(v[0]); v[1] = sigmoidf_(v[1]); v[2] = sigmoidf_(v[2]); v[3] = sigmoidf_(v[3]); }
;             w[n] = u32x2{cvtpk(v[0], v[1]), cvtpk(v[2], v[3])};
;           } else if (MODE == G_MERGE1) {
;             const u32x2 ga = gg[n];
;             w[n] = u32x2{cvtpk(v[0] * bflo(ga[0]), v[1] * bfhi(ga[0])), cvtpk(v[2] * bflo(ga[1]), v[3] * bfhi(ga[1]))};
;           } else {
;             const u32x2 gb = gg[n], tv = tt[n];
;             w[n] = u32x2{cvtpk(bflo(tv[0]) + v[0] * bflo(gb[0]), bfhi(tv[0]) + v[1] * bfhi(gb[0])), cvtpk(bflo(tv[1]) + v[2] * bflo(gb[1]), bfhi(tv[1]) + v[3] * bfhi(gb[1]))};
;           }
;         }
;         bf16* dst;
;         if (MODE == G_PROJ) {
;           if (bcol < AQKV) dst = (bf16*)(ws + OFF_QKVA) + (long)row * AQKV + cb;
;           else if (bcol < AQKV + BQKV) dst = (bf16*)(ws + OFF_QKVB) + (long)row * BQKV + (cb - AQKV);
;           else dst = gates + (long)row * GWID + (cb - AQKV - BQKV);
;         } else if (MODE == G_MERGE1) dst = (bf16*)(ws + OFF_TMP) + (long)row * DM + cb;
;         else dst = (bf16*)(ws + OFF_H) + (long)row * DM + cb;
;         store_pair16(dst, w[0], w[1], fq);
	v_mov_b32_e32 v0, v36
	v_mov_b32_e32 v36, v37
	v_mov_b32_e32 v37, v44
	v_mov_b32_e32 v44, v45
	s_nop 0
	v_permlane16_swap_b32_e32 v42, v37
	v_permlane16_swap_b32_e32 v43, v44
	v_permlane16_swap_b32_e32 v34, v0
	v_permlane16_swap_b32_e32 v35, v36
	v_lshlrev_b32_e32 v51, 16, v42
	v_and_b32_e32 v42, 0xffff0000, v42
	v_lshlrev_b32_e32 v52, 16, v43
	v_and_b32_e32 v43, 0xffff0000, v43
	v_lshlrev_b32_e32 v45, 16, v34
	v_and_b32_e32 v34, 0xffff0000, v34
	v_lshlrev_b32_e32 v46, 16, v35
	v_and_b32_e32 v35, 0xffff0000, v35
	v_lshlrev_b32_e32 v47, 16, v0
	v_and_b32_e32 v0, 0xffff0000, v0
	v_lshlrev_b32_e32 v50, 16, v36
	v_and_b32_e32 v36, 0xffff0000, v36
	v_lshlrev_b32_e32 v53, 16, v37
	v_and_b32_e32 v37, 0xffff0000, v37
	v_lshlrev_b32_e32 v54, 16, v44
	v_and_b32_e32 v44, 0xffff0000, v44
	v_mul_f32_e32 v22, v22, v51
	v_mul_f32_e32 v23, v23, v42
	v_mul_f32_e32 v24, v24, v52
	v_mul_f32_e32 v25, v25, v43
	v_mul_f32_e32 v30, v30, v45
	v_mul_f32_e32 v31, v31, v34
	v_mul_f32_e32 v32, v32, v46
	v_mul_f32_e32 v33, v33, v35
	v_mul_f32_e32 v26, v26, v47
	v_mul_f32_e32 v0, v27, v0
	v_mul_f32_e32 v27, v28, v50
	v_mul_f32_e32 v28, v29, v36
	v_mul_f32_e32 v29, v18, v53
	v_mul_f32_e32 v34, v19, v37
	v_mul_f32_e32 v35, v20, v54
	v_mul_f32_e32 v36, v21, v44
	v_cvt_pk_bf16_f32 v18, v30, v31
	v_cvt_pk_bf16_f32 v19, v32, v33
	v_cvt_pk_bf16_f32 v20, v26, v0
	v_cvt_pk_bf16_f32 v21, v27, v28
	v_cvt_pk_bf16_f32 v22, v22, v23
	v_cvt_pk_bf16_f32 v23, v24, v25
	v_cvt_pk_bf16_f32 v24, v29, v34
	v_cvt_pk_bf16_f32 v25, v35, v36
	s_nop 0
	v_permlane16_swap_b32_e32 v18, v20
	v_permlane16_swap_b32_e32 v19, v21
	v_permlane16_swap_b32_e32 v22, v24
	v_permlane16_swap_b32_e32 v23, v25
	global_store_dwordx4 v[48:49], v[18:21], off
	global_store_dwordx4 v[48:49], v[22:25], off offset:256
	global_load_dwordx4 v[18:21], v[40:41], off
	v_lshlrev_b64 v[26:27], 12, v[38:39]
	global_load_dwordx4 v[22:25], v[40:41], off offset:256
	v_lshl_add_u64 v[26:27], v[144:145], 0, v[26:27]
	v_lshl_add_u64 v[26:27], v[26:27], 0, v[142:143]
	s_waitcnt vmcnt(0)
	v_mov_b32_e32 v0, v20
	v_mov_b32_e32 v20, v21
	v_mov_b32_e32 v21, v24
	v_mov_b32_e32 v24, v25
	v_permlane16_swap_b32_e32 v18, v0
	v_permlane16_swap_b32_e32 v19, v20
	v_permlane16_swap_b32_e32 v22, v21
	v_permlane16_swap_b32_e32 v23, v24
	v_lshlrev_b32_e32 v25, 16, v18
	v_and_b32_e32 v18, 0xffff0000, v18
	v_lshlrev_b32_e32 v28, 16, v19
	v_and_b32_e32 v19, 0xffff0000, v19
	v_lshlrev_b32_e32 v29, 16, v0
	v_and_b32_e32 v0, 0xffff0000, v0
	v_lshlrev_b32_e32 v30, 16, v20
	v_and_b32_e32 v20, 0xffff0000, v20
	v_lshlrev_b32_e32 v31, 16, v22
	v_and_b32_e32 v22, 0xffff0000, v22
	v_lshlrev_b32_e32 v32, 16, v23
	v_and_b32_e32 v23, 0xffff0000, v23
	v_lshlrev_b32_e32 v33, 16, v21
	v_and_b32_e32 v21, 0xffff0000, v21
	v_lshlrev_b32_e32 v34, 16, v24
	v_and_b32_e32 v24, 0xffff0000, v24
	v_mul_f32_e32 v14, v14, v25
	v_mul_f32_e32 v15, v15, v18
	v_mul_f32_e32 v16, v16, v28
	v_mul_f32_e32 v17, v17, v19
	v_mul_f32_e32 v10, v10, v29
	v_mul_f32_e32 v0, v11, v0
	v_mul_f32_e32 v11, v12, v30
	v_mul_f32_e32 v12, v13, v20
	v_mul_f32_e32 v6, v6, v31
	v_mul_f32_e32 v7, v7, v22
	v_mul_f32_e32 v8, v8, v32
	v_mul_f32_e32 v9, v9, v23
	v_mul_f32_e32 v13, v2, v33
	v_mul_f32_e32 v18, v3, v21
	v_mul_f32_e32 v19, v4, v34
	v_mul_f32_e32 v20, v5, v24
	v_cvt_pk_bf16_f32 v2, v14, v15
	v_cvt_pk_bf16_f32 v3, v16, v17
	v_cvt_pk_bf16_f32 v4, v10, v0
	v_cvt_pk_bf16_f32 v5, v11, v12
	v_cvt_pk_bf16_f32 v6, v6, v7
	v_cvt_pk_bf16_f32 v7, v8, v9
	v_cvt_pk_bf16_f32 v8, v13, v18
	v_cvt_pk_bf16_f32 v9, v19, v20
	s_nop 0
	v_permlane16_swap_b32_e32 v2, v4
	v_permlane16_swap_b32_e32 v3, v5
	v_permlane16_swap_b32_e32 v6, v8
	v_permlane16_swap_b32_e32 v7, v9
	global_store_dwordx4 v[26:27], v[2:5], off
	global_store_dwordx4 v[26:27], v[6:9], off offset:256
	s_cbranch_scc0 .LBB0_63
	s_waitcnt vmcnt(0)
	s_movk_i32 s2, 0x100
	v_cmp_gt_u32_e32 vcc, s2, v154
	s_and_saveexec_b64 s[4:5], vcc
	s_cbranch_execz .LBB0_74
	s_barrier

; #define LDA(dst, b, h) _Pragma("unroll") for (int m = 0; m < 4; ++m) _Pragma("unroll") for (int k = 0; k < 2; ++k) \
;     dst[m][k] = *reinterpret_cast<const bf16x8*>((char*)SA(b, h) + lds_byte(wr * 64 + m * 16 + fr, k * 32 + fq * 8))
; #define LDB(dst, b, h) _Pragma("unroll") for (int n = 0; n < 2; ++n) _Pragma("unroll") for (int k = 0; k < 2; ++k) \
;     dst[n][k] = *reinterpret_cast<const bf16x8*>((char*)SB(b, h) + lds_byte(wc * 32 + n * 16 + fr, k * 32 + fq * 8))
; #define WAIT_V(n) asm volatile("s_waitcnt vmcnt(" #n ")" ::: "memory")
; #define WAIT_L(n) asm volatile("s_waitcnt lgkmcnt(" #n ")" ::: "memory")
; #define BAR __builtin_amdgcn_s_barrier()
; #define SCHED __builtin_amdgcn_sched_barrier(0)
; template <int MODE>
; __device__ __forceinline__ void gemm_phase(int s, char* lds, const int wave) {
;     ...
;       for (int t = 0; t < nt; t += 2) {
;         const bool lastit = t + 2 >= nt;
;         const bf16* A2 = lastit ? Anext : Acur; const bf16* B2 = lastit ? Bnext : Bcur; const int k2 = lastit ? 0 : t + 2;
;         LDB(B0, 0, 0); SCHED; LDA(At, 0, 0); STAGE(SA(1, 1), Acur, HALF, t + 1);
;         WAIT_L(8); BAR; WAIT_L(0); MMA(0, 0, At, B0); BAR; SCHED;
;         LDB(B1, 0, 1); STAGE(SB(0, 0), B2, 0, k2);
;         BAR; WAIT_L(0); MMA(0, 1, At, B1); BAR;
;         LDA(At, 0, 1); STAGE(SA(0, 0), A2, 0, k2);
;         BAR; WAIT_L(0); MMA(1, 0, At, B0); BAR; SCHED;
;         STAGE(SB(0, 1), B2, HALF, k2);
;         WAIT_V(6); BAR; MMA(1, 1, At, B1); BAR;
;         LDB(B0, 1, 0); SCHED; LDA(At, 1, 0); STAGE(SA(0, 1), A2, HALF, k2);
;         WAIT_L(8); BAR; WAIT_L(0); MMA(0, 0, At, B0); BAR; SCHED;
;         LDB(B1, 1, 1); STAGE(SB(1, 0), B2, 0, k2 + 1);
;         BAR; WAIT_L(0); MMA(0, 1, At, B1); BAR;
;         LDA(At, 1, 1); STAGE(SA(1, 0), A2, 0, k2 + 1);
;         BAR; WAIT_L(0); MMA(1, 0, At, B0); BAR; SCHED;
;         STAGE(SB(1, 1), B2, HALF, k2 + 1);
;         WAIT_V(6); BAR; MMA(1, 1, At, B1); BAR;
;       }
.LBB0_90:
	ds_read_b128 v[134:137], v179
	ds_read_b128 v[138:141], v179 offset:1024
	ds_read_b128 v[150:153], v179 offset:2048
	ds_read_b128 v[154:157], v179 offset:3072
	s_add_i32 s11, s11, 2
	s_cmp_gt_u32 s11, 29
	s_cselect_b64 s[40:41], -1, 0
	s_and_b64 vcc, s[40:41], exec
	s_cselect_b32 s44, s53, s59
	s_cselect_b32 s45, s52, s58
	v_add_u32_e32 v0, 0xc000, v167
	ds_read_b128 v[158:161], v180
	ds_read_b128 v[200:203], v180 offset:1024
	ds_read_b128 v[204:207], v181
	ds_read_b128 v[208:211], v181 offset:1024
	ds_read_b128 v[212:215], v182
	ds_read_b128 v[216:219], v182 offset:1024
	ds_read_b128 v[220:223], v183
	ds_read_b128 v[224:227], v183 offset:1024
	v_readfirstlane_b32 s30, v0
	v_add_u32_e32 v0, 0xe000, v167
	s_mov_b32 m0, s30
	v_readfirstlane_b32 s30, v0
	global_load_lds_dwordx4 v[132:133], off
	s_mov_b32 m0, s30
	s_nop 0
	global_load_lds_dwordx4 v[130:131], off
	s_waitcnt lgkmcnt(8)
	s_barrier
	s_waitcnt lgkmcnt(0)
	s_waitcnt lgkmcnt(0)
	v_mfma_f32_16x16x32_bf16 v[126:129], v[134:137], v[158:161], v[126:129]
	v_mfma_f32_16x16x32_bf16 v[122:125], v[150:153], v[158:161], v[122:125]
	v_mfma_f32_16x16x32_bf16 v[110:113], v[134:137], v[204:207], v[110:113]
	v_mfma_f32_16x16x32_bf16 v[106:109], v[150:153], v[204:207], v[106:109]
	v_mfma_f32_16x16x32_bf16 v[94:97], v[134:137], v[212:215], v[94:97]
	v_mfma_f32_16x16x32_bf16 v[90:93], v[150:153], v[212:215], v[90:93]
	v_mfma_f32_16x16x32_bf16 v[78:81], v[134:137], v[220:223], v[78:81]
	v_mfma_f32_16x16x32_bf16 v[74:77], v[150:153], v[220:223], v[74:77]
	v_mfma_f32_16x16x32_bf16 v[126:129], v[138:141], v[200:203], v[126:129]
	v_mfma_f32_16x16x32_bf16 v[122:125], v[154:157], v[200:203], v[122:125]
	v_mfma_f32_16x16x32_bf16 v[110:113], v[138:141], v[208:211], v[110:113]
	v_mfma_f32_16x16x32_bf16 v[106:109], v[154:157], v[208:211], v[106:109]
	v_mfma_f32_16x16x32_bf16 v[94:97], v[138:141], v[216:219], v[94:97]
	v_mfma_f32_16x16x32_bf16 v[90:93], v[154:157], v[216:219], v[90:93]
	v_mfma_f32_16x16x32_bf16 v[78:81], v[138:141], v[224:227], v[78:81]
	v_mfma_f32_16x16x32_bf16 v[74:77], v[154:157], v[224:227], v[74:77]
	s_barrier
	s_cselect_b32 s30, 0, s15
	s_cselect_b32 s46, s55, s61
	s_cselect_b32 s47, s54, s60
	s_lshl_b64 s[40:41], s[30:31], 1
	s_add_u32 s42, s47, s40
	s_addc_u32 s43, s46, s41
	v_readfirstlane_b32 s57, v165
	v_lshl_add_u64 v[162:163], s[42:43], 0, v[142:143]
	s_mov_b32 m0, s57
	v_lshl_add_u64 v[244:245], s[42:43], 0, v[144:145]
	v_readfirstlane_b32 s42, v166
	ds_read_b128 v[228:231], v184
	ds_read_b128 v[232:235], v184 offset:1024
	ds_read_b128 v[236:239], v184 offset:2048
	ds_read_b128 v[240:243], v184 offset:3072
	global_load_lds_dwordx4 v[162:163], off
	s_mov_b32 m0, s42
	s_nop 0
	global_load_lds_dwordx4 v[244:245], off
	s_barrier
	s_waitcnt lgkmcnt(0)
	s_waitcnt lgkmcnt(0)
	v_mfma_f32_16x16x32_bf16 v[118:121], v[228:231], v[158:161], v[118:121]
	v_mfma_f32_16x16x32_bf16 v[114:117], v[236:239], v[158:161], v[114:117]
	v_mfma_f32_16x16x32_bf16 v[102:105], v[228:231], v[204:207], v[102:105]
	v_mfma_f32_16x16x32_bf16 v[98:101], v[236:239], v[204:207], v[98:101]
	v_mfma_f32_16x16x32_bf16 v[86:89], v[228:231], v[212:215], v[86:89]
	v_mfma_f32_16x16x32_bf16 v[82:85], v[236:239], v[212:215], v[82:85]
	v_mfma_f32_16x16x32_bf16 v[70:73], v[228:231], v[220:223], v[70:73]
	v_mfma_f32_16x16x32_bf16 v[66:69], v[236:239], v[220:223], v[66:69]
	v_mfma_f32_16x16x32_bf16 v[118:121], v[232:235], v[200:203], v[118:121]
	v_mfma_f32_16x16x32_bf16 v[114:117], v[240:243], v[200:203], v[114:117]
	v_mfma_f32_16x16x32_bf16 v[102:105], v[232:235], v[208:211], v[102:105]
	v_mfma_f32_16x16x32_bf16 v[98:101], v[240:243], v[208:211], v[98:101]
	v_mfma_f32_16x16x32_bf16 v[86:89], v[232:235], v[216:219], v[86:89]
	v_mfma_f32_16x16x32_bf16 v[82:85], v[240:243], v[216:219], v[82:85]
	v_mfma_f32_16x16x32_bf16 v[70:73], v[232:235], v[224:227], v[70:73]
	v_mfma_f32_16x16x32_bf16 v[66:69], v[240:243], v[224:227], v[66:69]
	s_add_u32 s42, s45, s40
	s_addc_u32 s43, s44, s41
	v_readfirstlane_b32 s44, v167
	v_lshl_add_u64 v[246:247], s[42:43], 0, v[142:143]
	s_mov_b32 m0, s44
	v_readfirstlane_b32 s44, v168
	s_barrier
	ds_read_b128 v[158:161], v180 offset:16384
	ds_read_b128 v[200:203], v180 offset:17408
	ds_read_b128 v[204:207], v181 offset:16384
	ds_read_b128 v[208:211], v181 offset:17408
	ds_read_b128 v[212:215], v182 offset:16384
	ds_read_b128 v[216:219], v182 offset:17408
	ds_read_b128 v[220:223], v183 offset:16384
	ds_read_b128 v[224:227], v183 offset:17408
	global_load_lds_dwordx4 v[246:247], off
	v_lshl_add_u64 v[248:249], s[42:43], 0, v[144:145]
	s_mov_b32 m0, s44
	s_nop 0
	global_load_lds_dwordx4 v[248:249], off
	s_barrier
	s_waitcnt lgkmcnt(0)
	s_waitcnt lgkmcnt(0)
	v_mfma_f32_16x16x32_bf16 v[62:65], v[134:137], v[158:161], v[62:65]
	v_mfma_f32_16x16x32_bf16 v[58:61], v[150:153], v[158:161], v[58:61]
	v_mfma_f32_16x16x32_bf16 v[46:49], v[134:137], v[204:207], v[46:49]
	v_mfma_f32_16x16x32_bf16 v[42:45], v[150:153], v[204:207], v[42:45]
	v_mfma_f32_16x16x32_bf16 v[30:33], v[134:137], v[212:215], v[30:33]
	v_mfma_f32_16x16x32_bf16 v[26:29], v[150:153], v[212:215], v[26:29]
	v_mfma_f32_16x16x32_bf16 v[14:17], v[134:137], v[220:223], v[14:17]
	v_mfma_f32_16x16x32_bf16 v[10:13], v[150:153], v[220:223], v[10:13]
	v_mfma_f32_16x16x32_bf16 v[62:65], v[138:141], v[200:203], v[62:65]
	v_mfma_f32_16x16x32_bf16 v[58:61], v[154:157], v[200:203], v[58:61]
	v_mfma_f32_16x16x32_bf16 v[46:49], v[138:141], v[208:211], v[46:49]
	v_mfma_f32_16x16x32_bf16 v[42:45], v[154:157], v[208:211], v[42:45]
	v_mfma_f32_16x16x32_bf16 v[30:33], v[138:141], v[216:219], v[30:33]
	v_mfma_f32_16x16x32_bf16 v[26:29], v[154:157], v[216:219], v[26:29]
	v_mfma_f32_16x16x32_bf16 v[14:17], v[138:141], v[224:227], v[14:17]
	v_mfma_f32_16x16x32_bf16 v[10:13], v[154:157], v[224:227], v[10:13]
	s_barrier
; #define LDA(dst, b, h) _Pragma("unroll") for (int m = 0; m < 4; ++m) _Pragma("unroll") for (int k = 0; k < 2; ++k) \
;     dst[m][k] = *reinterpret_cast<const bf16x8*>((char*)SA(b, h) + lds_byte(wr * 64 + m * 16 + fr, k * 32 + fq * 8))
; #define LDB(dst, b, h) _Pragma("unroll") for (int n = 0; n < 2; ++n) _Pragma("unroll") for (int k = 0; k < 2; ++k) \
;     dst[n][k] = *reinterpret_cast<const bf16x8*>((char*)SB(b, h) + lds_byte(wc * 32 + n * 16 + fr, k * 32 + fq * 8))
; #define WAIT_V(n) asm volatile("s_waitcnt vmcnt(" #n ")" ::: "memory")
; #define WAIT_L(n) asm volatile("s_waitcnt lgkmcnt(" #n ")" ::: "memory")
; #define BAR __builtin_amdgcn_s_barrier()
; #define SCHED __builtin_amdgcn_sched_barrier(0)
; template <int MODE>
; __device__ __forceinline__ void gemm_phase(int s, char* lds, const int wave) {
;     ...
;       for (int t = 0; t < nt; t += 2) {
;         const bool lastit = t + 2 >= nt;
;         const bf16* A2 = lastit ? Anext : Acur; const bf16* B2 = lastit ? Bnext : Bcur; const int k2 = lastit ? 0 : t + 2;
;         LDB(B0, 0, 0); SCHED; LDA(At, 0, 0); STAGE(SA(1, 1), Acur, HALF, t + 1);
;         WAIT_L(8); BAR; WAIT_L(0); MMA(0, 0, At, B0); BAR; SCHED;
;         LDB(B1, 0, 1); STAGE(SB(0, 0), B2, 0, k2);
;         BAR; WAIT_L(0); MMA(0, 1, At, B1); BAR;
;         LDA(At, 0, 1); STAGE(SA(0, 0), A2, 0, k2);
;         BAR; WAIT_L(0); MMA(1, 0, At, B0); BAR; SCHED;
;         STAGE(SB(0, 1), B2, HALF, k2);
;         WAIT_V(6); BAR; MMA(1, 1, At, B1); BAR;
;         LDB(B0, 1, 0); SCHED; LDA(At, 1, 0); STAGE(SA(0, 1), A2, HALF, k2);
;         WAIT_L(8); BAR; WAIT_L(0); MMA(0, 0, At, B0); BAR; SCHED;
;         LDB(B1, 1, 1); STAGE(SB(1, 0), B2, 0, k2 + 1);
;         BAR; WAIT_L(0); MMA(0, 1, At, B1); BAR;
;         LDA(At, 1, 1); STAGE(SA(1, 0), A2, 0, k2 + 1);
;         BAR; WAIT_L(0); MMA(1, 0, At, B0); BAR; SCHED;
;         STAGE(SB(1, 1), B2, HALF, k2 + 1);
;         WAIT_V(6); BAR; MMA(1, 1, At, B1); BAR;
;       }
	s_add_u32 s62, s47, 0x80000
	s_addc_u32 s63, s46, 0
	s_add_u32 s40, s62, s40
	s_addc_u32 s41, s63, s41
	v_readfirstlane_b32 s44, v169
	v_lshl_add_u64 v[134:135], s[40:41], 0, v[142:143]
	s_mov_b32 m0, s44
	s_nop 0
	global_load_lds_dwordx4 v[134:135], off
	v_lshl_add_u64 v[134:135], s[40:41], 0, v[144:145]
	v_readfirstlane_b32 s40, v170
	s_mov_b32 m0, s40
	s_nop 0
	global_load_lds_dwordx4 v[134:135], off
	s_waitcnt vmcnt(6)
	s_barrier
	v_mfma_f32_16x16x32_bf16 v[54:57], v[228:231], v[158:161], v[54:57]
	v_mfma_f32_16x16x32_bf16 v[50:53], v[236:239], v[158:161], v[50:53]
	v_mfma_f32_16x16x32_bf16 v[38:41], v[228:231], v[204:207], v[38:41]
	v_mfma_f32_16x16x32_bf16 v[34:37], v[236:239], v[204:207], v[34:37]
	v_mfma_f32_16x16x32_bf16 v[22:25], v[228:231], v[212:215], v[22:25]
	v_mfma_f32_16x16x32_bf16 v[18:21], v[236:239], v[212:215], v[18:21]
	v_mfma_f32_16x16x32_bf16 v[6:9], v[228:231], v[220:223], v[6:9]
	v_mfma_f32_16x16x32_bf16 v[2:5], v[236:239], v[220:223], v[2:5]
	v_mfma_f32_16x16x32_bf16 v[54:57], v[232:235], v[200:203], v[54:57]
	v_mfma_f32_16x16x32_bf16 v[50:53], v[240:243], v[200:203], v[50:53]
	v_mfma_f32_16x16x32_bf16 v[38:41], v[232:235], v[208:211], v[38:41]
	v_mfma_f32_16x16x32_bf16 v[34:37], v[240:243], v[208:211], v[34:37]
	v_mfma_f32_16x16x32_bf16 v[22:25], v[232:235], v[216:219], v[22:25]
	v_mfma_f32_16x16x32_bf16 v[18:21], v[240:243], v[216:219], v[18:21]
	v_mfma_f32_16x16x32_bf16 v[6:9], v[232:235], v[224:227], v[6:9]
	v_mfma_f32_16x16x32_bf16 v[2:5], v[240:243], v[224:227], v[2:5]
	s_barrier
	ds_read_b128 v[134:137], v185
	ds_read_b128 v[138:141], v185 offset:1024
	ds_read_b128 v[150:153], v185 offset:2048
	ds_read_b128 v[154:157], v185 offset:3072
	s_add_u32 s40, s42, 0x80000
	s_addc_u32 s41, s43, 0
	v_readfirstlane_b32 s42, v171
	v_lshl_add_u64 v[228:229], s[40:41], 0, v[142:143]
	s_mov_b32 m0, s42
	ds_read_b128 v[158:161], v180 offset:32768
	ds_read_b128 v[200:203], v180 offset:33792
	ds_read_b128 v[204:207], v181 offset:32768
	ds_read_b128 v[208:211], v181 offset:33792
	ds_read_b128 v[212:215], v182 offset:32768
	ds_read_b128 v[216:219], v182 offset:33792
	ds_read_b128 v[220:223], v183 offset:32768
	ds_read_b128 v[224:227], v183 offset:33792
	global_load_lds_dwordx4 v[228:229], off
	v_lshl_add_u64 v[228:229], s[40:41], 0, v[144:145]
	v_readfirstlane_b32 s40, v172
	s_mov_b32 m0, s40
	s_nop 0
	global_load_lds_dwordx4 v[228:229], off
	s_waitcnt lgkmcnt(8)
	s_barrier
	s_waitcnt lgkmcnt(0)
	s_waitcnt lgkmcnt(0)
	v_mfma_f32_16x16x32_bf16 v[126:129], v[134:137], v[158:161], v[126:129]
	v_mfma_f32_16x16x32_bf16 v[122:125], v[150:153], v[158:161], v[122:125]
	v_mfma_f32_16x16x32_bf16 v[110:113], v[134:137], v[204:207], v[110:113]
	v_mfma_f32_16x16x32_bf16 v[106:109], v[150:153], v[204:207], v[106:109]
	v_mfma_f32_16x16x32_bf16 v[94:97], v[134:137], v[212:215], v[94:97]
	v_mfma_f32_16x16x32_bf16 v[90:93], v[150:153], v[212:215], v[90:93]
	v_mfma_f32_16x16x32_bf16 v[78:81], v[134:137], v[220:223], v[78:81]
	v_mfma_f32_16x16x32_bf16 v[74:77], v[150:153], v[220:223], v[74:77]
	v_mfma_f32_16x16x32_bf16 v[126:129], v[138:141], v[200:203], v[126:129]
	v_mfma_f32_16x16x32_bf16 v[122:125], v[154:157], v[200:203], v[122:125]
	v_mfma_f32_16x16x32_bf16 v[110:113], v[138:141], v[208:211], v[110:113]
	v_mfma_f32_16x16x32_bf16 v[106:109], v[154:157], v[208:211], v[106:109]
	v_mfma_f32_16x16x32_bf16 v[94:97], v[138:141], v[216:219], v[94:97]
	v_mfma_f32_16x16x32_bf16 v[90:93], v[154:157], v[216:219], v[90:93]
	v_mfma_f32_16x16x32_bf16 v[78:81], v[138:141], v[224:227], v[78:81]
	v_mfma_f32_16x16x32_bf16 v[74:77], v[154:157], v[224:227], v[74:77]
	s_barrier
	v_readfirstlane_b32 s40, v173
	v_lshl_add_u64 v[162:163], v[162:163], 0, s[18:19]
	s_mov_b32 m0, s40
	v_readfirstlane_b32 s40, v174
	ds_read_b128 v[228:231], v198
	ds_read_b128 v[232:235], v198 offset:1024
	ds_read_b128 v[236:239], v198 offset:2048
	ds_read_b128 v[240:243], v198 offset:3072
	global_load_lds_dwordx4 v[162:163], off
	v_lshl_add_u64 v[162:163], v[244:245], 0, s[18:19]
	s_mov_b32 m0, s40
	s_or_b32 s30, s30, 64
	global_load_lds_dwordx4 v[162:163], off
	s_barrier
	s_waitcnt lgkmcnt(0)
	s_waitcnt lgkmcnt(0)
	v_mfma_f32_16x16x32_bf16 v[118:121], v[228:231], v[158:161], v[118:121]
	v_mfma_f32_16x16x32_bf16 v[114:117], v[236:239], v[158:161], v[114:117]
	v_mfma_f32_16x16x32_bf16 v[102:105], v[228:231], v[204:207], v[102:105]
	v_mfma_f32_16x16x32_bf16 v[98:101], v[236:239], v[204:207], v[98:101]
	v_mfma_f32_16x16x32_bf16 v[86:89], v[228:231], v[212:215], v[86:89]
	v_mfma_f32_16x16x32_bf16 v[82:85], v[236:239], v[212:215], v[82:85]
	v_mfma_f32_16x16x32_bf16 v[70:73], v[228:231], v[220:223], v[70:73]
	v_mfma_f32_16x16x32_bf16 v[66:69], v[236:239], v[220:223], v[66:69]
	v_mfma_f32_16x16x32_bf16 v[118:121], v[232:235], v[200:203], v[118:121]
	v_mfma_f32_16x16x32_bf16 v[114:117], v[240:243], v[200:203], v[114:117]
	v_mfma_f32_16x16x32_bf16 v[102:105], v[232:235], v[208:211], v[102:105]
	v_mfma_f32_16x16x32_bf16 v[98:101], v[240:243], v[208:211], v[98:101]
	v_mfma_f32_16x16x32_bf16 v[86:89], v[232:235], v[216:219], v[86:89]
	v_mfma_f32_16x16x32_bf16 v[82:85], v[240:243], v[216:219], v[82:85]
	v_mfma_f32_16x16x32_bf16 v[70:73], v[232:235], v[224:227], v[70:73]
	v_mfma_f32_16x16x32_bf16 v[66:69], v[240:243], v[224:227], v[66:69]
	v_readfirstlane_b32 s40, v175
	v_lshl_add_u64 v[162:163], v[246:247], 0, s[18:19]
	s_mov_b32 m0, s40
	v_readfirstlane_b32 s40, v176
	s_barrier
; #define LDA(dst, b, h) _Pragma("unroll") for (int m = 0; m < 4; ++m) _Pragma("unroll") for (int k = 0; k < 2; ++k) \
;     dst[m][k] = *reinterpret_cast<const bf16x8*>((char*)SA(b, h) + lds_byte(wr * 64 + m * 16 + fr, k * 32 + fq * 8))
; #define WAIT_V(n) asm volatile("s_waitcnt vmcnt(" #n ")" ::: "memory")
; template <int MODE>
; __device__ __forceinline__ void gemm_epilogue(char* ws, const float* __restrict__ xseq, float* __restrict__ oseq, const int pm, const int pn,
;                                               f32x4 (&acc)[2][2][4][2], const int wave) {
;     ...
;     } else if (MODE == G_PROJ || MODE == G_MERGE1 || MODE == G_MERGE2) {
; #pragma unroll
;       for (int bj = 0; bj < 2; ++bj) {
;         const int cb = bcol + bj * HALF + wc * 32;
;         u32x2 w[2], gg[2], tt[2];
;         if (MODE == G_MERGE1) load_pair16(gates + (long)row * GWID + cb, fq, gg[0], gg[1]);
;         if (MODE == G_MERGE2) { load_pair16(gates + (long)row * GWID + 2048 + cb, fq, gg[0], gg[1]);
;                                 load_pair16((const bf16*)(ws + OFF_TMP) + (long)row * DM + cb, fq, tt[0], tt[1]); }
; #pragma unroll
; template <int MODE>
; __device__ __forceinline__ void gemm_phase(int s, char* lds, const int wave) {
;     ...
;       for (int t = 0; t < nt; t += 2) {
;         const bool lastit = t + 2 >= nt;
;         const bf16* A2 = lastit ? Anext : Acur; const bf16* B2 = lastit ? Bnext : Bcur; const int k2 = lastit ? 0 : t + 2;
;         LDB(B0, 0, 0); SCHED; LDA(At, 0, 0); STAGE(SA(1, 1), Acur, HALF, t + 1);
;         WAIT_L(8); BAR; WAIT_L(0); MMA(0, 0, At, B0); BAR; SCHED;
;         LDB(B1, 0, 1); STAGE(SB(0, 0), B2, 0, k2);
;         BAR; WAIT_L(0); MMA(0, 1, At, B1); BAR;
;         LDA(At, 0, 1); STAGE(SA(0, 0), A2, 0, k2);
;         BAR; WAIT_L(0); MMA(1, 0, At, B0); BAR; SCHED;
;         STAGE(SB(0, 1), B2, HALF, k2);
;         WAIT_V(6); BAR; MMA(1, 1, At, B1); BAR;
;         LDB(B0, 1, 0); SCHED; LDA(At, 1, 0); STAGE(SA(0, 1), A2, HALF, k2);
;         WAIT_L(8); BAR; WAIT_L(0); MMA(0, 0, At, B0); BAR; SCHED;
;         LDB(B1, 1, 1); STAGE(SB(1, 0), B2, 0, k2 + 1);
;         BAR; WAIT_L(0); MMA(0, 1, At, B1); BAR;
;         LDA(At, 1, 1); STAGE(SA(1, 0), A2, 0, k2 + 1);
;         BAR; WAIT_L(0); MMA(1, 0, At, B0); BAR; SCHED;
;         STAGE(SB(1, 1), B2, HALF, k2 + 1);
;         WAIT_V(6); BAR; MMA(1, 1, At, B1); BAR;
;       }
	ds_read_b128 v[158:161], v180 offset:49152
	ds_read_b128 v[200:203], v180 offset:50176
	ds_read_b128 v[204:207], v181 offset:49152
	ds_read_b128 v[208:211], v181 offset:50176
	ds_read_b128 v[212:215], v182 offset:49152
	ds_read_b128 v[216:219], v182 offset:50176
	ds_read_b128 v[220:223], v183 offset:49152
	ds_read_b128 v[224:227], v183 offset:50176
	global_load_lds_dwordx4 v[162:163], off
	v_lshl_add_u64 v[162:163], v[248:249], 0, s[18:19]
	s_mov_b32 m0, s40
	s_nop 0
	global_load_lds_dwordx4 v[162:163], off
	s_barrier
	s_waitcnt lgkmcnt(0)
	s_waitcnt lgkmcnt(0)
	v_mfma_f32_16x16x32_bf16 v[62:65], v[134:137], v[158:161], v[62:65]
	v_mfma_f32_16x16x32_bf16 v[58:61], v[150:153], v[158:161], v[58:61]
	v_mfma_f32_16x16x32_bf16 v[46:49], v[134:137], v[204:207], v[46:49]
	v_mfma_f32_16x16x32_bf16 v[42:45], v[150:153], v[204:207], v[42:45]
	v_mfma_f32_16x16x32_bf16 v[30:33], v[134:137], v[212:215], v[30:33]
	v_mfma_f32_16x16x32_bf16 v[26:29], v[150:153], v[212:215], v[26:29]
	v_mfma_f32_16x16x32_bf16 v[14:17], v[134:137], v[220:223], v[14:17]
	v_mfma_f32_16x16x32_bf16 v[10:13], v[150:153], v[220:223], v[10:13]
	v_mfma_f32_16x16x32_bf16 v[62:65], v[138:141], v[200:203], v[62:65]
	v_mfma_f32_16x16x32_bf16 v[58:61], v[154:157], v[200:203], v[58:61]
	v_mfma_f32_16x16x32_bf16 v[46:49], v[138:141], v[208:211], v[46:49]
	v_mfma_f32_16x16x32_bf16 v[42:45], v[154:157], v[208:211], v[42:45]
	v_mfma_f32_16x16x32_bf16 v[30:33], v[138:141], v[216:219], v[30:33]
	v_mfma_f32_16x16x32_bf16 v[26:29], v[154:157], v[216:219], v[26:29]
	v_mfma_f32_16x16x32_bf16 v[14:17], v[138:141], v[224:227], v[14:17]
	v_mfma_f32_16x16x32_bf16 v[10:13], v[154:157], v[224:227], v[10:13]
	s_barrier
	v_lshl_add_u64 v[134:135], s[62:63], 0, v[142:143]
	s_lshl_b64 s[40:41], s[30:31], 1
	v_readfirstlane_b32 s30, v177
	v_lshl_add_u64 v[134:135], v[134:135], 0, s[40:41]
	s_mov_b32 m0, s30
	v_readfirstlane_b32 s30, v178
	global_load_lds_dwordx4 v[134:135], off
	v_lshl_add_u64 v[134:135], s[62:63], 0, v[144:145]
	v_lshl_add_u64 v[134:135], v[134:135], 0, s[40:41]
	s_mov_b32 m0, s30
	s_nop 0
	global_load_lds_dwordx4 v[134:135], off
	s_waitcnt vmcnt(6)
	s_barrier
	v_mfma_f32_16x16x32_bf16 v[54:57], v[228:231], v[158:161], v[54:57]
	v_mfma_f32_16x16x32_bf16 v[50:53], v[236:239], v[158:161], v[50:53]
	v_mfma_f32_16x16x32_bf16 v[38:41], v[228:231], v[204:207], v[38:41]
	v_mfma_f32_16x16x32_bf16 v[34:37], v[236:239], v[204:207], v[34:37]
	v_mfma_f32_16x16x32_bf16 v[22:25], v[228:231], v[212:215], v[22:25]
	v_mfma_f32_16x16x32_bf16 v[18:21], v[236:239], v[212:215], v[18:21]
	v_mfma_f32_16x16x32_bf16 v[6:9], v[228:231], v[220:223], v[6:9]
	v_mfma_f32_16x16x32_bf16 v[2:5], v[236:239], v[220:223], v[2:5]
	v_mfma_f32_16x16x32_bf16 v[54:57], v[232:235], v[200:203], v[54:57]
	v_mfma_f32_16x16x32_bf16 v[50:53], v[240:243], v[200:203], v[50:53]
	v_mfma_f32_16x16x32_bf16 v[38:41], v[232:235], v[208:211], v[38:41]
	v_mfma_f32_16x16x32_bf16 v[34:37], v[240:243], v[208:211], v[34:37]
	v_mfma_f32_16x16x32_bf16 v[22:25], v[232:235], v[216:219], v[22:25]
	v_mfma_f32_16x16x32_bf16 v[18:21], v[240:243], v[216:219], v[18:21]
	v_mfma_f32_16x16x32_bf16 v[6:9], v[232:235], v[224:227], v[6:9]
	v_mfma_f32_16x16x32_bf16 v[2:5], v[240:243], v[224:227], v[2:5]
	v_lshl_add_u64 v[130:131], v[130:131], 0, s[38:39]
	v_lshl_add_u64 v[132:133], v[132:133], 0, s[38:39]
	s_addk_i32 s15, 0x80
	s_barrier
	s_cbranch_vccz .LBB0_90
	v_mov_b32_e32 v0, v187
	s_lshl_b32 s11, s56, 8
	v_ashrrev_i32_e32 v130, 2, v0
	v_and_b32_e32 v130, 0xffffffc0, v130
	v_and_or_b32 v131, v0, 15, s11
	v_add_u32_e32 v154, v131, v130
	v_lshrrev_b32_e32 v130, 1, v0
	v_and_b32_e32 v131, 16, v0
	v_lshrrev_b32_e32 v0, 2, v0
	v_and_b32_e32 v0, 12, v0
	v_and_b32_e32 v130, 0x60, v130
	v_add_u32_e32 v132, 12, v0
	v_cmp_eq_u32_e32 vcc, 0, v131
	v_ashrrev_i32_e32 v155, 31, v154
	v_lshl_or_b32 v130, s2, 8, v130
	v_cndmask_b32_e32 v0, v132, v0, vcc
	v_lshlrev_b64 v[132:133], 13, v[154:155]
	v_lshlrev_b32_e32 v0, 1, v0
	v_lshl_add_u64 v[132:133], s[4:5], 0, v[132:133]
	v_ashrrev_i32_e32 v131, 31, v130
	v_lshl_add_u64 v[152:153], s[6:7], 0, v[0:1]
	v_lshl_add_u64 v[132:133], v[132:133], 0, v[0:1]
	v_lshlrev_b64 v[160:161], 12, v[154:155]
	v_lshlrev_b64 v[150:151], 1, v[130:131]
	v_lshl_add_u64 v[134:135], v[152:153], 0, v[160:161]
	v_lshl_add_u64 v[136:137], v[132:133], 0, v[150:151]
	s_mov_b32 s2, 0x21e01000
	v_lshl_add_u64 v[130:131], v[134:135], 0, v[150:151]
	v_add_co_u32_e32 v134, vcc, s2, v136
	global_load_dwordx4 v[138:141], v[130:131], off
	s_nop 0
	global_load_dwordx4 v[130:133], v[130:131], off offset:256
	v_addc_co_u32_e32 v135, vcc, 0, v137, vcc
	global_load_dwordx4 v[200:203], v[134:135], off
	s_mov_b64 s[40:41], 0x21e01000
	v_lshl_add_u64 v[134:135], v[136:137], 0, s[40:41]
	global_load_dwordx4 v[134:137], v[134:135], off offset:256
	v_or_b32_e32 v162, 16, v154
	v_lshl_add_u64 v[156:157], s[8:9], 0, v[0:1]
	v_ashrrev_i32_e32 v163, 31, v162
	v_lshl_add_u64 v[160:161], v[156:157], 0, v[160:161]
	v_lshlrev_b64 v[158:159], 12, v[162:163]
	v_lshl_add_u64 v[160:161], v[160:161], 0, v[150:151]
	s_cmpk_gt_i32 s64, 0x1ff
	s_mov_b64 s[60:61], s[54:55]
	s_mov_b64 s[58:59], s[52:53]
	s_mov_b32 s56, s10
	s_waitcnt vmcnt(0)
; __device__ __forceinline__ float bflo(unsigned u) { return __uint_as_float(u << 16); }
; __device__ __forceinline__ float bfhi(unsigned u) { return __uint_as_float(u & 0xffff0000u); }
; template <int MODE>
; __device__ __forceinline__ void gemm_epilogue(char* ws, const float* __restrict__ xseq, float* __restrict__ oseq, const int pm, const int pn,
;                                               f32x4 (&acc)[2][2][4][2], const int wave) {
;     ...
;     } else if (MODE == G_PROJ || MODE == G_MERGE1 || MODE == G_MERGE2) {
; #pragma unroll
;       for (int bj = 0; bj < 2; ++bj) {
;         const int cb = bcol + bj * HALF + wc * 32;
;         u32x2 w[2], gg[2], tt[2];
;         if (MODE == G_MERGE1) load_pair16(gates + (long)row * GWID + cb, fq, gg[0], gg[1]);
;         if (MODE == G_MERGE2) { load_pair16(gates + (long)row * GWID + 2048 + cb, fq, gg[0], gg[1]);
;                                 load_pair16((const bf16*)(ws + OFF_TMP) + (long)row * DM + cb, fq, tt[0], tt[1]); }
; #pragma unroll
;         for (int n = 0; n < 2; ++n) {
;           f32x4 v = acc[ai][bj][m][n];
;           if (MODE == G_PROJ) {
;             if (bcol >= AQKV + BQKV) { v[0] = sigmoidf_(v[0]); v[1] = sigmoidf_(v[1]); v[2] = sigmoidf_(v[2]); v[3] = sigmoidf_(v[3]); }
;             w[n] = u32x2{cvtpk(v[0], v[1]), cvtpk(v[2], v[3])};
;           } else if (MODE == G_MERGE1) {
;             const u32x2 ga = gg[n];
;             w[n] = u32x2{cvtpk(v[0] * bflo(ga[0]), v[1] * bfhi(ga[0])), cvtpk(v[2] * bflo(ga[1]), v[3] * bfhi(ga[1]))};
;           } else {
;             const u32x2 gb = gg[n], tv = tt[n];
;             w[n] = u32x2{cvtpk(bflo(tv[0]) + v[0] * bflo(gb[0]), bfhi(tv[0]) + v[1] * bfhi(gb[0])), cvtpk(bflo(tv[1]) + v[2] * bflo(gb[1]), bfhi(tv[1]) + v[3] * bfhi(gb[1]))};
;           }
;         }
;         bf16* dst;
;         if (MODE == G_PROJ) {
;           if (bcol < AQKV) dst = (bf16*)(ws + OFF_QKVA) + (long)row * AQKV + cb;
;           else if (bcol < AQKV + BQKV) dst = (bf16*)(ws + OFF_QKVB) + (long)row * BQKV + (cb - AQKV);
;           else dst = gates + (long)row * GWID + (cb - AQKV - BQKV);
;         } else if (MODE == G_MERGE1) dst = (bf16*)(ws + OFF_TMP) + (long)row * DM + cb;
;         else dst = (bf16*)(ws + OFF_H) + (long)row * DM + cb;
;         store_pair16(dst, w[0], w[1], fq);
	v_permlane16_swap_b32_e32 v138, v140
	v_mov_b32_e32 v155, v132
	v_mov_b32_e32 v199, v133
	v_mov_b32_e32 v132, v202
	v_mov_b32_e32 v133, v203
	v_permlane16_swap_b32_e32 v139, v141
	v_permlane16_swap_b32_e32 v200, v132
	v_permlane16_swap_b32_e32 v201, v133
	v_mov_b32_e32 v202, v136
	v_mov_b32_e32 v203, v137
	v_lshlrev_b32_e32 v136, 16, v138
	v_and_b32_e32 v137, 0xffff0000, v138
	v_lshlrev_b32_e32 v138, 16, v139
	v_and_b32_e32 v139, 0xffff0000, v139
	v_lshlrev_b32_e32 v204, 16, v140
	v_and_b32_e32 v140, 0xffff0000, v140
	v_lshlrev_b32_e32 v205, 16, v141
	v_and_b32_e32 v141, 0xffff0000, v141
	v_lshlrev_b32_e32 v206, 16, v200
	v_and_b32_e32 v200, 0xffff0000, v200
	v_lshlrev_b32_e32 v207, 16, v201
	v_and_b32_e32 v201, 0xffff0000, v201
	v_lshlrev_b32_e32 v208, 16, v132
	v_and_b32_e32 v132, 0xffff0000, v132
	v_lshlrev_b32_e32 v209, 16, v133
	v_and_b32_e32 v133, 0xffff0000, v133
	v_fmac_f32_e32 v136, v126, v206
	v_fmac_f32_e32 v137, v127, v200
	v_fmac_f32_e32 v138, v128, v207
	v_fmac_f32_e32 v139, v129, v201
	v_fmac_f32_e32 v204, v122, v208
	v_fmac_f32_e32 v140, v123, v132
	v_fmac_f32_e32 v205, v124, v209
	v_fmac_f32_e32 v141, v125, v133
	v_cvt_pk_bf16_f32 v122, v136, v137
	v_cvt_pk_bf16_f32 v123, v138, v139
	v_cvt_pk_bf16_f32 v124, v204, v140
	v_cvt_pk_bf16_f32 v125, v205, v141
	v_permlane16_swap_b32_e32 v130, v155
	v_permlane16_swap_b32_e32 v122, v124
	v_permlane16_swap_b32_e32 v123, v125
	global_store_dwordx4 v[160:161], v[122:125], off
	v_permlane16_swap_b32_e32 v134, v202
	s_nop 0
	v_lshl_add_u64 v[122:123], v[152:153], 0, v[158:159]
	v_lshl_add_u64 v[132:133], v[122:123], 0, v[150:151]
	v_lshlrev_b64 v[122:123], 13, v[162:163]
	v_lshl_add_u64 v[122:123], s[4:5], 0, v[122:123]
	v_lshl_add_u64 v[122:123], v[122:123], 0, v[0:1]
	v_lshl_add_u64 v[136:137], v[122:123], 0, v[150:151]
	v_add_co_u32_e32 v122, vcc, s2, v136
	global_load_dwordx4 v[126:129], v[132:133], off
	s_nop 0
	v_addc_co_u32_e32 v123, vcc, 0, v137, vcc
	global_load_dwordx4 v[122:125], v[122:123], off
	v_lshlrev_b32_e32 v138, 16, v130
	v_lshlrev_b32_e32 v139, 16, v134
	v_permlane16_swap_b32_e32 v135, v203
	v_permlane16_swap_b32_e32 v131, v199
	v_fmac_f32_e32 v138, v118, v139
	v_and_b32_e32 v118, 0xffff0000, v130
	v_and_b32_e32 v130, 0xffff0000, v134
	v_fmac_f32_e32 v118, v119, v130
	v_lshlrev_b32_e32 v119, 16, v131
	v_lshlrev_b32_e32 v130, 16, v135
	v_fmac_f32_e32 v119, v120, v130
	v_and_b32_e32 v120, 0xffff0000, v131
	v_and_b32_e32 v130, 0xffff0000, v135
	v_fmac_f32_e32 v120, v121, v130
	v_cvt_pk_bf16_f32 v119, v119, v120
	v_lshlrev_b32_e32 v120, 16, v155
	v_lshlrev_b32_e32 v121, 16, v202
	v_fmac_f32_e32 v120, v114, v121
	v_and_b32_e32 v114, 0xffff0000, v155
	v_and_b32_e32 v121, 0xffff0000, v202
	v_fmac_f32_e32 v114, v115, v121
	v_cvt_pk_bf16_f32 v120, v120, v114
	v_lshlrev_b32_e32 v114, 16, v199
	v_lshlrev_b32_e32 v115, 16, v203
	v_fmac_f32_e32 v114, v116, v115
	v_and_b32_e32 v115, 0xffff0000, v199
	v_and_b32_e32 v116, 0xffff0000, v203
	v_cvt_pk_bf16_f32 v118, v138, v118
	v_fmac_f32_e32 v115, v117, v116
	v_cvt_pk_bf16_f32 v121, v114, v115
	v_permlane16_swap_b32_e32 v118, v120
	v_permlane16_swap_b32_e32 v119, v121
	global_store_dwordx4 v[160:161], v[118:121], off offset:256
	v_lshl_add_u64 v[114:115], v[136:137], 0, s[40:41]
	global_load_dwordx4 v[114:117], v[114:115], off offset:256
	s_nop 0
	global_load_dwordx4 v[118:121], v[132:133], off offset:256
	v_lshl_add_u64 v[130:131], v[156:157], 0, v[158:159]
	s_waitcnt vmcnt(0)
	v_permlane16_swap_b32_e32 v126, v128
	v_permlane16_swap_b32_e32 v127, v129
	v_permlane16_swap_b32_e32 v122, v124
	v_lshlrev_b32_e32 v134, 16, v128
	v_permlane16_swap_b32_e32 v123, v125
	v_lshlrev_b32_e32 v138, 16, v124
	v_and_b32_e32 v128, 0xffff0000, v128
	v_lshlrev_b32_e32 v135, 16, v129
	v_and_b32_e32 v124, 0xffff0000, v124
	v_fmac_f32_e32 v134, v106, v138
	v_lshlrev_b32_e32 v106, 16, v125
	v_fmac_f32_e32 v128, v107, v124
	v_fmac_f32_e32 v135, v108, v106
	v_and_b32_e32 v106, 0xffff0000, v129
	v_and_b32_e32 v107, 0xffff0000, v125
	v_lshlrev_b32_e32 v133, 16, v127
	v_and_b32_e32 v127, 0xffff0000, v127
	v_lshlrev_b32_e32 v137, 16, v123
	v_and_b32_e32 v123, 0xffff0000, v123
	v_fmac_f32_e32 v106, v109, v107
	v_fmac_f32_e32 v127, v113, v123
	v_cvt_pk_bf16_f32 v113, v135, v106
	v_or_b32_e32 v106, 32, v154
	v_ashrrev_i32_e32 v107, 31, v106
	v_lshlrev_b64 v[108:109], 13, v[106:107]
	v_lshlrev_b32_e32 v132, 16, v126
	v_and_b32_e32 v126, 0xffff0000, v126
	v_lshlrev_b32_e32 v136, 16, v122
	v_and_b32_e32 v122, 0xffff0000, v122
	v_lshl_add_u64 v[108:109], s[4:5], 0, v[108:109]
	v_fmac_f32_e32 v132, v110, v136
	v_fmac_f32_e32 v126, v111, v122
	v_fmac_f32_e32 v133, v112, v137
	v_cvt_pk_bf16_f32 v110, v132, v126
	v_cvt_pk_bf16_f32 v111, v133, v127
	v_cvt_pk_bf16_f32 v112, v134, v128
	v_lshl_add_u64 v[108:109], v[108:109], 0, v[0:1]
	v_permlane16_swap_b32_e32 v110, v112
	v_permlane16_swap_b32_e32 v111, v113
	v_lshl_add_u64 v[124:125], v[130:131], 0, v[150:151]
	v_lshlrev_b64 v[122:123], 12, v[106:107]
	v_lshl_add_u64 v[128:129], v[108:109], 0, v[150:151]
	global_store_dwordx4 v[124:125], v[110:113], off
	v_add_co_u32_e32 v106, vcc, s2, v128
	s_nop 0
	v_lshl_add_u64 v[110:111], v[152:153], 0, v[122:123]
	v_addc_co_u32_e32 v107, vcc, 0, v129, vcc
	v_lshl_add_u64 v[126:127], v[110:111], 0, v[150:151]
	global_load_dwordx4 v[106:109], v[106:107], off
	v_permlane16_swap_b32_e32 v114, v116
	global_load_dwordx4 v[110:113], v[126:127], off
	v_permlane16_swap_b32_e32 v118, v120
	v_lshlrev_b32_e32 v130, 16, v118
	v_lshlrev_b32_e32 v131, 16, v114
	v_permlane16_swap_b32_e32 v115, v117
	v_permlane16_swap_b32_e32 v119, v121
	v_fmac_f32_e32 v130, v102, v131
	v_and_b32_e32 v102, 0xffff0000, v118
	v_and_b32_e32 v114, 0xffff0000, v114
	v_fmac_f32_e32 v102, v103, v114
	v_lshlrev_b32_e32 v103, 16, v119
	v_lshlrev_b32_e32 v114, 16, v115
	v_fmac_f32_e32 v103, v104, v114
	v_and_b32_e32 v104, 0xffff0000, v119
	v_and_b32_e32 v114, 0xffff0000, v115
	v_fmac_f32_e32 v104, v105, v114
	v_cvt_pk_bf16_f32 v103, v103, v104
	v_lshlrev_b32_e32 v104, 16, v120
	v_lshlrev_b32_e32 v105, 16, v116
	v_fmac_f32_e32 v104, v98, v105
	v_and_b32_e32 v98, 0xffff0000, v120
	v_and_b32_e32 v105, 0xffff0000, v116
	v_fmac_f32_e32 v98, v99, v105
	v_cvt_pk_bf16_f32 v104, v104, v98
	v_lshlrev_b32_e32 v98, 16, v121
	v_lshlrev_b32_e32 v99, 16, v117
	v_fmac_f32_e32 v98, v100, v99
	v_and_b32_e32 v99, 0xffff0000, v121
	v_and_b32_e32 v100, 0xffff0000, v117
	v_cvt_pk_bf16_f32 v102, v130, v102
	v_fmac_f32_e32 v99, v101, v100
	v_cvt_pk_bf16_f32 v105, v98, v99
	v_permlane16_swap_b32_e32 v102, v104
	v_permlane16_swap_b32_e32 v103, v105
	global_store_dwordx4 v[124:125], v[102:105], off offset:256
	v_lshl_add_u64 v[98:99], v[128:129], 0, s[40:41]
	global_load_dwordx4 v[98:101], v[98:99], off offset:256
	s_nop 0
	global_load_dwordx4 v[102:105], v[126:127], off offset:256
	v_lshl_add_u64 v[114:115], v[156:157], 0, v[122:123]
	s_waitcnt vmcnt(0)
; __device__ __forceinline__ float bflo(unsigned u) { return __uint_as_float(u << 16); }
; __device__ __forceinline__ float bfhi(unsigned u) { return __uint_as_float(u & 0xffff0000u); }
; template <int MODE>
; __device__ __forceinline__ void gemm_epilogue(char* ws, const float* __restrict__ xseq, float* __restrict__ oseq, const int pm, const int pn,
;                                               f32x4 (&acc)[2][2][4][2], const int wave) {
;     ...
;     } else if (MODE == G_PROJ || MODE == G_MERGE1 || MODE == G_MERGE2) {
; #pragma unroll
;       for (int bj = 0; bj < 2; ++bj) {
;         const int cb = bcol + bj * HALF + wc * 32;
;         u32x2 w[2], gg[2], tt[2];
;         if (MODE == G_MERGE1) load_pair16(gates + (long)row * GWID + cb, fq, gg[0], gg[1]);
;         if (MODE == G_MERGE2) { load_pair16(gates + (long)row * GWID + 2048 + cb, fq, gg[0], gg[1]);
;                                 load_pair16((const bf16*)(ws + OFF_TMP) + (long)row * DM + cb, fq, tt[0], tt[1]); }
; #pragma unroll
;         for (int n = 0; n < 2; ++n) {
;           f32x4 v = acc[ai][bj][m][n];
;           if (MODE == G_PROJ) {
;             if (bcol >= AQKV + BQKV) { v[0] = sigmoidf_(v[0]); v[1] = sigmoidf_(v[1]); v[2] = sigmoidf_(v[2]); v[3] = sigmoidf_(v[3]); }
;             w[n] = u32x2{cvtpk(v[0], v[1]), cvtpk(v[2], v[3])};
;           } else if (MODE == G_MERGE1) {
;             const u32x2 ga = gg[n];
;             w[n] = u32x2{cvtpk(v[0] * bflo(ga[0]), v[1] * bfhi(ga[0])), cvtpk(v[2] * bflo(ga[1]), v[3] * bfhi(ga[1]))};
;           } else {
;             const u32x2 gb = gg[n], tv = tt[n];
;             w[n] = u32x2{cvtpk(bflo(tv[0]) + v[0] * bflo(gb[0]), bfhi(tv[0]) + v[1] * bfhi(gb[0])), cvtpk(bflo(tv[1]) + v[2] * bflo(gb[1]), bfhi(tv[1]) + v[3] * bfhi(gb[1]))};
;           }
;         }
;         bf16* dst;
;         if (MODE == G_PROJ) {
;           if (bcol < AQKV) dst = (bf16*)(ws + OFF_QKVA) + (long)row * AQKV + cb;
;           else if (bcol < AQKV + BQKV) dst = (bf16*)(ws + OFF_QKVB) + (long)row * BQKV + (cb - AQKV);
;           else dst = gates + (long)row * GWID + (cb - AQKV - BQKV);
;         } else if (MODE == G_MERGE1) dst = (bf16*)(ws + OFF_TMP) + (long)row * DM + cb;
;         else dst = (bf16*)(ws + OFF_H) + (long)row * DM + cb;
;         store_pair16(dst, w[0], w[1], fq);
	v_permlane16_swap_b32_e32 v106, v108
	v_lshlrev_b32_e32 v117, 16, v106
	v_permlane16_swap_b32_e32 v110, v112
	v_lshlrev_b32_e32 v116, 16, v110
	v_permlane16_swap_b32_e32 v107, v109
	v_permlane16_swap_b32_e32 v111, v113
	v_fmac_f32_e32 v116, v94, v117
	v_and_b32_e32 v94, 0xffff0000, v110
	v_and_b32_e32 v106, 0xffff0000, v106
	v_fmac_f32_e32 v94, v95, v106
	v_lshlrev_b32_e32 v95, 16, v111
	v_lshlrev_b32_e32 v106, 16, v107
	v_fmac_f32_e32 v95, v96, v106
	v_and_b32_e32 v96, 0xffff0000, v111
	v_and_b32_e32 v106, 0xffff0000, v107
	v_fmac_f32_e32 v96, v97, v106
	v_cvt_pk_bf16_f32 v95, v95, v96
	v_lshlrev_b32_e32 v96, 16, v112
	v_lshlrev_b32_e32 v97, 16, v108
	v_fmac_f32_e32 v96, v90, v97
	v_and_b32_e32 v90, 0xffff0000, v112
	v_and_b32_e32 v97, 0xffff0000, v108
	v_fmac_f32_e32 v90, v91, v97
	v_cvt_pk_bf16_f32 v96, v96, v90
	v_lshlrev_b32_e32 v90, 16, v113
	v_lshlrev_b32_e32 v91, 16, v109
	v_fmac_f32_e32 v90, v92, v91
	v_and_b32_e32 v91, 0xffff0000, v113
	v_and_b32_e32 v92, 0xffff0000, v109
	v_cvt_pk_bf16_f32 v94, v116, v94
	v_fmac_f32_e32 v91, v93, v92
	v_cvt_pk_bf16_f32 v97, v90, v91
	v_permlane16_swap_b32_e32 v94, v96
	v_permlane16_swap_b32_e32 v95, v97
	v_lshl_add_u64 v[106:107], v[114:115], 0, v[150:151]
	global_store_dwordx4 v[106:107], v[94:97], off
	v_mov_b32_e32 v112, v100
	s_nop 0
	v_or_b32_e32 v94, 48, v154
	v_ashrrev_i32_e32 v95, 31, v94
	v_lshlrev_b64 v[90:91], 13, v[94:95]
	v_lshl_add_u64 v[90:91], s[4:5], 0, v[90:91]
	v_lshl_add_u64 v[90:91], v[90:91], 0, v[0:1]
	v_mov_b32_e32 v113, v101
	v_lshl_add_u64 v[110:111], v[90:91], 0, v[150:151]
	v_lshlrev_b64 v[100:101], 12, v[94:95]
	v_add_co_u32_e32 v90, vcc, s2, v110
	v_lshl_add_u64 v[94:95], v[152:153], 0, v[100:101]
	s_nop 0
	v_addc_co_u32_e32 v91, vcc, 0, v111, vcc
	v_lshl_add_u64 v[108:109], v[94:95], 0, v[150:151]
	global_load_dwordx4 v[90:93], v[90:91], off
	v_permlane16_swap_b32_e32 v98, v112
	global_load_dwordx4 v[94:97], v[108:109], off
	v_permlane16_swap_b32_e32 v102, v104
	v_lshlrev_b32_e32 v114, 16, v102
	v_lshlrev_b32_e32 v115, 16, v98
	v_permlane16_swap_b32_e32 v99, v113
	v_permlane16_swap_b32_e32 v103, v105
	v_fmac_f32_e32 v114, v86, v115
	v_and_b32_e32 v86, 0xffff0000, v102
	v_and_b32_e32 v98, 0xffff0000, v98
	v_fmac_f32_e32 v86, v87, v98
	v_lshlrev_b32_e32 v87, 16, v103
	v_lshlrev_b32_e32 v98, 16, v99
	v_fmac_f32_e32 v87, v88, v98
	v_and_b32_e32 v88, 0xffff0000, v103
	v_and_b32_e32 v98, 0xffff0000, v99
	v_fmac_f32_e32 v88, v89, v98
	v_cvt_pk_bf16_f32 v87, v87, v88
	v_lshlrev_b32_e32 v88, 16, v104
	v_lshlrev_b32_e32 v89, 16, v112
	v_fmac_f32_e32 v88, v82, v89
	v_and_b32_e32 v82, 0xffff0000, v104
	v_and_b32_e32 v89, 0xffff0000, v112
	v_fmac_f32_e32 v82, v83, v89
	v_cvt_pk_bf16_f32 v88, v88, v82
	v_lshlrev_b32_e32 v82, 16, v105
	v_lshlrev_b32_e32 v83, 16, v113
	v_fmac_f32_e32 v82, v84, v83
	v_and_b32_e32 v83, 0xffff0000, v105
	v_and_b32_e32 v84, 0xffff0000, v113
	v_cvt_pk_bf16_f32 v86, v114, v86
	v_fmac_f32_e32 v83, v85, v84
	v_cvt_pk_bf16_f32 v89, v82, v83
	v_permlane16_swap_b32_e32 v86, v88
	v_permlane16_swap_b32_e32 v87, v89
	global_store_dwordx4 v[106:107], v[86:89], off offset:256
	v_lshl_add_u64 v[82:83], v[110:111], 0, s[40:41]
	global_load_dwordx4 v[82:85], v[82:83], off offset:256
	s_nop 0
	global_load_dwordx4 v[86:89], v[108:109], off offset:256
	v_lshl_add_u64 v[98:99], v[156:157], 0, v[100:101]
	s_waitcnt vmcnt(0)
	v_permlane16_swap_b32_e32 v90, v92
	v_lshlrev_b32_e32 v101, 16, v90
	v_permlane16_swap_b32_e32 v94, v96
	v_lshlrev_b32_e32 v100, 16, v94
	v_permlane16_swap_b32_e32 v91, v93
	v_permlane16_swap_b32_e32 v95, v97
	v_fmac_f32_e32 v100, v78, v101
	v_and_b32_e32 v78, 0xffff0000, v94
	v_and_b32_e32 v90, 0xffff0000, v90
	v_fmac_f32_e32 v78, v79, v90
	v_lshlrev_b32_e32 v79, 16, v95
	v_lshlrev_b32_e32 v90, 16, v91
	v_fmac_f32_e32 v79, v80, v90
	v_and_b32_e32 v80, 0xffff0000, v95
	v_and_b32_e32 v90, 0xffff0000, v91
	v_fmac_f32_e32 v80, v81, v90
	v_cvt_pk_bf16_f32 v79, v79, v80
	v_lshlrev_b32_e32 v80, 16, v96
	v_lshlrev_b32_e32 v81, 16, v92
	v_fmac_f32_e32 v80, v74, v81
	v_and_b32_e32 v74, 0xffff0000, v96
	v_and_b32_e32 v81, 0xffff0000, v92
	v_fmac_f32_e32 v74, v75, v81
	v_cvt_pk_bf16_f32 v80, v80, v74
	v_lshlrev_b32_e32 v74, 16, v97
	v_lshlrev_b32_e32 v75, 16, v93
	v_fmac_f32_e32 v74, v76, v75
	v_and_b32_e32 v75, 0xffff0000, v97
	v_and_b32_e32 v76, 0xffff0000, v93
	v_cvt_pk_bf16_f32 v78, v100, v78
	v_fmac_f32_e32 v75, v77, v76
	v_cvt_pk_bf16_f32 v81, v74, v75
	v_permlane16_swap_b32_e32 v78, v80
	v_permlane16_swap_b32_e32 v79, v81
	v_lshl_add_u64 v[90:91], v[98:99], 0, v[150:151]
	global_store_dwordx4 v[90:91], v[78:81], off
	v_mov_b32_e32 v96, v84
	s_nop 0
	v_add_u32_e32 v78, 0x80, v154
	v_ashrrev_i32_e32 v79, 31, v78
	v_lshlrev_b64 v[74:75], 13, v[78:79]
	v_lshl_add_u64 v[74:75], s[4:5], 0, v[74:75]
	v_lshl_add_u64 v[74:75], v[74:75], 0, v[0:1]
	v_mov_b32_e32 v97, v85
	v_lshl_add_u64 v[94:95], v[74:75], 0, v[150:151]
	v_lshlrev_b64 v[84:85], 12, v[78:79]
	v_add_co_u32_e32 v74, vcc, s2, v94
	v_lshl_add_u64 v[78:79], v[152:153], 0, v[84:85]
	s_nop 0
	v_addc_co_u32_e32 v75, vcc, 0, v95, vcc
	v_lshl_add_u64 v[92:93], v[78:79], 0, v[150:151]
	global_load_dwordx4 v[74:77], v[74:75], off
	v_permlane16_swap_b32_e32 v82, v96
	global_load_dwordx4 v[78:81], v[92:93], off
	v_permlane16_swap_b32_e32 v86, v88
	v_lshlrev_b32_e32 v98, 16, v86
	v_lshlrev_b32_e32 v99, 16, v82
	v_permlane16_swap_b32_e32 v83, v97
	v_permlane16_swap_b32_e32 v87, v89
	v_fmac_f32_e32 v98, v70, v99
	v_and_b32_e32 v70, 0xffff0000, v86
	v_and_b32_e32 v82, 0xffff0000, v82
	v_fmac_f32_e32 v70, v71, v82
	v_lshlrev_b32_e32 v71, 16, v87
	v_lshlrev_b32_e32 v82, 16, v83
	v_fmac_f32_e32 v71, v72, v82
	v_and_b32_e32 v72, 0xffff0000, v87
	v_and_b32_e32 v82, 0xffff0000, v83
	v_fmac_f32_e32 v72, v73, v82
	v_cvt_pk_bf16_f32 v71, v71, v72
	v_lshlrev_b32_e32 v72, 16, v88
	v_lshlrev_b32_e32 v73, 16, v96
	v_fmac_f32_e32 v72, v66, v73
	v_and_b32_e32 v66, 0xffff0000, v88
	v_and_b32_e32 v73, 0xffff0000, v96
	v_fmac_f32_e32 v66, v67, v73
	v_cvt_pk_bf16_f32 v72, v72, v66
	v_lshlrev_b32_e32 v66, 16, v89
	v_lshlrev_b32_e32 v67, 16, v97
	v_fmac_f32_e32 v66, v68, v67
	v_and_b32_e32 v67, 0xffff0000, v89
	v_and_b32_e32 v68, 0xffff0000, v97
	v_cvt_pk_bf16_f32 v70, v98, v70
	v_fmac_f32_e32 v67, v69, v68
	v_cvt_pk_bf16_f32 v73, v66, v67
	v_permlane16_swap_b32_e32 v70, v72
	v_permlane16_swap_b32_e32 v71, v73
	global_store_dwordx4 v[90:91], v[70:73], off offset:256
	v_lshl_add_u64 v[66:67], v[94:95], 0, s[40:41]
	global_load_dwordx4 v[66:69], v[66:67], off offset:256
	s_nop 0
	global_load_dwordx4 v[70:73], v[92:93], off offset:256
	v_lshl_add_u64 v[82:83], v[156:157], 0, v[84:85]
	s_waitcnt vmcnt(0)
; __device__ __forceinline__ float bflo(unsigned u) { return __uint_as_float(u << 16); }
; __device__ __forceinline__ float bfhi(unsigned u) { return __uint_as_float(u & 0xffff0000u); }
; template <int MODE>
; __device__ __forceinline__ void gemm_epilogue(char* ws, const float* __restrict__ xseq, float* __restrict__ oseq, const int pm, const int pn,
;                                               f32x4 (&acc)[2][2][4][2], const int wave) {
;     ...
;     } else if (MODE == G_PROJ || MODE == G_MERGE1 || MODE == G_MERGE2) {
; #pragma unroll
;       for (int bj = 0; bj < 2; ++bj) {
;         const int cb = bcol + bj * HALF + wc * 32;
;         u32x2 w[2], gg[2], tt[2];
;         if (MODE == G_MERGE1) load_pair16(gates + (long)row * GWID + cb, fq, gg[0], gg[1]);
;         if (MODE == G_MERGE2) { load_pair16(gates + (long)row * GWID + 2048 + cb, fq, gg[0], gg[1]);
;                                 load_pair16((const bf16*)(ws + OFF_TMP) + (long)row * DM + cb, fq, tt[0], tt[1]); }
; #pragma unroll
;         for (int n = 0; n < 2; ++n) {
;           f32x4 v = acc[ai][bj][m][n];
;           if (MODE == G_PROJ) {
;             if (bcol >= AQKV + BQKV) { v[0] = sigmoidf_(v[0]); v[1] = sigmoidf_(v[1]); v[2] = sigmoidf_(v[2]); v[3] = sigmoidf_(v[3]); }
;             w[n] = u32x2{cvtpk(v[0], v[1]), cvtpk(v[2], v[3])};
;           } else if (MODE == G_MERGE1) {
;             const u32x2 ga = gg[n];
;             w[n] = u32x2{cvtpk(v[0] * bflo(ga[0]), v[1] * bfhi(ga[0])), cvtpk(v[2] * bflo(ga[1]), v[3] * bfhi(ga[1]))};
;           } else {
;             const u32x2 gb = gg[n], tv = tt[n];
;             w[n] = u32x2{cvtpk(bflo(tv[0]) + v[0] * bflo(gb[0]), bfhi(tv[0]) + v[1] * bfhi(gb[0])), cvtpk(bflo(tv[1]) + v[2] * bflo(gb[1]), bfhi(tv[1]) + v[3] * bfhi(gb[1]))};
;           }
;         }
;         bf16* dst;
;         if (MODE == G_PROJ) {
;           if (bcol < AQKV) dst = (bf16*)(ws + OFF_QKVA) + (long)row * AQKV + cb;
;           else if (bcol < AQKV + BQKV) dst = (bf16*)(ws + OFF_QKVB) + (long)row * BQKV + (cb - AQKV);
;           else dst = gates + (long)row * GWID + (cb - AQKV - BQKV);
;         } else if (MODE == G_MERGE1) dst = (bf16*)(ws + OFF_TMP) + (long)row * DM + cb;
;         else dst = (bf16*)(ws + OFF_H) + (long)row * DM + cb;
;         store_pair16(dst, w[0], w[1], fq);
	v_permlane16_swap_b32_e32 v74, v76
	v_lshlrev_b32_e32 v85, 16, v74
	v_permlane16_swap_b32_e32 v78, v80
	v_lshlrev_b32_e32 v84, 16, v78
	v_permlane16_swap_b32_e32 v75, v77
	v_permlane16_swap_b32_e32 v79, v81
	v_fmac_f32_e32 v84, v62, v85
	v_and_b32_e32 v62, 0xffff0000, v78
	v_and_b32_e32 v74, 0xffff0000, v74
	v_fmac_f32_e32 v62, v63, v74
	v_lshlrev_b32_e32 v63, 16, v79
	v_lshlrev_b32_e32 v74, 16, v75
	v_fmac_f32_e32 v63, v64, v74
	v_and_b32_e32 v64, 0xffff0000, v79
	v_and_b32_e32 v74, 0xffff0000, v75
	v_fmac_f32_e32 v64, v65, v74
	v_cvt_pk_bf16_f32 v63, v63, v64
	v_lshlrev_b32_e32 v64, 16, v80
	v_lshlrev_b32_e32 v65, 16, v76
	v_fmac_f32_e32 v64, v58, v65
	v_and_b32_e32 v58, 0xffff0000, v80
	v_and_b32_e32 v65, 0xffff0000, v76
	v_fmac_f32_e32 v58, v59, v65
	v_cvt_pk_bf16_f32 v64, v64, v58
	v_lshlrev_b32_e32 v58, 16, v81
	v_lshlrev_b32_e32 v59, 16, v77
	v_fmac_f32_e32 v58, v60, v59
	v_and_b32_e32 v59, 0xffff0000, v81
	v_and_b32_e32 v60, 0xffff0000, v77
	v_cvt_pk_bf16_f32 v62, v84, v62
	v_fmac_f32_e32 v59, v61, v60
	v_cvt_pk_bf16_f32 v65, v58, v59
	v_permlane16_swap_b32_e32 v62, v64
	v_permlane16_swap_b32_e32 v63, v65
	v_lshl_add_u64 v[74:75], v[82:83], 0, v[150:151]
	global_store_dwordx4 v[74:75], v[62:65], off
	v_mov_b32_e32 v80, v68
	s_nop 0
	v_add_u32_e32 v62, 0x90, v154
	v_ashrrev_i32_e32 v63, 31, v62
	v_lshlrev_b64 v[58:59], 13, v[62:63]
	v_lshl_add_u64 v[58:59], s[4:5], 0, v[58:59]
	v_lshl_add_u64 v[58:59], v[58:59], 0, v[0:1]
	v_mov_b32_e32 v81, v69
	v_lshl_add_u64 v[78:79], v[58:59], 0, v[150:151]
	v_lshlrev_b64 v[68:69], 12, v[62:63]
	v_add_co_u32_e32 v58, vcc, s2, v78
	v_lshl_add_u64 v[62:63], v[152:153], 0, v[68:69]
	s_nop 0
	v_addc_co_u32_e32 v59, vcc, 0, v79, vcc
	v_lshl_add_u64 v[76:77], v[62:63], 0, v[150:151]
	global_load_dwordx4 v[58:61], v[58:59], off
	v_permlane16_swap_b32_e32 v66, v80
	global_load_dwordx4 v[62:65], v[76:77], off
	v_permlane16_swap_b32_e32 v70, v72
	v_lshlrev_b32_e32 v82, 16, v70
	v_lshlrev_b32_e32 v83, 16, v66
	v_permlane16_swap_b32_e32 v67, v81
	v_permlane16_swap_b32_e32 v71, v73
	v_fmac_f32_e32 v82, v54, v83
	v_and_b32_e32 v54, 0xffff0000, v70
	v_and_b32_e32 v66, 0xffff0000, v66
	v_fmac_f32_e32 v54, v55, v66
	v_lshlrev_b32_e32 v55, 16, v71
	v_lshlrev_b32_e32 v66, 16, v67
	v_fmac_f32_e32 v55, v56, v66
	v_and_b32_e32 v56, 0xffff0000, v71
	v_and_b32_e32 v66, 0xffff0000, v67
	v_fmac_f32_e32 v56, v57, v66
	v_cvt_pk_bf16_f32 v55, v55, v56
	v_lshlrev_b32_e32 v56, 16, v72
	v_lshlrev_b32_e32 v57, 16, v80
	v_fmac_f32_e32 v56, v50, v57
	v_and_b32_e32 v50, 0xffff0000, v72
	v_and_b32_e32 v57, 0xffff0000, v80
	v_fmac_f32_e32 v50, v51, v57
	v_cvt_pk_bf16_f32 v56, v56, v50
	v_lshlrev_b32_e32 v50, 16, v73
	v_lshlrev_b32_e32 v51, 16, v81
	v_fmac_f32_e32 v50, v52, v51
	v_and_b32_e32 v51, 0xffff0000, v73
	v_and_b32_e32 v52, 0xffff0000, v81
	v_cvt_pk_bf16_f32 v54, v82, v54
	v_fmac_f32_e32 v51, v53, v52
	v_cvt_pk_bf16_f32 v57, v50, v51
	v_permlane16_swap_b32_e32 v54, v56
	v_permlane16_swap_b32_e32 v55, v57
	global_store_dwordx4 v[74:75], v[54:57], off offset:256
	v_lshl_add_u64 v[50:51], v[78:79], 0, s[40:41]
	global_load_dwordx4 v[50:53], v[50:51], off offset:256
	s_nop 0
	global_load_dwordx4 v[54:57], v[76:77], off offset:256
	v_lshl_add_u64 v[66:67], v[156:157], 0, v[68:69]
	s_waitcnt vmcnt(0)
	v_permlane16_swap_b32_e32 v58, v60
	v_lshlrev_b32_e32 v69, 16, v58
	v_permlane16_swap_b32_e32 v62, v64
	v_lshlrev_b32_e32 v68, 16, v62
	v_permlane16_swap_b32_e32 v59, v61
	v_permlane16_swap_b32_e32 v63, v65
	v_fmac_f32_e32 v68, v46, v69
	v_and_b32_e32 v46, 0xffff0000, v62
	v_and_b32_e32 v58, 0xffff0000, v58
	v_fmac_f32_e32 v46, v47, v58
	v_lshlrev_b32_e32 v47, 16, v63
	v_lshlrev_b32_e32 v58, 16, v59
	v_fmac_f32_e32 v47, v48, v58
	v_and_b32_e32 v48, 0xffff0000, v63
	v_and_b32_e32 v58, 0xffff0000, v59
	v_fmac_f32_e32 v48, v49, v58
	v_cvt_pk_bf16_f32 v47, v47, v48
	v_lshlrev_b32_e32 v48, 16, v64
	v_lshlrev_b32_e32 v49, 16, v60
	v_fmac_f32_e32 v48, v42, v49
	v_and_b32_e32 v42, 0xffff0000, v64
	v_and_b32_e32 v49, 0xffff0000, v60
	v_fmac_f32_e32 v42, v43, v49
	v_cvt_pk_bf16_f32 v48, v48, v42
	v_lshlrev_b32_e32 v42, 16, v65
	v_lshlrev_b32_e32 v43, 16, v61
	v_fmac_f32_e32 v42, v44, v43
	v_and_b32_e32 v43, 0xffff0000, v65
	v_and_b32_e32 v44, 0xffff0000, v61
	v_cvt_pk_bf16_f32 v46, v68, v46
	v_fmac_f32_e32 v43, v45, v44
	v_cvt_pk_bf16_f32 v49, v42, v43
	v_permlane16_swap_b32_e32 v46, v48
	v_permlane16_swap_b32_e32 v47, v49
	v_lshl_add_u64 v[58:59], v[66:67], 0, v[150:151]
	global_store_dwordx4 v[58:59], v[46:49], off
	v_mov_b32_e32 v64, v52
	s_nop 0
	v_add_u32_e32 v46, 0xa0, v154
	v_ashrrev_i32_e32 v47, 31, v46
	v_lshlrev_b64 v[42:43], 13, v[46:47]
	v_lshl_add_u64 v[42:43], s[4:5], 0, v[42:43]
	v_lshl_add_u64 v[42:43], v[42:43], 0, v[0:1]
	v_mov_b32_e32 v65, v53
	v_lshl_add_u64 v[62:63], v[42:43], 0, v[150:151]
	v_lshlrev_b64 v[52:53], 12, v[46:47]
	v_add_co_u32_e32 v42, vcc, s2, v62
	v_lshl_add_u64 v[46:47], v[152:153], 0, v[52:53]
	s_nop 0
	v_addc_co_u32_e32 v43, vcc, 0, v63, vcc
	v_lshl_add_u64 v[60:61], v[46:47], 0, v[150:151]
	global_load_dwordx4 v[42:45], v[42:43], off
	v_permlane16_swap_b32_e32 v50, v64
	global_load_dwordx4 v[46:49], v[60:61], off
	v_permlane16_swap_b32_e32 v54, v56
	v_lshlrev_b32_e32 v66, 16, v54
	v_lshlrev_b32_e32 v67, 16, v50
	v_permlane16_swap_b32_e32 v51, v65
	v_permlane16_swap_b32_e32 v55, v57
	v_fmac_f32_e32 v66, v38, v67
	v_and_b32_e32 v38, 0xffff0000, v54
	v_and_b32_e32 v50, 0xffff0000, v50
	v_fmac_f32_e32 v38, v39, v50
	v_lshlrev_b32_e32 v39, 16, v55
	v_lshlrev_b32_e32 v50, 16, v51
	v_fmac_f32_e32 v39, v40, v50
	v_and_b32_e32 v40, 0xffff0000, v55
	v_and_b32_e32 v50, 0xffff0000, v51
	v_fmac_f32_e32 v40, v41, v50
	v_cvt_pk_bf16_f32 v39, v39, v40
	v_lshlrev_b32_e32 v40, 16, v56
	v_lshlrev_b32_e32 v41, 16, v64
	v_fmac_f32_e32 v40, v34, v41
	v_and_b32_e32 v34, 0xffff0000, v56
	v_and_b32_e32 v41, 0xffff0000, v64
	v_fmac_f32_e32 v34, v35, v41
	v_cvt_pk_bf16_f32 v40, v40, v34
	v_lshlrev_b32_e32 v34, 16, v57
	v_lshlrev_b32_e32 v35, 16, v65
	v_fmac_f32_e32 v34, v36, v35
	v_and_b32_e32 v35, 0xffff0000, v57
	v_and_b32_e32 v36, 0xffff0000, v65
	v_cvt_pk_bf16_f32 v38, v66, v38
	v_fmac_f32_e32 v35, v37, v36
	v_cvt_pk_bf16_f32 v41, v34, v35
	v_permlane16_swap_b32_e32 v38, v40
	v_permlane16_swap_b32_e32 v39, v41
	global_store_dwordx4 v[58:59], v[38:41], off offset:256
	v_lshl_add_u64 v[34:35], v[62:63], 0, s[40:41]
	global_load_dwordx4 v[34:37], v[34:35], off offset:256
	s_nop 0
	global_load_dwordx4 v[38:41], v[60:61], off offset:256
	v_lshl_add_u64 v[50:51], v[156:157], 0, v[52:53]
	s_waitcnt vmcnt(0)
; __device__ __forceinline__ float bflo(unsigned u) { return __uint_as_float(u << 16); }
; __device__ __forceinline__ float bfhi(unsigned u) { return __uint_as_float(u & 0xffff0000u); }
; template <int MODE>
; __device__ __forceinline__ void gemm_epilogue(char* ws, const float* __restrict__ xseq, float* __restrict__ oseq, const int pm, const int pn,
;                                               f32x4 (&acc)[2][2][4][2], const int wave) {
;     ...
;     } else if (MODE == G_PROJ || MODE == G_MERGE1 || MODE == G_MERGE2) {
; #pragma unroll
;       for (int bj = 0; bj < 2; ++bj) {
;         const int cb = bcol + bj * HALF + wc * 32;
;         u32x2 w[2], gg[2], tt[2];
;         if (MODE == G_MERGE1) load_pair16(gates + (long)row * GWID + cb, fq, gg[0], gg[1]);
;         if (MODE == G_MERGE2) { load_pair16(gates + (long)row * GWID + 2048 + cb, fq, gg[0], gg[1]);
;                                 load_pair16((const bf16*)(ws + OFF_TMP) + (long)row * DM + cb, fq, tt[0], tt[1]); }
; #pragma unroll
;         for (int n = 0; n < 2; ++n) {
;           f32x4 v = acc[ai][bj][m][n];
;           if (MODE == G_PROJ) {
;             if (bcol >= AQKV + BQKV) { v[0] = sigmoidf_(v[0]); v[1] = sigmoidf_(v[1]); v[2] = sigmoidf_(v[2]); v[3] = sigmoidf_(v[3]); }
;             w[n] = u32x2{cvtpk(v[0], v[1]), cvtpk(v[2], v[3])};
;           } else if (MODE == G_MERGE1) {
;             const u32x2 ga = gg[n];
;             w[n] = u32x2{cvtpk(v[0] * bflo(ga[0]), v[1] * bfhi(ga[0])), cvtpk(v[2] * bflo(ga[1]), v[3] * bfhi(ga[1]))};
;           } else {
;             const u32x2 gb = gg[n], tv = tt[n];
;             w[n] = u32x2{cvtpk(bflo(tv[0]) + v[0] * bflo(gb[0]), bfhi(tv[0]) + v[1] * bfhi(gb[0])), cvtpk(bflo(tv[1]) + v[2] * bflo(gb[1]), bfhi(tv[1]) + v[3] * bfhi(gb[1]))};
;           }
;         }
;         bf16* dst;
;         if (MODE == G_PROJ) {
;           if (bcol < AQKV) dst = (bf16*)(ws + OFF_QKVA) + (long)row * AQKV + cb;
;           else if (bcol < AQKV + BQKV) dst = (bf16*)(ws + OFF_QKVB) + (long)row * BQKV + (cb - AQKV);
;           else dst = gates + (long)row * GWID + (cb - AQKV - BQKV);
;         } else if (MODE == G_MERGE1) dst = (bf16*)(ws + OFF_TMP) + (long)row * DM + cb;
;         else dst = (bf16*)(ws + OFF_H) + (long)row * DM + cb;
;         store_pair16(dst, w[0], w[1], fq);
	v_permlane16_swap_b32_e32 v42, v44
	v_lshlrev_b32_e32 v53, 16, v42
	v_permlane16_swap_b32_e32 v46, v48
	v_lshlrev_b32_e32 v52, 16, v46
	v_permlane16_swap_b32_e32 v43, v45
	v_permlane16_swap_b32_e32 v47, v49
	v_fmac_f32_e32 v52, v30, v53
	v_and_b32_e32 v30, 0xffff0000, v46
	v_and_b32_e32 v42, 0xffff0000, v42
	v_fmac_f32_e32 v30, v31, v42
	v_lshlrev_b32_e32 v31, 16, v47
	v_lshlrev_b32_e32 v42, 16, v43
	v_fmac_f32_e32 v31, v32, v42
	v_and_b32_e32 v32, 0xffff0000, v47
	v_and_b32_e32 v42, 0xffff0000, v43
	v_fmac_f32_e32 v32, v33, v42
	v_cvt_pk_bf16_f32 v31, v31, v32
	v_lshlrev_b32_e32 v32, 16, v48
	v_lshlrev_b32_e32 v33, 16, v44
	v_fmac_f32_e32 v32, v26, v33
	v_and_b32_e32 v26, 0xffff0000, v48
	v_and_b32_e32 v33, 0xffff0000, v44
	v_fmac_f32_e32 v26, v27, v33
	v_cvt_pk_bf16_f32 v32, v32, v26
	v_lshlrev_b32_e32 v26, 16, v49
	v_lshlrev_b32_e32 v27, 16, v45
	v_fmac_f32_e32 v26, v28, v27
	v_and_b32_e32 v27, 0xffff0000, v49
	v_and_b32_e32 v28, 0xffff0000, v45
	v_cvt_pk_bf16_f32 v30, v52, v30
	v_fmac_f32_e32 v27, v29, v28
	v_cvt_pk_bf16_f32 v33, v26, v27
	v_permlane16_swap_b32_e32 v30, v32
	v_permlane16_swap_b32_e32 v31, v33
	v_lshl_add_u64 v[42:43], v[50:51], 0, v[150:151]
	global_store_dwordx4 v[42:43], v[30:33], off
	v_mov_b32_e32 v48, v36
	s_nop 0
	v_add_u32_e32 v30, 0xb0, v154
	v_ashrrev_i32_e32 v31, 31, v30
	v_lshlrev_b64 v[26:27], 13, v[30:31]
	v_lshl_add_u64 v[26:27], s[4:5], 0, v[26:27]
	v_lshl_add_u64 v[26:27], v[26:27], 0, v[0:1]
	v_mov_b32_e32 v49, v37
	v_lshl_add_u64 v[46:47], v[26:27], 0, v[150:151]
	v_mov_b32_e32 v0, v40
	v_lshlrev_b64 v[36:37], 12, v[30:31]
	v_permlane16_swap_b32_e32 v34, v48
	v_add_co_u32_e32 v26, vcc, s2, v46
	v_lshl_add_u64 v[30:31], v[152:153], 0, v[36:37]
	v_permlane16_swap_b32_e32 v38, v0
	v_addc_co_u32_e32 v27, vcc, 0, v47, vcc
	v_lshl_add_u64 v[44:45], v[30:31], 0, v[150:151]
	v_mov_b32_e32 v40, v41
	v_lshlrev_b32_e32 v41, 16, v38
	v_lshlrev_b32_e32 v50, 16, v34
	global_load_dwordx4 v[26:29], v[26:27], off
	v_permlane16_swap_b32_e32 v35, v49
	global_load_dwordx4 v[30:33], v[44:45], off
	v_permlane16_swap_b32_e32 v39, v40
	v_fmac_f32_e32 v41, v22, v50
	v_and_b32_e32 v22, 0xffff0000, v38
	v_and_b32_e32 v34, 0xffff0000, v34
	v_fmac_f32_e32 v22, v23, v34
	v_lshlrev_b32_e32 v23, 16, v39
	v_lshlrev_b32_e32 v34, 16, v35
	v_fmac_f32_e32 v23, v24, v34
	v_and_b32_e32 v24, 0xffff0000, v39
	v_and_b32_e32 v34, 0xffff0000, v35
	v_fmac_f32_e32 v24, v25, v34
	v_cvt_pk_bf16_f32 v23, v23, v24
	v_lshlrev_b32_e32 v24, 16, v0
	v_lshlrev_b32_e32 v25, 16, v48
	v_fmac_f32_e32 v24, v18, v25
	v_and_b32_e32 v0, 0xffff0000, v0
	v_and_b32_e32 v18, 0xffff0000, v48
	v_fmac_f32_e32 v0, v19, v18
	v_cvt_pk_bf16_f32 v24, v24, v0
	v_lshlrev_b32_e32 v0, 16, v40
	v_lshlrev_b32_e32 v18, 16, v49
	v_fmac_f32_e32 v0, v20, v18
	v_and_b32_e32 v18, 0xffff0000, v40
	v_and_b32_e32 v19, 0xffff0000, v49
	v_cvt_pk_bf16_f32 v22, v41, v22
	v_fmac_f32_e32 v18, v21, v19
	v_cvt_pk_bf16_f32 v25, v0, v18
	v_permlane16_swap_b32_e32 v22, v24
	v_permlane16_swap_b32_e32 v23, v25
	global_store_dwordx4 v[42:43], v[22:25], off offset:256
	v_lshl_add_u64 v[18:19], v[46:47], 0, s[40:41]
	global_load_dwordx4 v[18:21], v[18:19], off offset:256
	s_nop 0
	global_load_dwordx4 v[22:25], v[44:45], off offset:256
	v_lshl_add_u64 v[34:35], v[156:157], 0, v[36:37]
	s_mov_b32 s2, s14
	s_waitcnt vmcnt(0)
	v_mov_b32_e32 v0, v28
	v_mov_b32_e32 v28, v29
	s_nop 0
	v_permlane16_swap_b32_e32 v26, v0
	v_mov_b32_e32 v29, v32
	s_nop 1
	v_permlane16_swap_b32_e32 v30, v29
	v_mov_b32_e32 v32, v33
	v_lshlrev_b32_e32 v33, 16, v30
	v_lshlrev_b32_e32 v36, 16, v26
	v_permlane16_swap_b32_e32 v27, v28
	v_permlane16_swap_b32_e32 v31, v32
	v_fmac_f32_e32 v33, v14, v36
	v_and_b32_e32 v14, 0xffff0000, v30
	v_and_b32_e32 v26, 0xffff0000, v26
	v_fmac_f32_e32 v14, v15, v26
	v_lshlrev_b32_e32 v15, 16, v31
	v_lshlrev_b32_e32 v26, 16, v27
	v_fmac_f32_e32 v15, v16, v26
	v_and_b32_e32 v16, 0xffff0000, v31
	v_and_b32_e32 v26, 0xffff0000, v27
	v_fmac_f32_e32 v16, v17, v26
	v_cvt_pk_bf16_f32 v15, v15, v16
	v_lshlrev_b32_e32 v16, 16, v29
	v_lshlrev_b32_e32 v17, 16, v0
	v_fmac_f32_e32 v16, v10, v17
	v_and_b32_e32 v10, 0xffff0000, v29
	v_and_b32_e32 v0, 0xffff0000, v0
	v_fmac_f32_e32 v10, v11, v0
	v_cvt_pk_bf16_f32 v16, v16, v10
	v_lshlrev_b32_e32 v0, 16, v32
	v_lshlrev_b32_e32 v10, 16, v28
	v_fmac_f32_e32 v0, v12, v10
	v_and_b32_e32 v10, 0xffff0000, v32
	v_and_b32_e32 v11, 0xffff0000, v28
	v_cvt_pk_bf16_f32 v14, v33, v14
	v_fmac_f32_e32 v10, v13, v11
	v_cvt_pk_bf16_f32 v17, v0, v10
	v_mov_b32_e32 v0, v20
	v_mov_b32_e32 v13, v24
	v_permlane16_swap_b32_e32 v14, v16
	v_permlane16_swap_b32_e32 v15, v17
	v_lshl_add_u64 v[10:11], v[34:35], 0, v[150:151]
	v_permlane16_swap_b32_e32 v18, v0
	v_permlane16_swap_b32_e32 v22, v13
	global_store_dwordx4 v[10:11], v[14:17], off
	v_mov_b32_e32 v12, v21
	s_nop 1
	v_permlane16_swap_b32_e32 v19, v12
	v_lshlrev_b32_e32 v15, 16, v22
	v_lshlrev_b32_e32 v16, 16, v18
	v_mov_b32_e32 v14, v25
	v_fmac_f32_e32 v15, v6, v16
	v_and_b32_e32 v6, 0xffff0000, v22
	v_and_b32_e32 v16, 0xffff0000, v18
	v_permlane16_swap_b32_e32 v23, v14
	v_fmac_f32_e32 v6, v7, v16
	v_cvt_pk_bf16_f32 v6, v15, v6
	v_lshlrev_b32_e32 v7, 16, v23
	v_lshlrev_b32_e32 v15, 16, v19
	v_fmac_f32_e32 v7, v8, v15
	v_and_b32_e32 v8, 0xffff0000, v23
	v_and_b32_e32 v15, 0xffff0000, v19
	v_fmac_f32_e32 v8, v9, v15
	v_cvt_pk_bf16_f32 v7, v7, v8
	v_lshlrev_b32_e32 v8, 16, v13
	v_lshlrev_b32_e32 v9, 16, v0
	v_fmac_f32_e32 v8, v2, v9
	v_and_b32_e32 v2, 0xffff0000, v13
	v_and_b32_e32 v0, 0xffff0000, v0
	v_fmac_f32_e32 v2, v3, v0
	v_cvt_pk_bf16_f32 v8, v8, v2
	v_lshlrev_b32_e32 v0, 16, v14
	v_lshlrev_b32_e32 v2, 16, v12
	v_fmac_f32_e32 v0, v4, v2
	v_and_b32_e32 v2, 0xffff0000, v14
	v_and_b32_e32 v3, 0xffff0000, v12
	v_fmac_f32_e32 v2, v5, v3
	v_cvt_pk_bf16_f32 v9, v0, v2
	v_permlane16_swap_b32_e32 v6, v8
	v_permlane16_swap_b32_e32 v7, v9
	global_store_dwordx4 v[10:11], v[6:9], off offset:256
	s_cbranch_scc0 .LBB0_83
	s_waitcnt vmcnt(0)
	s_movk_i32 s2, 0x100
	v_cmp_gt_u32_e32 vcc, s2, v164
	s_and_saveexec_b64 s[4:5], vcc
	s_cbranch_execz .LBB0_94
	s_barrier

; #define LDA(dst, b, h) _Pragma("unroll") for (int m = 0; m < 4; ++m) _Pragma("unroll") for (int k = 0; k < 2; ++k) \
;     dst[m][k] = *reinterpret_cast<const bf16x8*>((char*)SA(b, h) + lds_byte(wr * 64 + m * 16 + fr, k * 32 + fq * 8))
; #define LDB(dst, b, h) _Pragma("unroll") for (int n = 0; n < 2; ++n) _Pragma("unroll") for (int k = 0; k < 2; ++k) \
;     dst[n][k] = *reinterpret_cast<const bf16x8*>((char*)SB(b, h) + lds_byte(wc * 32 + n * 16 + fr, k * 32 + fq * 8))
; #define WAIT_V(n) asm volatile("s_waitcnt vmcnt(" #n ")" ::: "memory")
; #define WAIT_L(n) asm volatile("s_waitcnt lgkmcnt(" #n ")" ::: "memory")
; #define BAR __builtin_amdgcn_s_barrier()
; #define SCHED __builtin_amdgcn_sched_barrier(0)
; template <int MODE>
; __device__ __forceinline__ void gemm_phase(int s, char* lds, const int wave) {
;     ...
;       for (int t = 0; t < nt; t += 2) {
;         const bool lastit = t + 2 >= nt;
;         const bf16* A2 = lastit ? Anext : Acur; const bf16* B2 = lastit ? Bnext : Bcur; const int k2 = lastit ? 0 : t + 2;
;         LDB(B0, 0, 0); SCHED; LDA(At, 0, 0); STAGE(SA(1, 1), Acur, HALF, t + 1);
;         WAIT_L(8); BAR; WAIT_L(0); MMA(0, 0, At, B0); BAR; SCHED;
;         LDB(B1, 0, 1); STAGE(SB(0, 0), B2, 0, k2);
;         BAR; WAIT_L(0); MMA(0, 1, At, B1); BAR;
;         LDA(At, 0, 1); STAGE(SA(0, 0), A2, 0, k2);
;         BAR; WAIT_L(0); MMA(1, 0, At, B0); BAR; SCHED;
;         STAGE(SB(0, 1), B2, HALF, k2);
;         WAIT_V(6); BAR; MMA(1, 1, At, B1); BAR;
;         LDB(B0, 1, 0); SCHED; LDA(At, 1, 0); STAGE(SA(0, 1), A2, HALF, k2);
;         WAIT_L(8); BAR; WAIT_L(0); MMA(0, 0, At, B0); BAR; SCHED;
;         LDB(B1, 1, 1); STAGE(SB(1, 0), B2, 0, k2 + 1);
;         BAR; WAIT_L(0); MMA(0, 1, At, B1); BAR;
;         LDA(At, 1, 1); STAGE(SA(1, 0), A2, 0, k2 + 1);
;         BAR; WAIT_L(0); MMA(1, 0, At, B0); BAR; SCHED;
;         STAGE(SB(1, 1), B2, HALF, k2 + 1);
;         WAIT_V(6); BAR; MMA(1, 1, At, B1); BAR;
;       }
.LBB0_191:
	ds_read_b128 v[164:167], v0
	ds_read_b128 v[168:171], v0 offset:1024
	ds_read_b128 v[172:175], v0 offset:2048
	ds_read_b128 v[176:179], v0 offset:3072
	s_add_i32 s9, s9, 2
	s_cmp_gt_u32 s9, 29
	s_cselect_b64 s[40:41], -1, 0
	s_and_b64 vcc, s[40:41], exec
	s_cselect_b32 s44, s13, s55
	s_cselect_b32 s45, s12, s54
	v_add_u32_e32 v184, 0xc000, v145
	ds_read_b128 v[180:183], v157
	ds_read_b128 v[198:201], v157 offset:1024
	ds_read_b128 v[202:205], v158
	ds_read_b128 v[206:209], v158 offset:1024
	ds_read_b128 v[210:213], v159
	ds_read_b128 v[214:217], v159 offset:1024
	ds_read_b128 v[218:221], v160
	ds_read_b128 v[222:225], v160 offset:1024
	v_readfirstlane_b32 s30, v184
	v_add_u32_e32 v184, 0xe000, v145
	s_mov_b32 m0, s30
	v_readfirstlane_b32 s30, v184
	global_load_lds_dwordx4 v[140:141], off
	s_mov_b32 m0, s30
	s_nop 0
	global_load_lds_dwordx4 v[138:139], off
	s_waitcnt lgkmcnt(8)
	s_barrier
	s_waitcnt lgkmcnt(0)
	s_waitcnt lgkmcnt(0)
	v_mfma_f32_16x16x32_bf16 v[126:129], v[164:167], v[180:183], v[126:129]
	v_mfma_f32_16x16x32_bf16 v[122:125], v[172:175], v[180:183], v[122:125]
	v_mfma_f32_16x16x32_bf16 v[110:113], v[164:167], v[202:205], v[110:113]
	v_mfma_f32_16x16x32_bf16 v[106:109], v[172:175], v[202:205], v[106:109]
	v_mfma_f32_16x16x32_bf16 v[94:97], v[164:167], v[210:213], v[94:97]
	v_mfma_f32_16x16x32_bf16 v[90:93], v[172:175], v[210:213], v[90:93]
	v_mfma_f32_16x16x32_bf16 v[78:81], v[164:167], v[218:221], v[78:81]
	v_mfma_f32_16x16x32_bf16 v[74:77], v[172:175], v[218:221], v[74:77]
	v_mfma_f32_16x16x32_bf16 v[126:129], v[168:171], v[198:201], v[126:129]
	v_mfma_f32_16x16x32_bf16 v[122:125], v[176:179], v[198:201], v[122:125]
	v_mfma_f32_16x16x32_bf16 v[110:113], v[168:171], v[206:209], v[110:113]
	v_mfma_f32_16x16x32_bf16 v[106:109], v[176:179], v[206:209], v[106:109]
	v_mfma_f32_16x16x32_bf16 v[94:97], v[168:171], v[214:217], v[94:97]
	v_mfma_f32_16x16x32_bf16 v[90:93], v[176:179], v[214:217], v[90:93]
	v_mfma_f32_16x16x32_bf16 v[78:81], v[168:171], v[222:225], v[78:81]
	v_mfma_f32_16x16x32_bf16 v[74:77], v[176:179], v[222:225], v[74:77]
	s_barrier
	s_cselect_b32 s30, 0, s11
	s_cselect_b32 s46, s15, s57
	s_cselect_b32 s47, s14, s56
	s_lshl_b64 s[40:41], s[30:31], 1
	s_add_u32 s42, s47, s40
	s_addc_u32 s43, s46, s41
	v_readfirstlane_b32 s51, v143
	v_lshl_add_u64 v[184:185], s[42:43], 0, v[130:131]
	s_mov_b32 m0, s51
	v_lshl_add_u64 v[242:243], s[42:43], 0, v[132:133]
	v_readfirstlane_b32 s42, v144
	ds_read_b128 v[226:229], v161
	ds_read_b128 v[230:233], v161 offset:1024
	ds_read_b128 v[234:237], v161 offset:2048
	ds_read_b128 v[238:241], v161 offset:3072
	global_load_lds_dwordx4 v[184:185], off
	s_mov_b32 m0, s42
	s_nop 0
	global_load_lds_dwordx4 v[242:243], off
	s_barrier
	s_waitcnt lgkmcnt(0)
	s_waitcnt lgkmcnt(0)
	v_mfma_f32_16x16x32_bf16 v[118:121], v[226:229], v[180:183], v[118:121]
	v_mfma_f32_16x16x32_bf16 v[114:117], v[234:237], v[180:183], v[114:117]
	v_mfma_f32_16x16x32_bf16 v[102:105], v[226:229], v[202:205], v[102:105]
	v_mfma_f32_16x16x32_bf16 v[98:101], v[234:237], v[202:205], v[98:101]
	v_mfma_f32_16x16x32_bf16 v[86:89], v[226:229], v[210:213], v[86:89]
	v_mfma_f32_16x16x32_bf16 v[82:85], v[234:237], v[210:213], v[82:85]
	v_mfma_f32_16x16x32_bf16 v[70:73], v[226:229], v[218:221], v[70:73]
	v_mfma_f32_16x16x32_bf16 v[66:69], v[234:237], v[218:221], v[66:69]
	v_mfma_f32_16x16x32_bf16 v[118:121], v[230:233], v[198:201], v[118:121]
	v_mfma_f32_16x16x32_bf16 v[114:117], v[238:241], v[198:201], v[114:117]
	v_mfma_f32_16x16x32_bf16 v[102:105], v[230:233], v[206:209], v[102:105]
	v_mfma_f32_16x16x32_bf16 v[98:101], v[238:241], v[206:209], v[98:101]
	v_mfma_f32_16x16x32_bf16 v[86:89], v[230:233], v[214:217], v[86:89]
	v_mfma_f32_16x16x32_bf16 v[82:85], v[238:241], v[214:217], v[82:85]
	v_mfma_f32_16x16x32_bf16 v[70:73], v[230:233], v[222:225], v[70:73]
	v_mfma_f32_16x16x32_bf16 v[66:69], v[238:241], v[222:225], v[66:69]
	s_add_u32 s42, s45, s40
	s_addc_u32 s43, s44, s41
	v_readfirstlane_b32 s44, v145
	v_lshl_add_u64 v[244:245], s[42:43], 0, v[130:131]
	s_mov_b32 m0, s44
	v_readfirstlane_b32 s44, v146
	s_barrier
	ds_read_b128 v[180:183], v157 offset:16384
	ds_read_b128 v[198:201], v157 offset:17408
	ds_read_b128 v[202:205], v158 offset:16384
	ds_read_b128 v[206:209], v158 offset:17408
	ds_read_b128 v[210:213], v159 offset:16384
	ds_read_b128 v[214:217], v159 offset:17408
	ds_read_b128 v[218:221], v160 offset:16384
	ds_read_b128 v[222:225], v160 offset:17408
	global_load_lds_dwordx4 v[244:245], off
	v_lshl_add_u64 v[246:247], s[42:43], 0, v[132:133]
	s_mov_b32 m0, s44
	s_nop 0
	global_load_lds_dwordx4 v[246:247], off
	s_barrier
	s_waitcnt lgkmcnt(0)
	s_waitcnt lgkmcnt(0)
	v_mfma_f32_16x16x32_bf16 v[62:65], v[164:167], v[180:183], v[62:65]
	v_mfma_f32_16x16x32_bf16 v[58:61], v[172:175], v[180:183], v[58:61]
	v_mfma_f32_16x16x32_bf16 v[46:49], v[164:167], v[202:205], v[46:49]
	v_mfma_f32_16x16x32_bf16 v[42:45], v[172:175], v[202:205], v[42:45]
	v_mfma_f32_16x16x32_bf16 v[30:33], v[164:167], v[210:213], v[30:33]
	v_mfma_f32_16x16x32_bf16 v[26:29], v[172:175], v[210:213], v[26:29]
	v_mfma_f32_16x16x32_bf16 v[14:17], v[164:167], v[218:221], v[14:17]
	v_mfma_f32_16x16x32_bf16 v[10:13], v[172:175], v[218:221], v[10:13]
	v_mfma_f32_16x16x32_bf16 v[62:65], v[168:171], v[198:201], v[62:65]
	v_mfma_f32_16x16x32_bf16 v[58:61], v[176:179], v[198:201], v[58:61]
	v_mfma_f32_16x16x32_bf16 v[46:49], v[168:171], v[206:209], v[46:49]
	v_mfma_f32_16x16x32_bf16 v[42:45], v[176:179], v[206:209], v[42:45]
	v_mfma_f32_16x16x32_bf16 v[30:33], v[168:171], v[214:217], v[30:33]
	v_mfma_f32_16x16x32_bf16 v[26:29], v[176:179], v[214:217], v[26:29]
	v_mfma_f32_16x16x32_bf16 v[14:17], v[168:171], v[222:225], v[14:17]
	v_mfma_f32_16x16x32_bf16 v[10:13], v[176:179], v[222:225], v[10:13]
	s_barrier
; #define LDA(dst, b, h) _Pragma("unroll") for (int m = 0; m < 4; ++m) _Pragma("unroll") for (int k = 0; k < 2; ++k) \
;     dst[m][k] = *reinterpret_cast<const bf16x8*>((char*)SA(b, h) + lds_byte(wr * 64 + m * 16 + fr, k * 32 + fq * 8))
; #define LDB(dst, b, h) _Pragma("unroll") for (int n = 0; n < 2; ++n) _Pragma("unroll") for (int k = 0; k < 2; ++k) \
;     dst[n][k] = *reinterpret_cast<const bf16x8*>((char*)SB(b, h) + lds_byte(wc * 32 + n * 16 + fr, k * 32 + fq * 8))
; #define WAIT_V(n) asm volatile("s_waitcnt vmcnt(" #n ")" ::: "memory")
; #define WAIT_L(n) asm volatile("s_waitcnt lgkmcnt(" #n ")" ::: "memory")
; #define BAR __builtin_amdgcn_s_barrier()
; #define SCHED __builtin_amdgcn_sched_barrier(0)
; template <int MODE>
; __device__ __forceinline__ void gemm_phase(int s, char* lds, const int wave) {
;     ...
;       for (int t = 0; t < nt; t += 2) {
;         const bool lastit = t + 2 >= nt;
;         const bf16* A2 = lastit ? Anext : Acur; const bf16* B2 = lastit ? Bnext : Bcur; const int k2 = lastit ? 0 : t + 2;
;         LDB(B0, 0, 0); SCHED; LDA(At, 0, 0); STAGE(SA(1, 1), Acur, HALF, t + 1);
;         WAIT_L(8); BAR; WAIT_L(0); MMA(0, 0, At, B0); BAR; SCHED;
;         LDB(B1, 0, 1); STAGE(SB(0, 0), B2, 0, k2);
;         BAR; WAIT_L(0); MMA(0, 1, At, B1); BAR;
;         LDA(At, 0, 1); STAGE(SA(0, 0), A2, 0, k2);
;         BAR; WAIT_L(0); MMA(1, 0, At, B0); BAR; SCHED;
;         STAGE(SB(0, 1), B2, HALF, k2);
;         WAIT_V(6); BAR; MMA(1, 1, At, B1); BAR;
;         LDB(B0, 1, 0); SCHED; LDA(At, 1, 0); STAGE(SA(0, 1), A2, HALF, k2);
;         WAIT_L(8); BAR; WAIT_L(0); MMA(0, 0, At, B0); BAR; SCHED;
;         LDB(B1, 1, 1); STAGE(SB(1, 0), B2, 0, k2 + 1);
;         BAR; WAIT_L(0); MMA(0, 1, At, B1); BAR;
;         LDA(At, 1, 1); STAGE(SA(1, 0), A2, 0, k2 + 1);
;         BAR; WAIT_L(0); MMA(1, 0, At, B0); BAR; SCHED;
;         STAGE(SB(1, 1), B2, HALF, k2 + 1);
;         WAIT_V(6); BAR; MMA(1, 1, At, B1); BAR;
;       }
	s_add_u32 s58, s47, 0x80000
	s_addc_u32 s59, s46, 0
	s_add_u32 s40, s58, s40
	s_addc_u32 s41, s59, s41
	v_readfirstlane_b32 s44, v147
	v_lshl_add_u64 v[164:165], s[40:41], 0, v[130:131]
	s_mov_b32 m0, s44
	s_nop 0
	global_load_lds_dwordx4 v[164:165], off
	v_lshl_add_u64 v[164:165], s[40:41], 0, v[132:133]
	v_readfirstlane_b32 s40, v148
	s_mov_b32 m0, s40
	s_nop 0
	global_load_lds_dwordx4 v[164:165], off
	s_waitcnt vmcnt(6)
	s_barrier
	v_mfma_f32_16x16x32_bf16 v[54:57], v[226:229], v[180:183], v[54:57]
	v_mfma_f32_16x16x32_bf16 v[50:53], v[234:237], v[180:183], v[50:53]
	v_mfma_f32_16x16x32_bf16 v[38:41], v[226:229], v[202:205], v[38:41]
	v_mfma_f32_16x16x32_bf16 v[34:37], v[234:237], v[202:205], v[34:37]
	v_mfma_f32_16x16x32_bf16 v[22:25], v[226:229], v[210:213], v[22:25]
	v_mfma_f32_16x16x32_bf16 v[18:21], v[234:237], v[210:213], v[18:21]
	v_mfma_f32_16x16x32_bf16 v[6:9], v[226:229], v[218:221], v[6:9]
	v_mfma_f32_16x16x32_bf16 v[2:5], v[234:237], v[218:221], v[2:5]
	v_mfma_f32_16x16x32_bf16 v[54:57], v[230:233], v[198:201], v[54:57]
	v_mfma_f32_16x16x32_bf16 v[50:53], v[238:241], v[198:201], v[50:53]
	v_mfma_f32_16x16x32_bf16 v[38:41], v[230:233], v[206:209], v[38:41]
	v_mfma_f32_16x16x32_bf16 v[34:37], v[238:241], v[206:209], v[34:37]
	v_mfma_f32_16x16x32_bf16 v[22:25], v[230:233], v[214:217], v[22:25]
	v_mfma_f32_16x16x32_bf16 v[18:21], v[238:241], v[214:217], v[18:21]
	v_mfma_f32_16x16x32_bf16 v[6:9], v[230:233], v[222:225], v[6:9]
	v_mfma_f32_16x16x32_bf16 v[2:5], v[238:241], v[222:225], v[2:5]
	s_barrier
	ds_read_b128 v[164:167], v162
	ds_read_b128 v[168:171], v162 offset:1024
	ds_read_b128 v[172:175], v162 offset:2048
	ds_read_b128 v[176:179], v162 offset:3072
	s_add_u32 s40, s42, 0x80000
	s_addc_u32 s41, s43, 0
	v_readfirstlane_b32 s42, v149
	v_lshl_add_u64 v[226:227], s[40:41], 0, v[130:131]
	s_mov_b32 m0, s42
	ds_read_b128 v[180:183], v157 offset:32768
	ds_read_b128 v[198:201], v157 offset:33792
	ds_read_b128 v[202:205], v158 offset:32768
	ds_read_b128 v[206:209], v158 offset:33792
	ds_read_b128 v[210:213], v159 offset:32768
	ds_read_b128 v[214:217], v159 offset:33792
	ds_read_b128 v[218:221], v160 offset:32768
	ds_read_b128 v[222:225], v160 offset:33792
	global_load_lds_dwordx4 v[226:227], off
	v_lshl_add_u64 v[226:227], s[40:41], 0, v[132:133]
	v_readfirstlane_b32 s40, v150
	s_mov_b32 m0, s40
	s_nop 0
	global_load_lds_dwordx4 v[226:227], off
	s_waitcnt lgkmcnt(8)
	s_barrier
	s_waitcnt lgkmcnt(0)
	s_waitcnt lgkmcnt(0)
	v_mfma_f32_16x16x32_bf16 v[126:129], v[164:167], v[180:183], v[126:129]
	v_mfma_f32_16x16x32_bf16 v[122:125], v[172:175], v[180:183], v[122:125]
	v_mfma_f32_16x16x32_bf16 v[110:113], v[164:167], v[202:205], v[110:113]
	v_mfma_f32_16x16x32_bf16 v[106:109], v[172:175], v[202:205], v[106:109]
	v_mfma_f32_16x16x32_bf16 v[94:97], v[164:167], v[210:213], v[94:97]
	v_mfma_f32_16x16x32_bf16 v[90:93], v[172:175], v[210:213], v[90:93]
	v_mfma_f32_16x16x32_bf16 v[78:81], v[164:167], v[218:221], v[78:81]
	v_mfma_f32_16x16x32_bf16 v[74:77], v[172:175], v[218:221], v[74:77]
	v_mfma_f32_16x16x32_bf16 v[126:129], v[168:171], v[198:201], v[126:129]
	v_mfma_f32_16x16x32_bf16 v[122:125], v[176:179], v[198:201], v[122:125]
	v_mfma_f32_16x16x32_bf16 v[110:113], v[168:171], v[206:209], v[110:113]
	v_mfma_f32_16x16x32_bf16 v[106:109], v[176:179], v[206:209], v[106:109]
	v_mfma_f32_16x16x32_bf16 v[94:97], v[168:171], v[214:217], v[94:97]
	v_mfma_f32_16x16x32_bf16 v[90:93], v[176:179], v[214:217], v[90:93]
	v_mfma_f32_16x16x32_bf16 v[78:81], v[168:171], v[222:225], v[78:81]
	v_mfma_f32_16x16x32_bf16 v[74:77], v[176:179], v[222:225], v[74:77]
	s_barrier
	v_readfirstlane_b32 s40, v151
	v_lshl_add_u64 v[184:185], v[184:185], 0, s[18:19]
	s_mov_b32 m0, s40
	v_readfirstlane_b32 s40, v152
	ds_read_b128 v[226:229], v163
	ds_read_b128 v[230:233], v163 offset:1024
	ds_read_b128 v[234:237], v163 offset:2048
	ds_read_b128 v[238:241], v163 offset:3072
	global_load_lds_dwordx4 v[184:185], off
	v_lshl_add_u64 v[184:185], v[242:243], 0, s[18:19]
	s_mov_b32 m0, s40
	s_or_b32 s30, s30, 64
	global_load_lds_dwordx4 v[184:185], off
	s_barrier
	s_waitcnt lgkmcnt(0)
	s_waitcnt lgkmcnt(0)
	v_mfma_f32_16x16x32_bf16 v[118:121], v[226:229], v[180:183], v[118:121]
	v_mfma_f32_16x16x32_bf16 v[114:117], v[234:237], v[180:183], v[114:117]
	v_mfma_f32_16x16x32_bf16 v[102:105], v[226:229], v[202:205], v[102:105]
	v_mfma_f32_16x16x32_bf16 v[98:101], v[234:237], v[202:205], v[98:101]
	v_mfma_f32_16x16x32_bf16 v[86:89], v[226:229], v[210:213], v[86:89]
	v_mfma_f32_16x16x32_bf16 v[82:85], v[234:237], v[210:213], v[82:85]
	v_mfma_f32_16x16x32_bf16 v[70:73], v[226:229], v[218:221], v[70:73]
	v_mfma_f32_16x16x32_bf16 v[66:69], v[234:237], v[218:221], v[66:69]
	v_mfma_f32_16x16x32_bf16 v[118:121], v[230:233], v[198:201], v[118:121]
	v_mfma_f32_16x16x32_bf16 v[114:117], v[238:241], v[198:201], v[114:117]
	v_mfma_f32_16x16x32_bf16 v[102:105], v[230:233], v[206:209], v[102:105]
	v_mfma_f32_16x16x32_bf16 v[98:101], v[238:241], v[206:209], v[98:101]
	v_mfma_f32_16x16x32_bf16 v[86:89], v[230:233], v[214:217], v[86:89]
	v_mfma_f32_16x16x32_bf16 v[82:85], v[238:241], v[214:217], v[82:85]
	v_mfma_f32_16x16x32_bf16 v[70:73], v[230:233], v[222:225], v[70:73]
	v_mfma_f32_16x16x32_bf16 v[66:69], v[238:241], v[222:225], v[66:69]
	v_readfirstlane_b32 s40, v153
	v_lshl_add_u64 v[184:185], v[244:245], 0, s[18:19]
	s_mov_b32 m0, s40
	v_readfirstlane_b32 s40, v154
	s_barrier
; #define WAIT_V(n) asm volatile("s_waitcnt vmcnt(" #n ")" ::: "memory")
; #define WAIT_L(n) asm volatile("s_waitcnt lgkmcnt(" #n ")" ::: "memory")
; template <int MODE>
; __device__ __forceinline__ void gemm_epilogue(char* ws, const float* __restrict__ xseq, float* __restrict__ oseq, const int pm, const int pn,
;                                               f32x4 (&acc)[2][2][4][2], const int wave) {
;     ...
;     } else {
; #pragma unroll
;       for (int n = 0; n < 2; ++n)
; #pragma unroll
;       for (int bj = 0; bj < 2; ++bj) {
;         f32x4 v = acc[ai][bj][m][n];
;         const int col = bcol + bj * HALF + wc * 32 + n * 16 + fq * 4;
;         if (MODE == G_WO) {
;           const f32x4 xv = *(const f32x4*)(xseq + (long)row * DM + col);
;           v[0] += xv[0]; v[1] += xv[1]; v[2] += xv[2]; v[3] += xv[3];
;           *(f32x4*)(oseq + (long)row * DM + col) = v;
;         } else {
;           float* op = oseq + (long)row * DM + col;
;           const f32x4 xv = *(const f32x4*)op;
;           v[0] += xv[0]; v[1] += xv[1]; v[2] += xv[2]; v[3] += xv[3];
;           *(f32x4*)op = v;
;         }
;       }
; template <int MODE>
; __device__ __forceinline__ void gemm_phase(int s, char* lds, const int wave) {
;     ...
;       for (int t = 0; t < nt; t += 2) {
;         const bool lastit = t + 2 >= nt;
;         const bf16* A2 = lastit ? Anext : Acur; const bf16* B2 = lastit ? Bnext : Bcur; const int k2 = lastit ? 0 : t + 2;
;         LDB(B0, 0, 0); SCHED; LDA(At, 0, 0); STAGE(SA(1, 1), Acur, HALF, t + 1);
;         WAIT_L(8); BAR; WAIT_L(0); MMA(0, 0, At, B0); BAR; SCHED;
;         LDB(B1, 0, 1); STAGE(SB(0, 0), B2, 0, k2);
;         BAR; WAIT_L(0); MMA(0, 1, At, B1); BAR;
;         LDA(At, 0, 1); STAGE(SA(0, 0), A2, 0, k2);
;         BAR; WAIT_L(0); MMA(1, 0, At, B0); BAR; SCHED;
;         STAGE(SB(0, 1), B2, HALF, k2);
;         WAIT_V(6); BAR; MMA(1, 1, At, B1); BAR;
;         LDB(B0, 1, 0); SCHED; LDA(At, 1, 0); STAGE(SA(0, 1), A2, HALF, k2);
;         WAIT_L(8); BAR; WAIT_L(0); MMA(0, 0, At, B0); BAR; SCHED;
;         LDB(B1, 1, 1); STAGE(SB(1, 0), B2, 0, k2 + 1);
;         BAR; WAIT_L(0); MMA(0, 1, At, B1); BAR;
;         LDA(At, 1, 1); STAGE(SA(1, 0), A2, 0, k2 + 1);
;         BAR; WAIT_L(0); MMA(1, 0, At, B0); BAR; SCHED;
;         STAGE(SB(1, 1), B2, HALF, k2 + 1);
;         WAIT_V(6); BAR; MMA(1, 1, At, B1); BAR;
;       }
	ds_read_b128 v[180:183], v157 offset:49152
	ds_read_b128 v[198:201], v157 offset:50176
	ds_read_b128 v[202:205], v158 offset:49152
	ds_read_b128 v[206:209], v158 offset:50176
	ds_read_b128 v[210:213], v159 offset:49152
	ds_read_b128 v[214:217], v159 offset:50176
	ds_read_b128 v[218:221], v160 offset:49152
	ds_read_b128 v[222:225], v160 offset:50176
	global_load_lds_dwordx4 v[184:185], off
	v_lshl_add_u64 v[184:185], v[246:247], 0, s[18:19]
	s_mov_b32 m0, s40
	s_nop 0
	global_load_lds_dwordx4 v[184:185], off
	s_barrier
	s_waitcnt lgkmcnt(0)
	s_waitcnt lgkmcnt(0)
	v_mfma_f32_16x16x32_bf16 v[62:65], v[164:167], v[180:183], v[62:65]
	v_mfma_f32_16x16x32_bf16 v[58:61], v[172:175], v[180:183], v[58:61]
	v_mfma_f32_16x16x32_bf16 v[46:49], v[164:167], v[202:205], v[46:49]
	v_mfma_f32_16x16x32_bf16 v[42:45], v[172:175], v[202:205], v[42:45]
	v_mfma_f32_16x16x32_bf16 v[30:33], v[164:167], v[210:213], v[30:33]
	v_mfma_f32_16x16x32_bf16 v[26:29], v[172:175], v[210:213], v[26:29]
	v_mfma_f32_16x16x32_bf16 v[14:17], v[164:167], v[218:221], v[14:17]
	v_mfma_f32_16x16x32_bf16 v[10:13], v[172:175], v[218:221], v[10:13]
	v_mfma_f32_16x16x32_bf16 v[62:65], v[168:171], v[198:201], v[62:65]
	v_mfma_f32_16x16x32_bf16 v[58:61], v[176:179], v[198:201], v[58:61]
	v_mfma_f32_16x16x32_bf16 v[46:49], v[168:171], v[206:209], v[46:49]
	v_mfma_f32_16x16x32_bf16 v[42:45], v[176:179], v[206:209], v[42:45]
	v_mfma_f32_16x16x32_bf16 v[30:33], v[168:171], v[214:217], v[30:33]
	v_mfma_f32_16x16x32_bf16 v[26:29], v[176:179], v[214:217], v[26:29]
	v_mfma_f32_16x16x32_bf16 v[14:17], v[168:171], v[222:225], v[14:17]
	v_mfma_f32_16x16x32_bf16 v[10:13], v[176:179], v[222:225], v[10:13]
	s_barrier
	v_lshl_add_u64 v[164:165], s[58:59], 0, v[130:131]
	s_lshl_b64 s[40:41], s[30:31], 1
	v_readfirstlane_b32 s30, v155
	v_lshl_add_u64 v[164:165], v[164:165], 0, s[40:41]
	s_mov_b32 m0, s30
	v_readfirstlane_b32 s30, v156
	global_load_lds_dwordx4 v[164:165], off
	v_lshl_add_u64 v[164:165], s[58:59], 0, v[132:133]
	v_lshl_add_u64 v[164:165], v[164:165], 0, s[40:41]
	s_mov_b32 m0, s30
	s_nop 0
	global_load_lds_dwordx4 v[164:165], off
	s_waitcnt vmcnt(6)
	s_barrier
	v_mfma_f32_16x16x32_bf16 v[54:57], v[226:229], v[180:183], v[54:57]
	v_mfma_f32_16x16x32_bf16 v[50:53], v[234:237], v[180:183], v[50:53]
	v_mfma_f32_16x16x32_bf16 v[38:41], v[226:229], v[202:205], v[38:41]
	v_mfma_f32_16x16x32_bf16 v[34:37], v[234:237], v[202:205], v[34:37]
	v_mfma_f32_16x16x32_bf16 v[22:25], v[226:229], v[210:213], v[22:25]
	v_mfma_f32_16x16x32_bf16 v[18:21], v[234:237], v[210:213], v[18:21]
	v_mfma_f32_16x16x32_bf16 v[6:9], v[226:229], v[218:221], v[6:9]
	v_mfma_f32_16x16x32_bf16 v[2:5], v[234:237], v[218:221], v[2:5]
	v_mfma_f32_16x16x32_bf16 v[54:57], v[230:233], v[198:201], v[54:57]
	v_mfma_f32_16x16x32_bf16 v[50:53], v[238:241], v[198:201], v[50:53]
	v_mfma_f32_16x16x32_bf16 v[38:41], v[230:233], v[206:209], v[38:41]
	v_mfma_f32_16x16x32_bf16 v[34:37], v[238:241], v[206:209], v[34:37]
	v_mfma_f32_16x16x32_bf16 v[22:25], v[230:233], v[214:217], v[22:25]
	v_mfma_f32_16x16x32_bf16 v[18:21], v[238:241], v[214:217], v[18:21]
	v_mfma_f32_16x16x32_bf16 v[6:9], v[230:233], v[222:225], v[6:9]
	v_mfma_f32_16x16x32_bf16 v[2:5], v[238:241], v[222:225], v[2:5]
	v_lshl_add_u64 v[138:139], v[138:139], 0, s[38:39]
	v_lshl_add_u64 v[140:141], v[140:141], 0, s[38:39]
	s_addk_i32 s11, 0x80
	s_barrier
	s_cbranch_vccz .LBB0_191
	v_mov_b32_e32 v139, v187
	s_lshl_b32 s9, s52, 8
	v_ashrrev_i32_e32 v138, 2, v139
	v_and_b32_e32 v138, 0xffffffc0, v138
	v_and_or_b32 v140, v139, 15, s9
	v_add_u32_e32 v138, v140, v138
	v_lshrrev_b32_e32 v140, 1, v139
	v_lshrrev_b32_e32 v139, 2, v139
	s_lshl_b32 s2, s2, 8
	v_and_b32_e32 v140, 0x60, v140
	v_and_b32_e32 v139, 12, v139
	v_or3_b32 v140, v140, s2, v139
	v_ashrrev_i32_e32 v139, 31, v138
	v_ashrrev_i32_e32 v141, 31, v140
	v_lshlrev_b64 v[140:141], 2, v[140:141]
	s_cmpk_gt_i32 s60, 0x1ff
	s_mov_b64 s[56:57], s[14:15]
	s_mov_b64 s[54:55], s[12:13]
	s_mov_b32 s2, s10
	s_mov_b32 s52, s8
	v_lshlrev_b64 v[178:179], 13, v[138:139]
	v_lshl_add_u64 v[164:165], s[4:5], 0, v[178:179]
	v_lshl_add_u64 v[164:165], v[164:165], 0, v[140:141]
	v_lshl_add_u64 v[166:167], s[6:7], 0, v[178:179]
	v_lshl_add_u64 v[166:167], v[166:167], 0, v[140:141]
	global_load_dwordx4 v[198:201], v[164:165], off
	global_load_dwordx4 v[202:205], v[164:165], off offset:512
	global_load_dwordx4 v[206:209], v[164:165], off offset:64
	global_load_dwordx4 v[210:213], v[164:165], off offset:576
	v_or_b32_e32 v176, 16, v138
	v_ashrrev_i32_e32 v177, 31, v176
	v_lshlrev_b64 v[178:179], 13, v[176:177]
	v_lshl_add_u64 v[168:169], s[4:5], 0, v[178:179]
	v_lshl_add_u64 v[168:169], v[168:169], 0, v[140:141]
	v_lshl_add_u64 v[170:171], s[6:7], 0, v[178:179]
	v_lshl_add_u64 v[170:171], v[170:171], 0, v[140:141]
	global_load_dwordx4 v[214:217], v[168:169], off
	global_load_dwordx4 v[218:221], v[168:169], off offset:512
	global_load_dwordx4 v[222:225], v[168:169], off offset:64
	global_load_dwordx4 v[226:229], v[168:169], off offset:576
	v_or_b32_e32 v176, 32, v138
	v_ashrrev_i32_e32 v177, 31, v176
	v_lshlrev_b64 v[178:179], 13, v[176:177]
	v_lshl_add_u64 v[172:173], s[4:5], 0, v[178:179]
	v_lshl_add_u64 v[172:173], v[172:173], 0, v[140:141]
	v_lshl_add_u64 v[174:175], s[6:7], 0, v[178:179]
	v_lshl_add_u64 v[174:175], v[174:175], 0, v[140:141]
	global_load_dwordx4 v[230:233], v[172:173], off
	global_load_dwordx4 v[234:237], v[172:173], off offset:512
	global_load_dwordx4 v[238:241], v[172:173], off offset:64
	global_load_dwordx4 v[242:245], v[172:173], off offset:576
	s_waitcnt vmcnt(11)
	v_pk_add_f32 v[200:201], v[128:129], v[200:201]
	v_pk_add_f32 v[198:199], v[126:127], v[198:199]
	s_waitcnt vmcnt(10)
; template <int MODE>
; __device__ __forceinline__ void gemm_epilogue(char* ws, const float* __restrict__ xseq, float* __restrict__ oseq, const int pm, const int pn,
;                                               f32x4 (&acc)[2][2][4][2], const int wave) {
;     ...
;     } else {
; #pragma unroll
;       for (int n = 0; n < 2; ++n)
; #pragma unroll
;       for (int bj = 0; bj < 2; ++bj) {
;         f32x4 v = acc[ai][bj][m][n];
;         const int col = bcol + bj * HALF + wc * 32 + n * 16 + fq * 4;
;         if (MODE == G_WO) {
;           const f32x4 xv = *(const f32x4*)(xseq + (long)row * DM + col);
;           v[0] += xv[0]; v[1] += xv[1]; v[2] += xv[2]; v[3] += xv[3];
;           *(f32x4*)(oseq + (long)row * DM + col) = v;
;         } else {
;           float* op = oseq + (long)row * DM + col;
;           const f32x4 xv = *(const f32x4*)op;
;           v[0] += xv[0]; v[1] += xv[1]; v[2] += xv[2]; v[3] += xv[3];
;           *(f32x4*)op = v;
;         }
;       }
	v_pk_add_f32 v[204:205], v[120:121], v[204:205]
	v_pk_add_f32 v[202:203], v[118:119], v[202:203]
	s_waitcnt vmcnt(9)
	v_pk_add_f32 v[208:209], v[124:125], v[208:209]
	v_pk_add_f32 v[206:207], v[122:123], v[206:207]
	s_waitcnt vmcnt(8)
	v_pk_add_f32 v[212:213], v[116:117], v[212:213]
	v_pk_add_f32 v[210:211], v[114:115], v[210:211]
	global_store_dwordx4 v[166:167], v[198:201], off
	global_store_dwordx4 v[166:167], v[202:205], off offset:512
	global_store_dwordx4 v[166:167], v[206:209], off offset:64
	global_store_dwordx4 v[166:167], v[210:213], off offset:576
	v_or_b32_e32 v176, 48, v138
	v_ashrrev_i32_e32 v177, 31, v176
	v_lshlrev_b64 v[178:179], 13, v[176:177]
	v_lshl_add_u64 v[164:165], s[4:5], 0, v[178:179]
	v_lshl_add_u64 v[164:165], v[164:165], 0, v[140:141]
	v_lshl_add_u64 v[166:167], s[6:7], 0, v[178:179]
	v_lshl_add_u64 v[166:167], v[166:167], 0, v[140:141]
	global_load_dwordx4 v[198:201], v[164:165], off
	global_load_dwordx4 v[202:205], v[164:165], off offset:512
	global_load_dwordx4 v[206:209], v[164:165], off offset:64
	global_load_dwordx4 v[210:213], v[164:165], off offset:576
	s_waitcnt vmcnt(15)
	v_pk_add_f32 v[216:217], v[112:113], v[216:217]
	v_pk_add_f32 v[214:215], v[110:111], v[214:215]
	s_waitcnt vmcnt(14)
	v_pk_add_f32 v[220:221], v[104:105], v[220:221]
	v_pk_add_f32 v[218:219], v[102:103], v[218:219]
	s_waitcnt vmcnt(13)
	v_pk_add_f32 v[224:225], v[108:109], v[224:225]
	v_pk_add_f32 v[222:223], v[106:107], v[222:223]
	s_waitcnt vmcnt(12)
	v_pk_add_f32 v[228:229], v[100:101], v[228:229]
	v_pk_add_f32 v[226:227], v[98:99], v[226:227]
	global_store_dwordx4 v[170:171], v[214:217], off
	global_store_dwordx4 v[170:171], v[218:221], off offset:512
	global_store_dwordx4 v[170:171], v[222:225], off offset:64
	global_store_dwordx4 v[170:171], v[226:229], off offset:576
	v_add_u32_e32 v176, 0x80, v138
	v_ashrrev_i32_e32 v177, 31, v176
	v_lshlrev_b64 v[178:179], 13, v[176:177]
	v_lshl_add_u64 v[168:169], s[4:5], 0, v[178:179]
	v_lshl_add_u64 v[168:169], v[168:169], 0, v[140:141]
	v_lshl_add_u64 v[170:171], s[6:7], 0, v[178:179]
	v_lshl_add_u64 v[170:171], v[170:171], 0, v[140:141]
	global_load_dwordx4 v[214:217], v[168:169], off
	global_load_dwordx4 v[218:221], v[168:169], off offset:512
	global_load_dwordx4 v[222:225], v[168:169], off offset:64
	global_load_dwordx4 v[226:229], v[168:169], off offset:576
	s_waitcnt vmcnt(19)
	v_pk_add_f32 v[232:233], v[96:97], v[232:233]
	v_pk_add_f32 v[230:231], v[94:95], v[230:231]
	s_waitcnt vmcnt(18)
	v_pk_add_f32 v[236:237], v[88:89], v[236:237]
	v_pk_add_f32 v[234:235], v[86:87], v[234:235]
	s_waitcnt vmcnt(17)
	v_pk_add_f32 v[240:241], v[92:93], v[240:241]
	v_pk_add_f32 v[238:239], v[90:91], v[238:239]
	s_waitcnt vmcnt(16)
	v_pk_add_f32 v[244:245], v[84:85], v[244:245]
	v_pk_add_f32 v[242:243], v[82:83], v[242:243]
	global_store_dwordx4 v[174:175], v[230:233], off
	global_store_dwordx4 v[174:175], v[234:237], off offset:512
	global_store_dwordx4 v[174:175], v[238:241], off offset:64
	global_store_dwordx4 v[174:175], v[242:245], off offset:576
	v_add_u32_e32 v176, 0x90, v138
	v_ashrrev_i32_e32 v177, 31, v176
	v_lshlrev_b64 v[178:179], 13, v[176:177]
	v_lshl_add_u64 v[172:173], s[4:5], 0, v[178:179]
	v_lshl_add_u64 v[172:173], v[172:173], 0, v[140:141]
	v_lshl_add_u64 v[174:175], s[6:7], 0, v[178:179]
	v_lshl_add_u64 v[174:175], v[174:175], 0, v[140:141]
	global_load_dwordx4 v[230:233], v[172:173], off
	global_load_dwordx4 v[234:237], v[172:173], off offset:512
	global_load_dwordx4 v[238:241], v[172:173], off offset:64
	global_load_dwordx4 v[242:245], v[172:173], off offset:576
	s_waitcnt vmcnt(19)
	v_pk_add_f32 v[200:201], v[80:81], v[200:201]
	v_pk_add_f32 v[198:199], v[78:79], v[198:199]
	s_waitcnt vmcnt(18)
	v_pk_add_f32 v[204:205], v[72:73], v[204:205]
	v_pk_add_f32 v[202:203], v[70:71], v[202:203]
	s_waitcnt vmcnt(17)
	v_pk_add_f32 v[208:209], v[76:77], v[208:209]
	v_pk_add_f32 v[206:207], v[74:75], v[206:207]
	s_waitcnt vmcnt(16)
; template <int MODE>
; __device__ __forceinline__ void gemm_epilogue(char* ws, const float* __restrict__ xseq, float* __restrict__ oseq, const int pm, const int pn,
;                                               f32x4 (&acc)[2][2][4][2], const int wave) {
;     ...
;     } else {
; #pragma unroll
;       for (int n = 0; n < 2; ++n)
; #pragma unroll
;       for (int bj = 0; bj < 2; ++bj) {
;         f32x4 v = acc[ai][bj][m][n];
;         const int col = bcol + bj * HALF + wc * 32 + n * 16 + fq * 4;
;         if (MODE == G_WO) {
;           const f32x4 xv = *(const f32x4*)(xseq + (long)row * DM + col);
;           v[0] += xv[0]; v[1] += xv[1]; v[2] += xv[2]; v[3] += xv[3];
;           *(f32x4*)(oseq + (long)row * DM + col) = v;
;         } else {
;           float* op = oseq + (long)row * DM + col;
;           const f32x4 xv = *(const f32x4*)op;
;           v[0] += xv[0]; v[1] += xv[1]; v[2] += xv[2]; v[3] += xv[3];
;           *(f32x4*)op = v;
;         }
;       }
	v_pk_add_f32 v[212:213], v[68:69], v[212:213]
	v_pk_add_f32 v[210:211], v[66:67], v[210:211]
	global_store_dwordx4 v[166:167], v[198:201], off
	global_store_dwordx4 v[166:167], v[202:205], off offset:512
	global_store_dwordx4 v[166:167], v[206:209], off offset:64
	global_store_dwordx4 v[166:167], v[210:213], off offset:576
	v_add_u32_e32 v176, 0xa0, v138
	v_ashrrev_i32_e32 v177, 31, v176
	v_lshlrev_b64 v[178:179], 13, v[176:177]
	v_lshl_add_u64 v[164:165], s[4:5], 0, v[178:179]
	v_lshl_add_u64 v[164:165], v[164:165], 0, v[140:141]
	v_lshl_add_u64 v[166:167], s[6:7], 0, v[178:179]
	v_lshl_add_u64 v[166:167], v[166:167], 0, v[140:141]
	global_load_dwordx4 v[198:201], v[164:165], off
	global_load_dwordx4 v[202:205], v[164:165], off offset:512
	global_load_dwordx4 v[206:209], v[164:165], off offset:64
	global_load_dwordx4 v[210:213], v[164:165], off offset:576
	s_waitcnt vmcnt(19)
	v_pk_add_f32 v[216:217], v[64:65], v[216:217]
	v_pk_add_f32 v[214:215], v[62:63], v[214:215]
	s_waitcnt vmcnt(18)
	v_pk_add_f32 v[220:221], v[56:57], v[220:221]
	v_pk_add_f32 v[218:219], v[54:55], v[218:219]
	s_waitcnt vmcnt(17)
	v_pk_add_f32 v[224:225], v[60:61], v[224:225]
	v_pk_add_f32 v[222:223], v[58:59], v[222:223]
	s_waitcnt vmcnt(16)
	v_pk_add_f32 v[228:229], v[52:53], v[228:229]
	v_pk_add_f32 v[226:227], v[50:51], v[226:227]
	global_store_dwordx4 v[170:171], v[214:217], off
	global_store_dwordx4 v[170:171], v[218:221], off offset:512
	global_store_dwordx4 v[170:171], v[222:225], off offset:64
	global_store_dwordx4 v[170:171], v[226:229], off offset:576
	v_add_u32_e32 v176, 0xb0, v138
	v_ashrrev_i32_e32 v177, 31, v176
	v_lshlrev_b64 v[178:179], 13, v[176:177]
	v_lshl_add_u64 v[168:169], s[4:5], 0, v[178:179]
	v_lshl_add_u64 v[168:169], v[168:169], 0, v[140:141]
	v_lshl_add_u64 v[170:171], s[6:7], 0, v[178:179]
	v_lshl_add_u64 v[170:171], v[170:171], 0, v[140:141]
	global_load_dwordx4 v[214:217], v[168:169], off
	global_load_dwordx4 v[218:221], v[168:169], off offset:512
	global_load_dwordx4 v[222:225], v[168:169], off offset:64
	global_load_dwordx4 v[226:229], v[168:169], off offset:576
	s_waitcnt vmcnt(19)
	v_pk_add_f32 v[232:233], v[48:49], v[232:233]
	v_pk_add_f32 v[230:231], v[46:47], v[230:231]
	s_waitcnt vmcnt(18)
	v_pk_add_f32 v[236:237], v[40:41], v[236:237]
	v_pk_add_f32 v[234:235], v[38:39], v[234:235]
	s_waitcnt vmcnt(17)
	v_pk_add_f32 v[240:241], v[44:45], v[240:241]
	v_pk_add_f32 v[238:239], v[42:43], v[238:239]
	s_waitcnt vmcnt(16)
	v_pk_add_f32 v[244:245], v[36:37], v[244:245]
	v_pk_add_f32 v[242:243], v[34:35], v[242:243]
	global_store_dwordx4 v[174:175], v[230:233], off
	global_store_dwordx4 v[174:175], v[234:237], off offset:512
	global_store_dwordx4 v[174:175], v[238:241], off offset:64
	global_store_dwordx4 v[174:175], v[242:245], off offset:576
	s_waitcnt vmcnt(15)
	v_pk_add_f32 v[200:201], v[32:33], v[200:201]
	v_pk_add_f32 v[198:199], v[30:31], v[198:199]
	s_waitcnt vmcnt(14)
	v_pk_add_f32 v[204:205], v[24:25], v[204:205]
	v_pk_add_f32 v[202:203], v[22:23], v[202:203]
	s_waitcnt vmcnt(13)
	v_pk_add_f32 v[208:209], v[28:29], v[208:209]
	v_pk_add_f32 v[206:207], v[26:27], v[206:207]
	s_waitcnt vmcnt(12)
	v_pk_add_f32 v[212:213], v[20:21], v[212:213]
	v_pk_add_f32 v[210:211], v[18:19], v[210:211]
	global_store_dwordx4 v[166:167], v[198:201], off
	global_store_dwordx4 v[166:167], v[202:205], off offset:512
	global_store_dwordx4 v[166:167], v[206:209], off offset:64
	global_store_dwordx4 v[166:167], v[210:213], off offset:576
	s_waitcnt vmcnt(11)
	v_pk_add_f32 v[216:217], v[16:17], v[216:217]
	v_pk_add_f32 v[214:215], v[14:15], v[214:215]
	s_waitcnt vmcnt(10)
	v_pk_add_f32 v[220:221], v[8:9], v[220:221]
	v_pk_add_f32 v[218:219], v[6:7], v[218:219]
	s_waitcnt vmcnt(9)
	v_pk_add_f32 v[224:225], v[12:13], v[224:225]
	v_pk_add_f32 v[222:223], v[10:11], v[222:223]
	s_waitcnt vmcnt(8)
	v_pk_add_f32 v[228:229], v[4:5], v[228:229]
	v_pk_add_f32 v[226:227], v[2:3], v[226:227]
	global_store_dwordx4 v[170:171], v[214:217], off
	global_store_dwordx4 v[170:171], v[218:221], off offset:512
	global_store_dwordx4 v[170:171], v[222:225], off offset:64
	global_store_dwordx4 v[170:171], v[226:229], off offset:576
	s_cbranch_scc0 .LBB0_184
	s_waitcnt vmcnt(0)
	s_movk_i32 s2, 0x100
	v_cmp_gt_u32_e32 vcc, s2, v142
	s_and_saveexec_b64 s[4:5], vcc
	s_cbranch_execz .LBB0_195
	s_barrier

; #define LDA(dst, b, h) _Pragma("unroll") for (int m = 0; m < 4; ++m) _Pragma("unroll") for (int k = 0; k < 2; ++k) \
;     dst[m][k] = *reinterpret_cast<const bf16x8*>((char*)SA(b, h) + lds_byte(wr * 64 + m * 16 + fr, k * 32 + fq * 8))
; #define LDB(dst, b, h) _Pragma("unroll") for (int n = 0; n < 2; ++n) _Pragma("unroll") for (int k = 0; k < 2; ++k) \
;     dst[n][k] = *reinterpret_cast<const bf16x8*>((char*)SB(b, h) + lds_byte(wc * 32 + n * 16 + fr, k * 32 + fq * 8))
; #define WAIT_V(n) asm volatile("s_waitcnt vmcnt(" #n ")" ::: "memory")
; #define WAIT_L(n) asm volatile("s_waitcnt lgkmcnt(" #n ")" ::: "memory")
; #define BAR __builtin_amdgcn_s_barrier()
; #define SCHED __builtin_amdgcn_sched_barrier(0)
; template <int MODE>
; __device__ __forceinline__ void gemm_phase(int s, char* lds, const int wave) {
;     ...
;       for (int t = 0; t < nt; t += 2) {
;         const bool lastit = t + 2 >= nt;
;         const bf16* A2 = lastit ? Anext : Acur; const bf16* B2 = lastit ? Bnext : Bcur; const int k2 = lastit ? 0 : t + 2;
;         LDB(B0, 0, 0); SCHED; LDA(At, 0, 0); STAGE(SA(1, 1), Acur, HALF, t + 1);
;         WAIT_L(8); BAR; WAIT_L(0); MMA(0, 0, At, B0); BAR; SCHED;
;         LDB(B1, 0, 1); STAGE(SB(0, 0), B2, 0, k2);
;         BAR; WAIT_L(0); MMA(0, 1, At, B1); BAR;
;         LDA(At, 0, 1); STAGE(SA(0, 0), A2, 0, k2);
;         BAR; WAIT_L(0); MMA(1, 0, At, B0); BAR; SCHED;
;         STAGE(SB(0, 1), B2, HALF, k2);
;         WAIT_V(6); BAR; MMA(1, 1, At, B1); BAR;
;         LDB(B0, 1, 0); SCHED; LDA(At, 1, 0); STAGE(SA(0, 1), A2, HALF, k2);
;         WAIT_L(8); BAR; WAIT_L(0); MMA(0, 0, At, B0); BAR; SCHED;
;         LDB(B1, 1, 1); STAGE(SB(1, 0), B2, 0, k2 + 1);
;         BAR; WAIT_L(0); MMA(0, 1, At, B1); BAR;
;         LDA(At, 1, 1); STAGE(SA(1, 0), A2, 0, k2 + 1);
;         BAR; WAIT_L(0); MMA(1, 0, At, B0); BAR; SCHED;
;         STAGE(SB(1, 1), B2, HALF, k2 + 1);
;         WAIT_V(6); BAR; MMA(1, 1, At, B1); BAR;
;       }
.LBB0_214:
	ds_read_b128 v[134:137], v175
	ds_read_b128 v[138:141], v175 offset:1024
	ds_read_b128 v[150:153], v175 offset:2048
	ds_read_b128 v[154:157], v175 offset:3072
	s_add_i32 s5, s5, 2
	s_cmp_gt_u32 s5, 29
	s_cselect_b64 s[42:43], -1, 0
	s_and_b64 vcc, s[42:43], exec
	s_cselect_b32 s41, s57, s7
	s_cselect_b32 s46, s56, s6
	v_add_u32_e32 v0, 0xc000, v163
	ds_read_b128 v[198:201], v176
	ds_read_b128 v[202:205], v176 offset:1024
	ds_read_b128 v[206:209], v177
	ds_read_b128 v[210:213], v177 offset:1024
	ds_read_b128 v[214:217], v178
	ds_read_b128 v[218:221], v178 offset:1024
	ds_read_b128 v[222:225], v179
	ds_read_b128 v[226:229], v179 offset:1024
	v_readfirstlane_b32 s30, v0
	v_add_u32_e32 v0, 0xe000, v163
	s_mov_b32 m0, s30
	v_readfirstlane_b32 s30, v0
	global_load_lds_dwordx4 v[132:133], off
	s_mov_b32 m0, s30
	s_nop 0
	global_load_lds_dwordx4 v[130:131], off
	s_waitcnt lgkmcnt(8)
	s_barrier
	s_waitcnt lgkmcnt(0)
	s_waitcnt lgkmcnt(0)
	v_mfma_f32_16x16x32_bf16 v[122:125], v[134:137], v[198:201], v[122:125]
	v_mfma_f32_16x16x32_bf16 v[114:117], v[150:153], v[198:201], v[114:117]
	v_mfma_f32_16x16x32_bf16 v[106:109], v[134:137], v[206:209], v[106:109]
	v_mfma_f32_16x16x32_bf16 v[98:101], v[150:153], v[206:209], v[98:101]
	v_mfma_f32_16x16x32_bf16 v[90:93], v[134:137], v[214:217], v[90:93]
	v_mfma_f32_16x16x32_bf16 v[82:85], v[150:153], v[214:217], v[82:85]
	v_mfma_f32_16x16x32_bf16 v[74:77], v[134:137], v[222:225], v[74:77]
	v_mfma_f32_16x16x32_bf16 v[66:69], v[150:153], v[222:225], v[66:69]
	v_mfma_f32_16x16x32_bf16 v[122:125], v[138:141], v[202:205], v[122:125]
	v_mfma_f32_16x16x32_bf16 v[114:117], v[154:157], v[202:205], v[114:117]
	v_mfma_f32_16x16x32_bf16 v[106:109], v[138:141], v[210:213], v[106:109]
	v_mfma_f32_16x16x32_bf16 v[98:101], v[154:157], v[210:213], v[98:101]
	v_mfma_f32_16x16x32_bf16 v[90:93], v[138:141], v[218:221], v[90:93]
	v_mfma_f32_16x16x32_bf16 v[82:85], v[154:157], v[218:221], v[82:85]
	v_mfma_f32_16x16x32_bf16 v[74:77], v[138:141], v[226:229], v[74:77]
	v_mfma_f32_16x16x32_bf16 v[66:69], v[154:157], v[226:229], v[66:69]
	s_barrier
	s_cselect_b32 s30, 0, s40
	s_cselect_b32 s47, s59, s9
	s_cselect_b32 s53, s58, s8
	s_lshl_b64 s[42:43], s[30:31], 1
	s_add_u32 s44, s53, s42
	s_addc_u32 s45, s47, s43
	v_readfirstlane_b32 s55, v161
	v_lshl_add_u64 v[158:159], s[44:45], 0, v[142:143]
	s_mov_b32 m0, s55
	v_lshl_add_u64 v[184:185], s[44:45], 0, v[144:145]
	v_readfirstlane_b32 s44, v162
	ds_read_b128 v[230:233], v180
	ds_read_b128 v[234:237], v180 offset:1024
	ds_read_b128 v[238:241], v180 offset:2048
	ds_read_b128 v[242:245], v180 offset:3072
	global_load_lds_dwordx4 v[158:159], off
	s_mov_b32 m0, s44
	s_nop 0
	global_load_lds_dwordx4 v[184:185], off
	s_barrier
	s_waitcnt lgkmcnt(0)
	s_waitcnt lgkmcnt(0)
	v_mfma_f32_16x16x32_bf16 v[126:129], v[230:233], v[198:201], v[126:129]
	v_mfma_f32_16x16x32_bf16 v[118:121], v[238:241], v[198:201], v[118:121]
	v_mfma_f32_16x16x32_bf16 v[110:113], v[230:233], v[206:209], v[110:113]
	v_mfma_f32_16x16x32_bf16 v[102:105], v[238:241], v[206:209], v[102:105]
	v_mfma_f32_16x16x32_bf16 v[94:97], v[230:233], v[214:217], v[94:97]
	v_mfma_f32_16x16x32_bf16 v[86:89], v[238:241], v[214:217], v[86:89]
	v_mfma_f32_16x16x32_bf16 v[78:81], v[230:233], v[222:225], v[78:81]
	v_mfma_f32_16x16x32_bf16 v[70:73], v[238:241], v[222:225], v[70:73]
	v_mfma_f32_16x16x32_bf16 v[126:129], v[234:237], v[202:205], v[126:129]
	v_mfma_f32_16x16x32_bf16 v[118:121], v[242:245], v[202:205], v[118:121]
	v_mfma_f32_16x16x32_bf16 v[110:113], v[234:237], v[210:213], v[110:113]
	v_mfma_f32_16x16x32_bf16 v[102:105], v[242:245], v[210:213], v[102:105]
	v_mfma_f32_16x16x32_bf16 v[94:97], v[234:237], v[218:221], v[94:97]
	v_mfma_f32_16x16x32_bf16 v[86:89], v[242:245], v[218:221], v[86:89]
	v_mfma_f32_16x16x32_bf16 v[78:81], v[234:237], v[226:229], v[78:81]
	v_mfma_f32_16x16x32_bf16 v[70:73], v[242:245], v[226:229], v[70:73]
	s_add_u32 s44, s46, s42
	s_addc_u32 s45, s41, s43
	v_readfirstlane_b32 s41, v163
	v_lshl_add_u64 v[246:247], s[44:45], 0, v[142:143]
	s_mov_b32 m0, s41
	v_readfirstlane_b32 s41, v164
	s_barrier
	ds_read_b128 v[198:201], v176 offset:16384
	ds_read_b128 v[202:205], v176 offset:17408
	ds_read_b128 v[206:209], v177 offset:16384
	ds_read_b128 v[210:213], v177 offset:17408
	ds_read_b128 v[214:217], v178 offset:16384
	ds_read_b128 v[218:221], v178 offset:17408
	ds_read_b128 v[222:225], v179 offset:16384
	ds_read_b128 v[226:229], v179 offset:17408
	global_load_lds_dwordx4 v[246:247], off
	v_lshl_add_u64 v[248:249], s[44:45], 0, v[144:145]
	s_mov_b32 m0, s41
	s_nop 0
	global_load_lds_dwordx4 v[248:249], off
	s_barrier
	s_waitcnt lgkmcnt(0)
	s_waitcnt lgkmcnt(0)
	v_mfma_f32_16x16x32_bf16 v[58:61], v[134:137], v[198:201], v[58:61]
	v_mfma_f32_16x16x32_bf16 v[50:53], v[150:153], v[198:201], v[50:53]
	v_mfma_f32_16x16x32_bf16 v[42:45], v[134:137], v[206:209], v[42:45]
	v_mfma_f32_16x16x32_bf16 v[34:37], v[150:153], v[206:209], v[34:37]
	v_mfma_f32_16x16x32_bf16 v[26:29], v[134:137], v[214:217], v[26:29]
	v_mfma_f32_16x16x32_bf16 v[18:21], v[150:153], v[214:217], v[18:21]
	v_mfma_f32_16x16x32_bf16 v[10:13], v[134:137], v[222:225], v[10:13]
	v_mfma_f32_16x16x32_bf16 v[2:5], v[150:153], v[222:225], v[2:5]
	v_mfma_f32_16x16x32_bf16 v[58:61], v[138:141], v[202:205], v[58:61]
	v_mfma_f32_16x16x32_bf16 v[50:53], v[154:157], v[202:205], v[50:53]
	v_mfma_f32_16x16x32_bf16 v[42:45], v[138:141], v[210:213], v[42:45]
	v_mfma_f32_16x16x32_bf16 v[34:37], v[154:157], v[210:213], v[34:37]
	v_mfma_f32_16x16x32_bf16 v[26:29], v[138:141], v[218:221], v[26:29]
	v_mfma_f32_16x16x32_bf16 v[18:21], v[154:157], v[218:221], v[18:21]
	v_mfma_f32_16x16x32_bf16 v[10:13], v[138:141], v[226:229], v[10:13]
	v_mfma_f32_16x16x32_bf16 v[2:5], v[154:157], v[226:229], v[2:5]
	s_barrier
; #define LDA(dst, b, h) _Pragma("unroll") for (int m = 0; m < 4; ++m) _Pragma("unroll") for (int k = 0; k < 2; ++k) \
;     dst[m][k] = *reinterpret_cast<const bf16x8*>((char*)SA(b, h) + lds_byte(wr * 64 + m * 16 + fr, k * 32 + fq * 8))
; #define LDB(dst, b, h) _Pragma("unroll") for (int n = 0; n < 2; ++n) _Pragma("unroll") for (int k = 0; k < 2; ++k) \
;     dst[n][k] = *reinterpret_cast<const bf16x8*>((char*)SB(b, h) + lds_byte(wc * 32 + n * 16 + fr, k * 32 + fq * 8))
; #define WAIT_V(n) asm volatile("s_waitcnt vmcnt(" #n ")" ::: "memory")
; #define WAIT_L(n) asm volatile("s_waitcnt lgkmcnt(" #n ")" ::: "memory")
; #define BAR __builtin_amdgcn_s_barrier()
; #define SCHED __builtin_amdgcn_sched_barrier(0)
; template <int MODE>
; __device__ __forceinline__ void gemm_phase(int s, char* lds, const int wave) {
;     ...
;       for (int t = 0; t < nt; t += 2) {
;         const bool lastit = t + 2 >= nt;
;         const bf16* A2 = lastit ? Anext : Acur; const bf16* B2 = lastit ? Bnext : Bcur; const int k2 = lastit ? 0 : t + 2;
;         LDB(B0, 0, 0); SCHED; LDA(At, 0, 0); STAGE(SA(1, 1), Acur, HALF, t + 1);
;         WAIT_L(8); BAR; WAIT_L(0); MMA(0, 0, At, B0); BAR; SCHED;
;         LDB(B1, 0, 1); STAGE(SB(0, 0), B2, 0, k2);
;         BAR; WAIT_L(0); MMA(0, 1, At, B1); BAR;
;         LDA(At, 0, 1); STAGE(SA(0, 0), A2, 0, k2);
;         BAR; WAIT_L(0); MMA(1, 0, At, B0); BAR; SCHED;
;         STAGE(SB(0, 1), B2, HALF, k2);
;         WAIT_V(6); BAR; MMA(1, 1, At, B1); BAR;
;         LDB(B0, 1, 0); SCHED; LDA(At, 1, 0); STAGE(SA(0, 1), A2, HALF, k2);
;         WAIT_L(8); BAR; WAIT_L(0); MMA(0, 0, At, B0); BAR; SCHED;
;         LDB(B1, 1, 1); STAGE(SB(1, 0), B2, 0, k2 + 1);
;         BAR; WAIT_L(0); MMA(0, 1, At, B1); BAR;
;         LDA(At, 1, 1); STAGE(SA(1, 0), A2, 0, k2 + 1);
;         BAR; WAIT_L(0); MMA(1, 0, At, B0); BAR; SCHED;
;         STAGE(SB(1, 1), B2, HALF, k2 + 1);
;         WAIT_V(6); BAR; MMA(1, 1, At, B1); BAR;
;       }
	s_add_u32 s60, s53, 0x80000
	s_addc_u32 s61, s47, 0
	s_add_u32 s42, s60, s42
	s_addc_u32 s43, s61, s43
	v_readfirstlane_b32 s41, v165
	v_lshl_add_u64 v[134:135], s[42:43], 0, v[142:143]
	s_mov_b32 m0, s41
	v_readfirstlane_b32 s41, v166
	global_load_lds_dwordx4 v[134:135], off
	v_lshl_add_u64 v[134:135], s[42:43], 0, v[144:145]
	s_mov_b32 m0, s41
	s_nop 0
	global_load_lds_dwordx4 v[134:135], off
	s_waitcnt vmcnt(6)
	s_barrier
	v_mfma_f32_16x16x32_bf16 v[62:65], v[230:233], v[198:201], v[62:65]
	v_mfma_f32_16x16x32_bf16 v[54:57], v[238:241], v[198:201], v[54:57]
	v_mfma_f32_16x16x32_bf16 v[46:49], v[230:233], v[206:209], v[46:49]
	v_mfma_f32_16x16x32_bf16 v[38:41], v[238:241], v[206:209], v[38:41]
	v_mfma_f32_16x16x32_bf16 v[30:33], v[230:233], v[214:217], v[30:33]
	v_mfma_f32_16x16x32_bf16 v[22:25], v[238:241], v[214:217], v[22:25]
	v_mfma_f32_16x16x32_bf16 v[14:17], v[230:233], v[222:225], v[14:17]
	v_mfma_f32_16x16x32_bf16 v[6:9], v[238:241], v[222:225], v[6:9]
	v_mfma_f32_16x16x32_bf16 v[62:65], v[234:237], v[202:205], v[62:65]
	v_mfma_f32_16x16x32_bf16 v[54:57], v[242:245], v[202:205], v[54:57]
	v_mfma_f32_16x16x32_bf16 v[46:49], v[234:237], v[210:213], v[46:49]
	v_mfma_f32_16x16x32_bf16 v[38:41], v[242:245], v[210:213], v[38:41]
	v_mfma_f32_16x16x32_bf16 v[30:33], v[234:237], v[218:221], v[30:33]
	v_mfma_f32_16x16x32_bf16 v[22:25], v[242:245], v[218:221], v[22:25]
	v_mfma_f32_16x16x32_bf16 v[14:17], v[234:237], v[226:229], v[14:17]
	v_mfma_f32_16x16x32_bf16 v[6:9], v[242:245], v[226:229], v[6:9]
	s_barrier
	ds_read_b128 v[134:137], v181
	ds_read_b128 v[138:141], v181 offset:1024
	ds_read_b128 v[150:153], v181 offset:2048
	ds_read_b128 v[154:157], v181 offset:3072
	s_add_u32 s42, s44, 0x80000
	s_addc_u32 s43, s45, 0
	v_readfirstlane_b32 s41, v167
	v_lshl_add_u64 v[230:231], s[42:43], 0, v[142:143]
	s_mov_b32 m0, s41
	v_readfirstlane_b32 s41, v168
	ds_read_b128 v[198:201], v176 offset:32768
	ds_read_b128 v[202:205], v176 offset:33792
	ds_read_b128 v[206:209], v177 offset:32768
	ds_read_b128 v[210:213], v177 offset:33792
	ds_read_b128 v[214:217], v178 offset:32768
	ds_read_b128 v[218:221], v178 offset:33792
	ds_read_b128 v[222:225], v179 offset:32768
	ds_read_b128 v[226:229], v179 offset:33792
	global_load_lds_dwordx4 v[230:231], off
	v_lshl_add_u64 v[230:231], s[42:43], 0, v[144:145]
	s_mov_b32 m0, s41
	s_nop 0
	global_load_lds_dwordx4 v[230:231], off
	s_waitcnt lgkmcnt(8)
	s_barrier
	s_waitcnt lgkmcnt(0)
	s_waitcnt lgkmcnt(0)
	v_mfma_f32_16x16x32_bf16 v[122:125], v[134:137], v[198:201], v[122:125]
	v_mfma_f32_16x16x32_bf16 v[114:117], v[150:153], v[198:201], v[114:117]
	v_mfma_f32_16x16x32_bf16 v[106:109], v[134:137], v[206:209], v[106:109]
	v_mfma_f32_16x16x32_bf16 v[98:101], v[150:153], v[206:209], v[98:101]
	v_mfma_f32_16x16x32_bf16 v[90:93], v[134:137], v[214:217], v[90:93]
	v_mfma_f32_16x16x32_bf16 v[82:85], v[150:153], v[214:217], v[82:85]
	v_mfma_f32_16x16x32_bf16 v[74:77], v[134:137], v[222:225], v[74:77]
	v_mfma_f32_16x16x32_bf16 v[66:69], v[150:153], v[222:225], v[66:69]
	v_mfma_f32_16x16x32_bf16 v[122:125], v[138:141], v[202:205], v[122:125]
	v_mfma_f32_16x16x32_bf16 v[114:117], v[154:157], v[202:205], v[114:117]
	v_mfma_f32_16x16x32_bf16 v[106:109], v[138:141], v[210:213], v[106:109]
	v_mfma_f32_16x16x32_bf16 v[98:101], v[154:157], v[210:213], v[98:101]
	v_mfma_f32_16x16x32_bf16 v[90:93], v[138:141], v[218:221], v[90:93]
	v_mfma_f32_16x16x32_bf16 v[82:85], v[154:157], v[218:221], v[82:85]
	v_mfma_f32_16x16x32_bf16 v[74:77], v[138:141], v[226:229], v[74:77]
	v_mfma_f32_16x16x32_bf16 v[66:69], v[154:157], v[226:229], v[66:69]
	s_barrier
	v_readfirstlane_b32 s41, v169
	v_lshl_add_u64 v[158:159], v[158:159], 0, s[18:19]
	s_mov_b32 m0, s41
	v_readfirstlane_b32 s41, v170
	ds_read_b128 v[230:233], v182
	ds_read_b128 v[234:237], v182 offset:1024
	ds_read_b128 v[238:241], v182 offset:2048
	ds_read_b128 v[242:245], v182 offset:3072
	global_load_lds_dwordx4 v[158:159], off
	v_lshl_add_u64 v[158:159], v[184:185], 0, s[18:19]
	s_mov_b32 m0, s41
	s_or_b32 s30, s30, 64
	global_load_lds_dwordx4 v[158:159], off
	s_barrier
	s_waitcnt lgkmcnt(0)
	s_waitcnt lgkmcnt(0)
	v_mfma_f32_16x16x32_bf16 v[126:129], v[230:233], v[198:201], v[126:129]
	v_mfma_f32_16x16x32_bf16 v[118:121], v[238:241], v[198:201], v[118:121]
	v_mfma_f32_16x16x32_bf16 v[110:113], v[230:233], v[206:209], v[110:113]
	v_mfma_f32_16x16x32_bf16 v[102:105], v[238:241], v[206:209], v[102:105]
	v_mfma_f32_16x16x32_bf16 v[94:97], v[230:233], v[214:217], v[94:97]
	v_mfma_f32_16x16x32_bf16 v[86:89], v[238:241], v[214:217], v[86:89]
	v_mfma_f32_16x16x32_bf16 v[78:81], v[230:233], v[222:225], v[78:81]
	v_mfma_f32_16x16x32_bf16 v[70:73], v[238:241], v[222:225], v[70:73]
	v_mfma_f32_16x16x32_bf16 v[126:129], v[234:237], v[202:205], v[126:129]
	v_mfma_f32_16x16x32_bf16 v[118:121], v[242:245], v[202:205], v[118:121]
	v_mfma_f32_16x16x32_bf16 v[110:113], v[234:237], v[210:213], v[110:113]
	v_mfma_f32_16x16x32_bf16 v[102:105], v[242:245], v[210:213], v[102:105]
	v_mfma_f32_16x16x32_bf16 v[94:97], v[234:237], v[218:221], v[94:97]
	v_mfma_f32_16x16x32_bf16 v[86:89], v[242:245], v[218:221], v[86:89]
	v_mfma_f32_16x16x32_bf16 v[78:81], v[234:237], v[226:229], v[78:81]
	v_mfma_f32_16x16x32_bf16 v[70:73], v[242:245], v[226:229], v[70:73]
	v_readfirstlane_b32 s41, v171
	v_lshl_add_u64 v[158:159], v[246:247], 0, s[18:19]
	s_mov_b32 m0, s41
	v_readfirstlane_b32 s41, v172
	s_barrier
; #define WAIT_V(n) asm volatile("s_waitcnt vmcnt(" #n ")" ::: "memory")
; template <int MODE>
; __device__ __forceinline__ void gemm_epilogue(char* ws, const float* __restrict__ xseq, float* __restrict__ oseq, const int pm, const int pn,
;                                               f32x4 (&acc)[2][2][4][2], const int wave) {
;     ...
;     } else if (MODE == G_PROJ && bcol < 2 * 3072) {
;       const float* cosr = (const float*)(ws + OFF_COS) + row * 64 + (wc & 1) * 32 + fq * 4;
;       const float* sinr = (const float*)(ws + OFF_SIN) + row * 64 + (wc & 1) * 32 + fq * 4;
;       u32x2 w1[2], w2[2];
; #pragma unroll
;       for (int n = 0; n < 2; ++n) {
;         const f32x4 c = *(const f32x4*)(cosr + n * 16), sn = *(const f32x4*)(sinr + n * 16);
;         const f32x4 x1 = acc[ai][0][m][n], x2 = acc[ai][1][m][n];
;         w1[n] = u32x2{cvtpk(x1[0] * c[0] - x2[0] * sn[0], x1[1] * c[1] - x2[1] * sn[1]), cvtpk(x1[2] * c[2] - x2[2] * sn[2], x1[3] * c[3] - x2[3] * sn[3])};
;         w2[n] = u32x2{cvtpk(x1[0] * sn[0] + x2[0] * c[0], x1[1] * sn[1] + x2[1] * c[1]), cvtpk(x1[2] * sn[2] + x2[2] * c[2], x1[3] * sn[3] + x2[3] * c[3])};
;       }
; template <int MODE>
; __device__ __forceinline__ void gemm_phase(int s, char* lds, const int wave) {
;     ...
;       for (int t = 0; t < nt; t += 2) {
;         const bool lastit = t + 2 >= nt;
;         const bf16* A2 = lastit ? Anext : Acur; const bf16* B2 = lastit ? Bnext : Bcur; const int k2 = lastit ? 0 : t + 2;
;         LDB(B0, 0, 0); SCHED; LDA(At, 0, 0); STAGE(SA(1, 1), Acur, HALF, t + 1);
;         WAIT_L(8); BAR; WAIT_L(0); MMA(0, 0, At, B0); BAR; SCHED;
;         LDB(B1, 0, 1); STAGE(SB(0, 0), B2, 0, k2);
;         BAR; WAIT_L(0); MMA(0, 1, At, B1); BAR;
;         LDA(At, 0, 1); STAGE(SA(0, 0), A2, 0, k2);
;         BAR; WAIT_L(0); MMA(1, 0, At, B0); BAR; SCHED;
;         STAGE(SB(0, 1), B2, HALF, k2);
;         WAIT_V(6); BAR; MMA(1, 1, At, B1); BAR;
;         LDB(B0, 1, 0); SCHED; LDA(At, 1, 0); STAGE(SA(0, 1), A2, HALF, k2);
;         WAIT_L(8); BAR; WAIT_L(0); MMA(0, 0, At, B0); BAR; SCHED;
;         LDB(B1, 1, 1); STAGE(SB(1, 0), B2, 0, k2 + 1);
;         BAR; WAIT_L(0); MMA(0, 1, At, B1); BAR;
;         LDA(At, 1, 1); STAGE(SA(1, 0), A2, 0, k2 + 1);
;         BAR; WAIT_L(0); MMA(1, 0, At, B0); BAR; SCHED;
;         STAGE(SB(1, 1), B2, HALF, k2 + 1);
;         WAIT_V(6); BAR; MMA(1, 1, At, B1); BAR;
;       }
	ds_read_b128 v[198:201], v176 offset:49152
	ds_read_b128 v[202:205], v176 offset:50176
	ds_read_b128 v[206:209], v177 offset:49152
	ds_read_b128 v[210:213], v177 offset:50176
	ds_read_b128 v[214:217], v178 offset:49152
	ds_read_b128 v[218:221], v178 offset:50176
	ds_read_b128 v[222:225], v179 offset:49152
	ds_read_b128 v[226:229], v179 offset:50176
	global_load_lds_dwordx4 v[158:159], off
	v_lshl_add_u64 v[158:159], v[248:249], 0, s[18:19]
	s_mov_b32 m0, s41
	s_nop 0
	global_load_lds_dwordx4 v[158:159], off
	s_barrier
	s_waitcnt lgkmcnt(0)
	s_waitcnt lgkmcnt(0)
	v_mfma_f32_16x16x32_bf16 v[58:61], v[134:137], v[198:201], v[58:61]
	v_mfma_f32_16x16x32_bf16 v[50:53], v[150:153], v[198:201], v[50:53]
	v_mfma_f32_16x16x32_bf16 v[42:45], v[134:137], v[206:209], v[42:45]
	v_mfma_f32_16x16x32_bf16 v[34:37], v[150:153], v[206:209], v[34:37]
	v_mfma_f32_16x16x32_bf16 v[26:29], v[134:137], v[214:217], v[26:29]
	v_mfma_f32_16x16x32_bf16 v[18:21], v[150:153], v[214:217], v[18:21]
	v_mfma_f32_16x16x32_bf16 v[10:13], v[134:137], v[222:225], v[10:13]
	v_mfma_f32_16x16x32_bf16 v[2:5], v[150:153], v[222:225], v[2:5]
	v_mfma_f32_16x16x32_bf16 v[58:61], v[138:141], v[202:205], v[58:61]
	v_mfma_f32_16x16x32_bf16 v[50:53], v[154:157], v[202:205], v[50:53]
	v_mfma_f32_16x16x32_bf16 v[42:45], v[138:141], v[210:213], v[42:45]
	v_mfma_f32_16x16x32_bf16 v[34:37], v[154:157], v[210:213], v[34:37]
	v_mfma_f32_16x16x32_bf16 v[26:29], v[138:141], v[218:221], v[26:29]
	v_mfma_f32_16x16x32_bf16 v[18:21], v[154:157], v[218:221], v[18:21]
	v_mfma_f32_16x16x32_bf16 v[10:13], v[138:141], v[226:229], v[10:13]
	v_mfma_f32_16x16x32_bf16 v[2:5], v[154:157], v[226:229], v[2:5]
	s_barrier
	v_lshl_add_u64 v[134:135], s[60:61], 0, v[142:143]
	s_lshl_b64 s[42:43], s[30:31], 1
	v_readfirstlane_b32 s30, v173
	v_lshl_add_u64 v[134:135], v[134:135], 0, s[42:43]
	s_mov_b32 m0, s30
	v_readfirstlane_b32 s30, v174
	global_load_lds_dwordx4 v[134:135], off
	v_lshl_add_u64 v[134:135], s[60:61], 0, v[144:145]
	v_lshl_add_u64 v[134:135], v[134:135], 0, s[42:43]
	s_mov_b32 m0, s30
	s_nop 0
	global_load_lds_dwordx4 v[134:135], off
	s_waitcnt vmcnt(6)
	s_barrier
	v_mfma_f32_16x16x32_bf16 v[62:65], v[230:233], v[198:201], v[62:65]
	v_mfma_f32_16x16x32_bf16 v[54:57], v[238:241], v[198:201], v[54:57]
	v_mfma_f32_16x16x32_bf16 v[46:49], v[230:233], v[206:209], v[46:49]
	v_mfma_f32_16x16x32_bf16 v[38:41], v[238:241], v[206:209], v[38:41]
	v_mfma_f32_16x16x32_bf16 v[30:33], v[230:233], v[214:217], v[30:33]
	v_mfma_f32_16x16x32_bf16 v[22:25], v[238:241], v[214:217], v[22:25]
	v_mfma_f32_16x16x32_bf16 v[14:17], v[230:233], v[222:225], v[14:17]
	v_mfma_f32_16x16x32_bf16 v[6:9], v[238:241], v[222:225], v[6:9]
	v_mfma_f32_16x16x32_bf16 v[62:65], v[234:237], v[202:205], v[62:65]
	v_mfma_f32_16x16x32_bf16 v[54:57], v[242:245], v[202:205], v[54:57]
	v_mfma_f32_16x16x32_bf16 v[46:49], v[234:237], v[210:213], v[46:49]
	v_mfma_f32_16x16x32_bf16 v[38:41], v[242:245], v[210:213], v[38:41]
	v_mfma_f32_16x16x32_bf16 v[30:33], v[234:237], v[218:221], v[30:33]
	v_mfma_f32_16x16x32_bf16 v[22:25], v[242:245], v[218:221], v[22:25]
	v_mfma_f32_16x16x32_bf16 v[14:17], v[234:237], v[226:229], v[14:17]
	v_mfma_f32_16x16x32_bf16 v[6:9], v[242:245], v[226:229], v[6:9]
	v_lshl_add_u64 v[130:131], v[130:131], 0, s[38:39]
	v_lshl_add_u64 v[132:133], v[132:133], 0, s[38:39]
	s_addk_i32 s40, 0x80
	s_barrier
	s_cbranch_vccz .LBB0_214
	s_lshl_b32 s5, s4, 8
	s_lshl_b32 s4, s2, 8
	s_cmp_gt_i32 s2, 23
	s_cselect_b64 s[6:7], -1, 0
	s_cmp_gt_i32 s2, 47
	s_cselect_b64 s[8:9], -1, 0
	s_cmp_gt_i32 s2, 35
	v_mov_b32_e32 v150, v187
	s_cselect_b64 s[60:61], -1, 0
	s_cmp_gt_u32 s2, 47
	s_cselect_b64 s[62:63], -1, 0
	v_ashrrev_i32_e32 v0, 2, v150
	v_and_or_b32 v130, v150, 15, s5
	s_ashr_i32 s5, s4, 31
	v_and_b32_e32 v0, 0xffffffc0, v0
	s_lshl_b64 s[40:41], s[4:5], 1
	v_lshrrev_b32_e32 v131, 2, v150
	v_add_u32_e32 v154, v130, v0
	s_add_u32 s64, s12, s40
	v_lshrrev_b32_e32 v152, 1, v150
	v_and_b32_e32 v130, 16, v150
	v_and_b32_e32 v153, 12, v131
	s_addc_u32 s65, s13, s41
	v_and_b32_e32 v0, 0x60, v152
	v_add_u32_e32 v131, 12, v153
	v_cmp_eq_u32_e32 vcc, 0, v130
	s_cmp_lt_i32 s2, 24
	v_or_b32_e32 v0, s4, v0
	v_cndmask_b32_e32 v151, v131, v153, vcc
	s_mov_b64 s[4:5], -1
	s_cbranch_scc1 .LBB0_241
	s_and_b64 vcc, exec, s[8:9]
	v_mov_b32_e32 v130, v122
	v_mov_b32_e32 v131, v123
	v_mov_b32_e32 v132, v124
	v_mov_b32_e32 v133, v125
	s_cbranch_vccz .LBB0_218
	v_mul_f32_e32 v130, 0xbfb8aa3b, v122
	v_mul_f32_e32 v131, 0xbfb8aa3b, v123
	v_mul_f32_e32 v132, 0xbfb8aa3b, v124
	v_mul_f32_e32 v133, 0xbfb8aa3b, v125
	v_exp_f32_e32 v130, v130
	v_exp_f32_e32 v131, v131
	v_exp_f32_e32 v132, v132
	v_exp_f32_e32 v133, v133
	v_add_f32_e32 v130, 1.0, v130
	v_add_f32_e32 v131, 1.0, v131
	v_add_f32_e32 v132, 1.0, v132
	v_add_f32_e32 v133, 1.0, v133
	v_rcp_f32_e32 v130, v130
	v_rcp_f32_e32 v131, v131
	v_rcp_f32_e32 v132, v132
	v_rcp_f32_e32 v133, v133

; #define LDA(dst, b, h) _Pragma("unroll") for (int m = 0; m < 4; ++m) _Pragma("unroll") for (int k = 0; k < 2; ++k) \
;     dst[m][k] = *reinterpret_cast<const bf16x8*>((char*)SA(b, h) + lds_byte(wr * 64 + m * 16 + fr, k * 32 + fq * 8))
; #define LDB(dst, b, h) _Pragma("unroll") for (int n = 0; n < 2; ++n) _Pragma("unroll") for (int k = 0; k < 2; ++k) \
;     dst[n][k] = *reinterpret_cast<const bf16x8*>((char*)SB(b, h) + lds_byte(wc * 32 + n * 16 + fr, k * 32 + fq * 8))
; #define WAIT_V(n) asm volatile("s_waitcnt vmcnt(" #n ")" ::: "memory")
; #define WAIT_L(n) asm volatile("s_waitcnt lgkmcnt(" #n ")" ::: "memory")
; #define BAR __builtin_amdgcn_s_barrier()
; #define SCHED __builtin_amdgcn_sched_barrier(0)
; template <int MODE>
; __device__ __forceinline__ void gemm_phase(int s, char* lds, const int wave) {
;     ...
;       for (int t = 0; t < nt; t += 2) {
;         const bool lastit = t + 2 >= nt;
;         const bf16* A2 = lastit ? Anext : Acur; const bf16* B2 = lastit ? Bnext : Bcur; const int k2 = lastit ? 0 : t + 2;
;         LDB(B0, 0, 0); SCHED; LDA(At, 0, 0); STAGE(SA(1, 1), Acur, HALF, t + 1);
;         WAIT_L(8); BAR; WAIT_L(0); MMA(0, 0, At, B0); BAR; SCHED;
;         LDB(B1, 0, 1); STAGE(SB(0, 0), B2, 0, k2);
;         BAR; WAIT_L(0); MMA(0, 1, At, B1); BAR;
;         LDA(At, 0, 1); STAGE(SA(0, 0), A2, 0, k2);
;         BAR; WAIT_L(0); MMA(1, 0, At, B0); BAR; SCHED;
;         STAGE(SB(0, 1), B2, HALF, k2);
;         WAIT_V(6); BAR; MMA(1, 1, At, B1); BAR;
;         LDB(B0, 1, 0); SCHED; LDA(At, 1, 0); STAGE(SA(0, 1), A2, HALF, k2);
;         WAIT_L(8); BAR; WAIT_L(0); MMA(0, 0, At, B0); BAR; SCHED;
;         LDB(B1, 1, 1); STAGE(SB(1, 0), B2, 0, k2 + 1);
;         BAR; WAIT_L(0); MMA(0, 1, At, B1); BAR;
;         LDA(At, 1, 1); STAGE(SA(1, 0), A2, 0, k2 + 1);
;         BAR; WAIT_L(0); MMA(1, 0, At, B0); BAR; SCHED;
;         STAGE(SB(1, 1), B2, HALF, k2 + 1);
;         WAIT_V(6); BAR; MMA(1, 1, At, B1); BAR;
;       }
.LBB0_645:
	ds_read_b128 v[164:167], v0
	ds_read_b128 v[168:171], v0 offset:1024
	ds_read_b128 v[172:175], v0 offset:2048
	ds_read_b128 v[176:179], v0 offset:3072
	s_add_i32 s41, s41, 2
	s_cmpk_gt_u32 s41, 0x55
	s_cselect_b64 s[44:45], -1, 0
	s_and_b64 vcc, s[44:45], exec
	s_cselect_b32 s43, s7, s13
	s_cselect_b32 s50, s6, s12
	v_add_u32_e32 v184, 0xc000, v145
	ds_read_b128 v[180:183], v157
	ds_read_b128 v[198:201], v157 offset:1024
	ds_read_b128 v[202:205], v158
	ds_read_b128 v[206:209], v158 offset:1024
	ds_read_b128 v[210:213], v159
	ds_read_b128 v[214:217], v159 offset:1024
	ds_read_b128 v[218:221], v160
	ds_read_b128 v[222:225], v160 offset:1024
	v_readfirstlane_b32 s30, v184
	v_add_u32_e32 v184, 0xe000, v145
	s_mov_b32 m0, s30
	v_readfirstlane_b32 s30, v184
	global_load_lds_dwordx4 v[140:141], off
	s_mov_b32 m0, s30
	s_nop 0
	global_load_lds_dwordx4 v[138:139], off
	s_waitcnt lgkmcnt(8)
	s_barrier
	s_waitcnt lgkmcnt(0)
	s_waitcnt lgkmcnt(0)
	v_mfma_f32_16x16x32_bf16 v[126:129], v[164:167], v[180:183], v[126:129]
	v_mfma_f32_16x16x32_bf16 v[122:125], v[172:175], v[180:183], v[122:125]
	v_mfma_f32_16x16x32_bf16 v[110:113], v[164:167], v[202:205], v[110:113]
	v_mfma_f32_16x16x32_bf16 v[106:109], v[172:175], v[202:205], v[106:109]
	v_mfma_f32_16x16x32_bf16 v[94:97], v[164:167], v[210:213], v[94:97]
	v_mfma_f32_16x16x32_bf16 v[90:93], v[172:175], v[210:213], v[90:93]
	v_mfma_f32_16x16x32_bf16 v[78:81], v[164:167], v[218:221], v[78:81]
	v_mfma_f32_16x16x32_bf16 v[74:77], v[172:175], v[218:221], v[74:77]
	v_mfma_f32_16x16x32_bf16 v[126:129], v[168:171], v[198:201], v[126:129]
	v_mfma_f32_16x16x32_bf16 v[122:125], v[176:179], v[198:201], v[122:125]
	v_mfma_f32_16x16x32_bf16 v[110:113], v[168:171], v[206:209], v[110:113]
	v_mfma_f32_16x16x32_bf16 v[106:109], v[176:179], v[206:209], v[106:109]
	v_mfma_f32_16x16x32_bf16 v[94:97], v[168:171], v[214:217], v[94:97]
	v_mfma_f32_16x16x32_bf16 v[90:93], v[176:179], v[214:217], v[90:93]
	v_mfma_f32_16x16x32_bf16 v[78:81], v[168:171], v[222:225], v[78:81]
	v_mfma_f32_16x16x32_bf16 v[74:77], v[176:179], v[222:225], v[74:77]
	s_barrier
	s_cselect_b32 s30, 0, s42
	s_cselect_b32 s51, s11, s15
	s_cselect_b32 s60, s10, s14
	s_lshl_b64 s[44:45], s[30:31], 1
	s_add_u32 s46, s60, s44
	s_addc_u32 s47, s51, s45
	v_readfirstlane_b32 s61, v143
	v_lshl_add_u64 v[184:185], s[46:47], 0, v[130:131]
	s_mov_b32 m0, s61
	v_lshl_add_u64 v[242:243], s[46:47], 0, v[132:133]
	v_readfirstlane_b32 s46, v144
	ds_read_b128 v[226:229], v161
	ds_read_b128 v[230:233], v161 offset:1024
	ds_read_b128 v[234:237], v161 offset:2048
	ds_read_b128 v[238:241], v161 offset:3072
	global_load_lds_dwordx4 v[184:185], off
	s_mov_b32 m0, s46
	s_nop 0
	global_load_lds_dwordx4 v[242:243], off
	s_barrier
	s_waitcnt lgkmcnt(0)
	s_waitcnt lgkmcnt(0)
	v_mfma_f32_16x16x32_bf16 v[118:121], v[226:229], v[180:183], v[118:121]
	v_mfma_f32_16x16x32_bf16 v[114:117], v[234:237], v[180:183], v[114:117]
	v_mfma_f32_16x16x32_bf16 v[102:105], v[226:229], v[202:205], v[102:105]
	v_mfma_f32_16x16x32_bf16 v[98:101], v[234:237], v[202:205], v[98:101]
	v_mfma_f32_16x16x32_bf16 v[86:89], v[226:229], v[210:213], v[86:89]
	v_mfma_f32_16x16x32_bf16 v[82:85], v[234:237], v[210:213], v[82:85]
	v_mfma_f32_16x16x32_bf16 v[70:73], v[226:229], v[218:221], v[70:73]
	v_mfma_f32_16x16x32_bf16 v[66:69], v[234:237], v[218:221], v[66:69]
	v_mfma_f32_16x16x32_bf16 v[118:121], v[230:233], v[198:201], v[118:121]
	v_mfma_f32_16x16x32_bf16 v[114:117], v[238:241], v[198:201], v[114:117]
	v_mfma_f32_16x16x32_bf16 v[102:105], v[230:233], v[206:209], v[102:105]
	v_mfma_f32_16x16x32_bf16 v[98:101], v[238:241], v[206:209], v[98:101]
	v_mfma_f32_16x16x32_bf16 v[86:89], v[230:233], v[214:217], v[86:89]
	v_mfma_f32_16x16x32_bf16 v[82:85], v[238:241], v[214:217], v[82:85]
	v_mfma_f32_16x16x32_bf16 v[70:73], v[230:233], v[222:225], v[70:73]
	v_mfma_f32_16x16x32_bf16 v[66:69], v[238:241], v[222:225], v[66:69]
	s_add_u32 s46, s50, s44
	s_addc_u32 s47, s43, s45
	v_readfirstlane_b32 s43, v145
	v_lshl_add_u64 v[244:245], s[46:47], 0, v[130:131]
	s_mov_b32 m0, s43
	v_readfirstlane_b32 s43, v146
	s_barrier
	ds_read_b128 v[180:183], v157 offset:16384
	ds_read_b128 v[198:201], v157 offset:17408
	ds_read_b128 v[202:205], v158 offset:16384
	ds_read_b128 v[206:209], v158 offset:17408
	ds_read_b128 v[210:213], v159 offset:16384
	ds_read_b128 v[214:217], v159 offset:17408
	ds_read_b128 v[218:221], v160 offset:16384
	ds_read_b128 v[222:225], v160 offset:17408
	global_load_lds_dwordx4 v[244:245], off
	v_lshl_add_u64 v[246:247], s[46:47], 0, v[132:133]
	s_mov_b32 m0, s43
	s_nop 0
	global_load_lds_dwordx4 v[246:247], off
	s_barrier
	s_waitcnt lgkmcnt(0)
	s_waitcnt lgkmcnt(0)
	v_mfma_f32_16x16x32_bf16 v[62:65], v[164:167], v[180:183], v[62:65]
	v_mfma_f32_16x16x32_bf16 v[58:61], v[172:175], v[180:183], v[58:61]
	v_mfma_f32_16x16x32_bf16 v[46:49], v[164:167], v[202:205], v[46:49]
	v_mfma_f32_16x16x32_bf16 v[42:45], v[172:175], v[202:205], v[42:45]
	v_mfma_f32_16x16x32_bf16 v[30:33], v[164:167], v[210:213], v[30:33]
	v_mfma_f32_16x16x32_bf16 v[26:29], v[172:175], v[210:213], v[26:29]
	v_mfma_f32_16x16x32_bf16 v[14:17], v[164:167], v[218:221], v[14:17]
	v_mfma_f32_16x16x32_bf16 v[10:13], v[172:175], v[218:221], v[10:13]
	v_mfma_f32_16x16x32_bf16 v[62:65], v[168:171], v[198:201], v[62:65]
	v_mfma_f32_16x16x32_bf16 v[58:61], v[176:179], v[198:201], v[58:61]
	v_mfma_f32_16x16x32_bf16 v[46:49], v[168:171], v[206:209], v[46:49]
	v_mfma_f32_16x16x32_bf16 v[42:45], v[176:179], v[206:209], v[42:45]
	v_mfma_f32_16x16x32_bf16 v[30:33], v[168:171], v[214:217], v[30:33]
	v_mfma_f32_16x16x32_bf16 v[26:29], v[176:179], v[214:217], v[26:29]
	v_mfma_f32_16x16x32_bf16 v[14:17], v[168:171], v[222:225], v[14:17]
	v_mfma_f32_16x16x32_bf16 v[10:13], v[176:179], v[222:225], v[10:13]
	s_barrier
; #define LDA(dst, b, h) _Pragma("unroll") for (int m = 0; m < 4; ++m) _Pragma("unroll") for (int k = 0; k < 2; ++k) \
;     dst[m][k] = *reinterpret_cast<const bf16x8*>((char*)SA(b, h) + lds_byte(wr * 64 + m * 16 + fr, k * 32 + fq * 8))
; #define LDB(dst, b, h) _Pragma("unroll") for (int n = 0; n < 2; ++n) _Pragma("unroll") for (int k = 0; k < 2; ++k) \
;     dst[n][k] = *reinterpret_cast<const bf16x8*>((char*)SB(b, h) + lds_byte(wc * 32 + n * 16 + fr, k * 32 + fq * 8))
; #define WAIT_V(n) asm volatile("s_waitcnt vmcnt(" #n ")" ::: "memory")
; #define WAIT_L(n) asm volatile("s_waitcnt lgkmcnt(" #n ")" ::: "memory")
; #define BAR __builtin_amdgcn_s_barrier()
; #define SCHED __builtin_amdgcn_sched_barrier(0)
; template <int MODE>
; __device__ __forceinline__ void gemm_phase(int s, char* lds, const int wave) {
;     ...
;       for (int t = 0; t < nt; t += 2) {
;         const bool lastit = t + 2 >= nt;
;         const bf16* A2 = lastit ? Anext : Acur; const bf16* B2 = lastit ? Bnext : Bcur; const int k2 = lastit ? 0 : t + 2;
;         LDB(B0, 0, 0); SCHED; LDA(At, 0, 0); STAGE(SA(1, 1), Acur, HALF, t + 1);
;         WAIT_L(8); BAR; WAIT_L(0); MMA(0, 0, At, B0); BAR; SCHED;
;         LDB(B1, 0, 1); STAGE(SB(0, 0), B2, 0, k2);
;         BAR; WAIT_L(0); MMA(0, 1, At, B1); BAR;
;         LDA(At, 0, 1); STAGE(SA(0, 0), A2, 0, k2);
;         BAR; WAIT_L(0); MMA(1, 0, At, B0); BAR; SCHED;
;         STAGE(SB(0, 1), B2, HALF, k2);
;         WAIT_V(6); BAR; MMA(1, 1, At, B1); BAR;
;         LDB(B0, 1, 0); SCHED; LDA(At, 1, 0); STAGE(SA(0, 1), A2, HALF, k2);
;         WAIT_L(8); BAR; WAIT_L(0); MMA(0, 0, At, B0); BAR; SCHED;
;         LDB(B1, 1, 1); STAGE(SB(1, 0), B2, 0, k2 + 1);
;         BAR; WAIT_L(0); MMA(0, 1, At, B1); BAR;
;         LDA(At, 1, 1); STAGE(SA(1, 0), A2, 0, k2 + 1);
;         BAR; WAIT_L(0); MMA(1, 0, At, B0); BAR; SCHED;
;         STAGE(SB(1, 1), B2, HALF, k2 + 1);
;         WAIT_V(6); BAR; MMA(1, 1, At, B1); BAR;
;       }
	s_add_u32 s50, s60, 0x160000
	s_addc_u32 s51, s51, 0
	s_add_u32 s44, s50, s44
	s_addc_u32 s45, s51, s45
	v_readfirstlane_b32 s43, v147
	v_lshl_add_u64 v[164:165], s[44:45], 0, v[130:131]
	s_mov_b32 m0, s43
	v_readfirstlane_b32 s43, v148
	global_load_lds_dwordx4 v[164:165], off
	v_lshl_add_u64 v[164:165], s[44:45], 0, v[132:133]
	s_mov_b32 m0, s43
	s_nop 0
	global_load_lds_dwordx4 v[164:165], off
	s_waitcnt vmcnt(6)
	s_barrier
	v_mfma_f32_16x16x32_bf16 v[54:57], v[226:229], v[180:183], v[54:57]
	v_mfma_f32_16x16x32_bf16 v[50:53], v[234:237], v[180:183], v[50:53]
	v_mfma_f32_16x16x32_bf16 v[38:41], v[226:229], v[202:205], v[38:41]
	v_mfma_f32_16x16x32_bf16 v[34:37], v[234:237], v[202:205], v[34:37]
	v_mfma_f32_16x16x32_bf16 v[22:25], v[226:229], v[210:213], v[22:25]
	v_mfma_f32_16x16x32_bf16 v[18:21], v[234:237], v[210:213], v[18:21]
	v_mfma_f32_16x16x32_bf16 v[6:9], v[226:229], v[218:221], v[6:9]
	v_mfma_f32_16x16x32_bf16 v[2:5], v[234:237], v[218:221], v[2:5]
	v_mfma_f32_16x16x32_bf16 v[54:57], v[230:233], v[198:201], v[54:57]
	v_mfma_f32_16x16x32_bf16 v[50:53], v[238:241], v[198:201], v[50:53]
	v_mfma_f32_16x16x32_bf16 v[38:41], v[230:233], v[206:209], v[38:41]
	v_mfma_f32_16x16x32_bf16 v[34:37], v[238:241], v[206:209], v[34:37]
	v_mfma_f32_16x16x32_bf16 v[22:25], v[230:233], v[214:217], v[22:25]
	v_mfma_f32_16x16x32_bf16 v[18:21], v[238:241], v[214:217], v[18:21]
	v_mfma_f32_16x16x32_bf16 v[6:9], v[230:233], v[222:225], v[6:9]
	v_mfma_f32_16x16x32_bf16 v[2:5], v[238:241], v[222:225], v[2:5]
	s_barrier
	ds_read_b128 v[164:167], v162
	ds_read_b128 v[168:171], v162 offset:1024
	ds_read_b128 v[172:175], v162 offset:2048
	ds_read_b128 v[176:179], v162 offset:3072
	s_add_u32 s44, s46, 0x160000
	s_addc_u32 s45, s47, 0
	v_readfirstlane_b32 s43, v149
	v_lshl_add_u64 v[226:227], s[44:45], 0, v[130:131]
	s_mov_b32 m0, s43
	v_readfirstlane_b32 s43, v150
	ds_read_b128 v[180:183], v157 offset:32768
	ds_read_b128 v[198:201], v157 offset:33792
	ds_read_b128 v[202:205], v158 offset:32768
	ds_read_b128 v[206:209], v158 offset:33792
	ds_read_b128 v[210:213], v159 offset:32768
	ds_read_b128 v[214:217], v159 offset:33792
	ds_read_b128 v[218:221], v160 offset:32768
	ds_read_b128 v[222:225], v160 offset:33792
	global_load_lds_dwordx4 v[226:227], off
	v_lshl_add_u64 v[226:227], s[44:45], 0, v[132:133]
	s_mov_b32 m0, s43
	s_nop 0
	global_load_lds_dwordx4 v[226:227], off
	s_waitcnt lgkmcnt(8)
	s_barrier
	s_waitcnt lgkmcnt(0)
	s_waitcnt lgkmcnt(0)
	v_mfma_f32_16x16x32_bf16 v[126:129], v[164:167], v[180:183], v[126:129]
	v_mfma_f32_16x16x32_bf16 v[122:125], v[172:175], v[180:183], v[122:125]
	v_mfma_f32_16x16x32_bf16 v[110:113], v[164:167], v[202:205], v[110:113]
	v_mfma_f32_16x16x32_bf16 v[106:109], v[172:175], v[202:205], v[106:109]
	v_mfma_f32_16x16x32_bf16 v[94:97], v[164:167], v[210:213], v[94:97]
	v_mfma_f32_16x16x32_bf16 v[90:93], v[172:175], v[210:213], v[90:93]
	v_mfma_f32_16x16x32_bf16 v[78:81], v[164:167], v[218:221], v[78:81]
	v_mfma_f32_16x16x32_bf16 v[74:77], v[172:175], v[218:221], v[74:77]
	v_mfma_f32_16x16x32_bf16 v[126:129], v[168:171], v[198:201], v[126:129]
	v_mfma_f32_16x16x32_bf16 v[122:125], v[176:179], v[198:201], v[122:125]
	v_mfma_f32_16x16x32_bf16 v[110:113], v[168:171], v[206:209], v[110:113]
	v_mfma_f32_16x16x32_bf16 v[106:109], v[176:179], v[206:209], v[106:109]
	v_mfma_f32_16x16x32_bf16 v[94:97], v[168:171], v[214:217], v[94:97]
	v_mfma_f32_16x16x32_bf16 v[90:93], v[176:179], v[214:217], v[90:93]
	v_mfma_f32_16x16x32_bf16 v[78:81], v[168:171], v[222:225], v[78:81]
	v_mfma_f32_16x16x32_bf16 v[74:77], v[176:179], v[222:225], v[74:77]
	s_barrier
	v_readfirstlane_b32 s43, v151
	v_lshl_add_u64 v[184:185], v[184:185], 0, s[18:19]
	s_mov_b32 m0, s43
	v_readfirstlane_b32 s43, v152
	ds_read_b128 v[226:229], v163
	ds_read_b128 v[230:233], v163 offset:1024
	ds_read_b128 v[234:237], v163 offset:2048
	ds_read_b128 v[238:241], v163 offset:3072
	global_load_lds_dwordx4 v[184:185], off
	v_lshl_add_u64 v[184:185], v[242:243], 0, s[18:19]
	s_mov_b32 m0, s43
	s_or_b32 s30, s30, 64
	global_load_lds_dwordx4 v[184:185], off
	s_barrier
	s_waitcnt lgkmcnt(0)
	s_waitcnt lgkmcnt(0)
	v_mfma_f32_16x16x32_bf16 v[118:121], v[226:229], v[180:183], v[118:121]
	v_mfma_f32_16x16x32_bf16 v[114:117], v[234:237], v[180:183], v[114:117]
	v_mfma_f32_16x16x32_bf16 v[102:105], v[226:229], v[202:205], v[102:105]
	v_mfma_f32_16x16x32_bf16 v[98:101], v[234:237], v[202:205], v[98:101]
	v_mfma_f32_16x16x32_bf16 v[86:89], v[226:229], v[210:213], v[86:89]
	v_mfma_f32_16x16x32_bf16 v[82:85], v[234:237], v[210:213], v[82:85]
	v_mfma_f32_16x16x32_bf16 v[70:73], v[226:229], v[218:221], v[70:73]
	v_mfma_f32_16x16x32_bf16 v[66:69], v[234:237], v[218:221], v[66:69]
	v_mfma_f32_16x16x32_bf16 v[118:121], v[230:233], v[198:201], v[118:121]
	v_mfma_f32_16x16x32_bf16 v[114:117], v[238:241], v[198:201], v[114:117]
	v_mfma_f32_16x16x32_bf16 v[102:105], v[230:233], v[206:209], v[102:105]
	v_mfma_f32_16x16x32_bf16 v[98:101], v[238:241], v[206:209], v[98:101]
	v_mfma_f32_16x16x32_bf16 v[86:89], v[230:233], v[214:217], v[86:89]
	v_mfma_f32_16x16x32_bf16 v[82:85], v[238:241], v[214:217], v[82:85]
	v_mfma_f32_16x16x32_bf16 v[70:73], v[230:233], v[222:225], v[70:73]
	v_mfma_f32_16x16x32_bf16 v[66:69], v[238:241], v[222:225], v[66:69]
	v_readfirstlane_b32 s43, v153
	v_lshl_add_u64 v[184:185], v[244:245], 0, s[18:19]
	s_mov_b32 m0, s43
	v_readfirstlane_b32 s43, v154
	s_barrier
; #define LDA(dst, b, h) _Pragma("unroll") for (int m = 0; m < 4; ++m) _Pragma("unroll") for (int k = 0; k < 2; ++k) \
;     dst[m][k] = *reinterpret_cast<const bf16x8*>((char*)SA(b, h) + lds_byte(wr * 64 + m * 16 + fr, k * 32 + fq * 8))
; #define LDB(dst, b, h) _Pragma("unroll") for (int n = 0; n < 2; ++n) _Pragma("unroll") for (int k = 0; k < 2; ++k) \
;     dst[n][k] = *reinterpret_cast<const bf16x8*>((char*)SB(b, h) + lds_byte(wc * 32 + n * 16 + fr, k * 32 + fq * 8))
; #define WAIT_V(n) asm volatile("s_waitcnt vmcnt(" #n ")" ::: "memory")
; #define WAIT_L(n) asm volatile("s_waitcnt lgkmcnt(" #n ")" ::: "memory")
; #define BAR __builtin_amdgcn_s_barrier()
; #define SCHED __builtin_amdgcn_sched_barrier(0)
; template <int MODE>
; __device__ __forceinline__ void gemm_epilogue(char* ws, const float* __restrict__ xseq, float* __restrict__ oseq, const int pm, const int pn,
;                                               f32x4 (&acc)[2][2][4][2], const int wave) {
;     ...
; #pragma unroll
;       for (int n = 0; n < 2; ++n)
; #pragma unroll
;       for (int bj = 0; bj < 2; ++bj) {
;         f32x4 v = acc[ai][bj][m][n];
;         const int col = bcol + bj * HALF + wc * 32 + n * 16 + fq * 4;
;         if (MODE == G_WO) {
;           const f32x4 xv = *(const f32x4*)(xseq + (long)row * DM + col);
;           v[0] += xv[0]; v[1] += xv[1]; v[2] += xv[2]; v[3] += xv[3];
;           *(f32x4*)(oseq + (long)row * DM + col) = v;
;         } else {
;           float* op = oseq + (long)row * DM + col;
;           const f32x4 xv = *(const f32x4*)op;
;           v[0] += xv[0]; v[1] += xv[1]; v[2] += xv[2]; v[3] += xv[3];
;           *(f32x4*)op = v;
;         }
; template <int MODE>
; __device__ __forceinline__ void gemm_phase(int s, char* lds, const int wave) {
;     ...
;         LDB(B0, 1, 0); SCHED; LDA(At, 1, 0); STAGE(SA(0, 1), A2, HALF, k2);
;         WAIT_L(8); BAR; WAIT_L(0); MMA(0, 0, At, B0); BAR; SCHED;
;         LDB(B1, 1, 1); STAGE(SB(1, 0), B2, 0, k2 + 1);
;         BAR; WAIT_L(0); MMA(0, 1, At, B1); BAR;
;         LDA(At, 1, 1); STAGE(SA(1, 0), A2, 0, k2 + 1);
;         BAR; WAIT_L(0); MMA(1, 0, At, B0); BAR; SCHED;
;         STAGE(SB(1, 1), B2, HALF, k2 + 1);
;         WAIT_V(6); BAR; MMA(1, 1, At, B1); BAR;
	ds_read_b128 v[180:183], v157 offset:49152
	ds_read_b128 v[198:201], v157 offset:50176
	ds_read_b128 v[202:205], v158 offset:49152
	ds_read_b128 v[206:209], v158 offset:50176
	ds_read_b128 v[210:213], v159 offset:49152
	ds_read_b128 v[214:217], v159 offset:50176
	ds_read_b128 v[218:221], v160 offset:49152
	ds_read_b128 v[222:225], v160 offset:50176
	global_load_lds_dwordx4 v[184:185], off
	v_lshl_add_u64 v[184:185], v[246:247], 0, s[18:19]
	s_mov_b32 m0, s43
	s_nop 0
	global_load_lds_dwordx4 v[184:185], off
	s_barrier
	s_waitcnt lgkmcnt(0)
	s_waitcnt lgkmcnt(0)
	v_mfma_f32_16x16x32_bf16 v[62:65], v[164:167], v[180:183], v[62:65]
	v_mfma_f32_16x16x32_bf16 v[58:61], v[172:175], v[180:183], v[58:61]
	v_mfma_f32_16x16x32_bf16 v[46:49], v[164:167], v[202:205], v[46:49]
	v_mfma_f32_16x16x32_bf16 v[42:45], v[172:175], v[202:205], v[42:45]
	v_mfma_f32_16x16x32_bf16 v[30:33], v[164:167], v[210:213], v[30:33]
	v_mfma_f32_16x16x32_bf16 v[26:29], v[172:175], v[210:213], v[26:29]
	v_mfma_f32_16x16x32_bf16 v[14:17], v[164:167], v[218:221], v[14:17]
	v_mfma_f32_16x16x32_bf16 v[10:13], v[172:175], v[218:221], v[10:13]
	v_mfma_f32_16x16x32_bf16 v[62:65], v[168:171], v[198:201], v[62:65]
	v_mfma_f32_16x16x32_bf16 v[58:61], v[176:179], v[198:201], v[58:61]
	v_mfma_f32_16x16x32_bf16 v[46:49], v[168:171], v[206:209], v[46:49]
	v_mfma_f32_16x16x32_bf16 v[42:45], v[176:179], v[206:209], v[42:45]
	v_mfma_f32_16x16x32_bf16 v[30:33], v[168:171], v[214:217], v[30:33]
	v_mfma_f32_16x16x32_bf16 v[26:29], v[176:179], v[214:217], v[26:29]
	v_mfma_f32_16x16x32_bf16 v[14:17], v[168:171], v[222:225], v[14:17]
	v_mfma_f32_16x16x32_bf16 v[10:13], v[176:179], v[222:225], v[10:13]
	s_barrier
	v_lshl_add_u64 v[164:165], s[50:51], 0, v[130:131]
	s_lshl_b64 s[44:45], s[30:31], 1
	v_readfirstlane_b32 s30, v155
	v_lshl_add_u64 v[164:165], v[164:165], 0, s[44:45]
	s_mov_b32 m0, s30
	v_readfirstlane_b32 s30, v156
	global_load_lds_dwordx4 v[164:165], off
	v_lshl_add_u64 v[164:165], s[50:51], 0, v[132:133]
	v_lshl_add_u64 v[164:165], v[164:165], 0, s[44:45]
	s_mov_b32 m0, s30
	s_nop 0
	global_load_lds_dwordx4 v[164:165], off
	s_waitcnt vmcnt(6)
	s_barrier
	v_mfma_f32_16x16x32_bf16 v[54:57], v[226:229], v[180:183], v[54:57]
	v_mfma_f32_16x16x32_bf16 v[50:53], v[234:237], v[180:183], v[50:53]
	v_mfma_f32_16x16x32_bf16 v[38:41], v[226:229], v[202:205], v[38:41]
	v_mfma_f32_16x16x32_bf16 v[34:37], v[234:237], v[202:205], v[34:37]
	v_mfma_f32_16x16x32_bf16 v[22:25], v[226:229], v[210:213], v[22:25]
	v_mfma_f32_16x16x32_bf16 v[18:21], v[234:237], v[210:213], v[18:21]
	v_mfma_f32_16x16x32_bf16 v[6:9], v[226:229], v[218:221], v[6:9]
	v_mfma_f32_16x16x32_bf16 v[2:5], v[234:237], v[218:221], v[2:5]
	v_mfma_f32_16x16x32_bf16 v[54:57], v[230:233], v[198:201], v[54:57]
	v_mfma_f32_16x16x32_bf16 v[50:53], v[238:241], v[198:201], v[50:53]
	v_mfma_f32_16x16x32_bf16 v[38:41], v[230:233], v[206:209], v[38:41]
	v_mfma_f32_16x16x32_bf16 v[34:37], v[238:241], v[206:209], v[34:37]
	v_mfma_f32_16x16x32_bf16 v[22:25], v[230:233], v[214:217], v[22:25]
	v_mfma_f32_16x16x32_bf16 v[18:21], v[238:241], v[214:217], v[18:21]
	v_mfma_f32_16x16x32_bf16 v[6:9], v[230:233], v[222:225], v[6:9]
	v_mfma_f32_16x16x32_bf16 v[2:5], v[238:241], v[222:225], v[2:5]
	v_lshl_add_u64 v[138:139], v[138:139], 0, s[38:39]
	v_lshl_add_u64 v[140:141], v[140:141], 0, s[38:39]
	s_addk_i32 s42, 0x80
	s_barrier
	s_cbranch_vccz .LBB0_645
	v_mov_b32_e32 v138, v187
	s_lshl_b32 s2, s2, 8
	v_ashrrev_i32_e32 v139, 2, v138
	v_and_b32_e32 v139, 0xffffffc0, v139
	v_and_or_b32 v140, v138, 15, s2
	v_add_u32_e32 v140, v140, v139
	v_lshrrev_b32_e32 v139, 1, v138
	v_lshrrev_b32_e32 v138, 2, v138
	s_lshl_b32 s12, s40, 8
	v_and_b32_e32 v139, 0x60, v139
	v_and_b32_e32 v138, 12, v138
	v_or3_b32 v138, v139, s12, v138
	v_ashrrev_i32_e32 v141, 31, v140
	v_ashrrev_i32_e32 v139, 31, v138
	v_lshlrev_b64 v[138:139], 2, v[138:139]
	s_cmpk_gt_i32 s52, 0x5ff
	s_mov_b64 s[14:15], s[10:11]
	s_mov_b64 s[12:13], s[6:7]
	s_mov_b32 s40, s58
	s_mov_b32 s2, s59
	v_lshlrev_b64 v[178:179], 13, v[140:141]
	v_lshl_add_u64 v[164:165], s[4:5], 0, v[178:179]
	v_lshl_add_u64 v[164:165], v[164:165], 0, v[138:139]
	global_load_dwordx4 v[198:201], v[164:165], off
	global_load_dwordx4 v[202:205], v[164:165], off offset:512
	global_load_dwordx4 v[206:209], v[164:165], off offset:64
	global_load_dwordx4 v[210:213], v[164:165], off offset:576
	v_or_b32_e32 v176, 16, v140
	v_ashrrev_i32_e32 v177, 31, v176
	v_lshlrev_b64 v[178:179], 13, v[176:177]
	v_lshl_add_u64 v[168:169], s[4:5], 0, v[178:179]
	v_lshl_add_u64 v[168:169], v[168:169], 0, v[138:139]
	global_load_dwordx4 v[214:217], v[168:169], off
	global_load_dwordx4 v[218:221], v[168:169], off offset:512
	global_load_dwordx4 v[222:225], v[168:169], off offset:64
	global_load_dwordx4 v[226:229], v[168:169], off offset:576
	v_or_b32_e32 v176, 32, v140
	v_ashrrev_i32_e32 v177, 31, v176
	v_lshlrev_b64 v[178:179], 13, v[176:177]
	v_lshl_add_u64 v[172:173], s[4:5], 0, v[178:179]
	v_lshl_add_u64 v[172:173], v[172:173], 0, v[138:139]
	global_load_dwordx4 v[230:233], v[172:173], off
	global_load_dwordx4 v[234:237], v[172:173], off offset:512
	global_load_dwordx4 v[238:241], v[172:173], off offset:64
	global_load_dwordx4 v[242:245], v[172:173], off offset:576
	s_waitcnt vmcnt(11)
	v_pk_add_f32 v[200:201], v[128:129], v[200:201]
	v_pk_add_f32 v[198:199], v[126:127], v[198:199]
	s_waitcnt vmcnt(10)
	v_pk_add_f32 v[204:205], v[120:121], v[204:205]
	v_pk_add_f32 v[202:203], v[118:119], v[202:203]
	s_waitcnt vmcnt(9)
	v_pk_add_f32 v[208:209], v[124:125], v[208:209]
	v_pk_add_f32 v[206:207], v[122:123], v[206:207]
	s_waitcnt vmcnt(8)
; template <int MODE>
; __device__ __forceinline__ void gemm_epilogue(char* ws, const float* __restrict__ xseq, float* __restrict__ oseq, const int pm, const int pn,
;                                               f32x4 (&acc)[2][2][4][2], const int wave) {
;     ...
; #pragma unroll
;       for (int n = 0; n < 2; ++n)
; #pragma unroll
;       for (int bj = 0; bj < 2; ++bj) {
;         f32x4 v = acc[ai][bj][m][n];
;         const int col = bcol + bj * HALF + wc * 32 + n * 16 + fq * 4;
;         if (MODE == G_WO) {
;           const f32x4 xv = *(const f32x4*)(xseq + (long)row * DM + col);
;           v[0] += xv[0]; v[1] += xv[1]; v[2] += xv[2]; v[3] += xv[3];
;           *(f32x4*)(oseq + (long)row * DM + col) = v;
;         } else {
;           float* op = oseq + (long)row * DM + col;
;           const f32x4 xv = *(const f32x4*)op;
;           v[0] += xv[0]; v[1] += xv[1]; v[2] += xv[2]; v[3] += xv[3];
;           *(f32x4*)op = v;
;         }
	v_pk_add_f32 v[212:213], v[116:117], v[212:213]
	v_pk_add_f32 v[210:211], v[114:115], v[210:211]
	global_store_dwordx4 v[164:165], v[198:201], off
	global_store_dwordx4 v[164:165], v[202:205], off offset:512
	global_store_dwordx4 v[164:165], v[206:209], off offset:64
	global_store_dwordx4 v[164:165], v[210:213], off offset:576
	v_or_b32_e32 v176, 48, v140
	v_ashrrev_i32_e32 v177, 31, v176
	v_lshlrev_b64 v[178:179], 13, v[176:177]
	v_lshl_add_u64 v[164:165], s[4:5], 0, v[178:179]
	v_lshl_add_u64 v[164:165], v[164:165], 0, v[138:139]
	global_load_dwordx4 v[198:201], v[164:165], off
	global_load_dwordx4 v[202:205], v[164:165], off offset:512
	global_load_dwordx4 v[206:209], v[164:165], off offset:64
	global_load_dwordx4 v[210:213], v[164:165], off offset:576
	s_waitcnt vmcnt(15)
	v_pk_add_f32 v[216:217], v[112:113], v[216:217]
	v_pk_add_f32 v[214:215], v[110:111], v[214:215]
	s_waitcnt vmcnt(14)
	v_pk_add_f32 v[220:221], v[104:105], v[220:221]
	v_pk_add_f32 v[218:219], v[102:103], v[218:219]
	s_waitcnt vmcnt(13)
	v_pk_add_f32 v[224:225], v[108:109], v[224:225]
	v_pk_add_f32 v[222:223], v[106:107], v[222:223]
	s_waitcnt vmcnt(12)
	v_pk_add_f32 v[228:229], v[100:101], v[228:229]
	v_pk_add_f32 v[226:227], v[98:99], v[226:227]
	global_store_dwordx4 v[168:169], v[214:217], off
	global_store_dwordx4 v[168:169], v[218:221], off offset:512
	global_store_dwordx4 v[168:169], v[222:225], off offset:64
	global_store_dwordx4 v[168:169], v[226:229], off offset:576
	v_add_u32_e32 v176, 0x80, v140
	v_ashrrev_i32_e32 v177, 31, v176
	v_lshlrev_b64 v[178:179], 13, v[176:177]
	v_lshl_add_u64 v[168:169], s[4:5], 0, v[178:179]
	v_lshl_add_u64 v[168:169], v[168:169], 0, v[138:139]
	global_load_dwordx4 v[214:217], v[168:169], off
	global_load_dwordx4 v[218:221], v[168:169], off offset:512
	global_load_dwordx4 v[222:225], v[168:169], off offset:64
	global_load_dwordx4 v[226:229], v[168:169], off offset:576
	s_waitcnt vmcnt(19)
	v_pk_add_f32 v[232:233], v[96:97], v[232:233]
	v_pk_add_f32 v[230:231], v[94:95], v[230:231]
	s_waitcnt vmcnt(18)
	v_pk_add_f32 v[236:237], v[88:89], v[236:237]
	v_pk_add_f32 v[234:235], v[86:87], v[234:235]
	s_waitcnt vmcnt(17)
	v_pk_add_f32 v[240:241], v[92:93], v[240:241]
	v_pk_add_f32 v[238:239], v[90:91], v[238:239]
	s_waitcnt vmcnt(16)
	v_pk_add_f32 v[244:245], v[84:85], v[244:245]
	v_pk_add_f32 v[242:243], v[82:83], v[242:243]
	global_store_dwordx4 v[172:173], v[230:233], off
	global_store_dwordx4 v[172:173], v[234:237], off offset:512
	global_store_dwordx4 v[172:173], v[238:241], off offset:64
	global_store_dwordx4 v[172:173], v[242:245], off offset:576
	v_add_u32_e32 v176, 0x90, v140
	v_ashrrev_i32_e32 v177, 31, v176
	v_lshlrev_b64 v[178:179], 13, v[176:177]
	v_lshl_add_u64 v[172:173], s[4:5], 0, v[178:179]
	v_lshl_add_u64 v[172:173], v[172:173], 0, v[138:139]
	global_load_dwordx4 v[230:233], v[172:173], off
	global_load_dwordx4 v[234:237], v[172:173], off offset:512
	global_load_dwordx4 v[238:241], v[172:173], off offset:64
	global_load_dwordx4 v[242:245], v[172:173], off offset:576
	s_waitcnt vmcnt(19)
	v_pk_add_f32 v[200:201], v[80:81], v[200:201]
	v_pk_add_f32 v[198:199], v[78:79], v[198:199]
	s_waitcnt vmcnt(18)
	v_pk_add_f32 v[204:205], v[72:73], v[204:205]
	v_pk_add_f32 v[202:203], v[70:71], v[202:203]
	s_waitcnt vmcnt(17)
	v_pk_add_f32 v[208:209], v[76:77], v[208:209]
	v_pk_add_f32 v[206:207], v[74:75], v[206:207]
	s_waitcnt vmcnt(16)
; #define WAIT_V(n) asm volatile("s_waitcnt vmcnt(" #n ")" ::: "memory")
; #define BAR __builtin_amdgcn_s_barrier()
; template <int MODE>
; __device__ __forceinline__ void gemm_epilogue(char* ws, const float* __restrict__ xseq, float* __restrict__ oseq, const int pm, const int pn,
;                                               f32x4 (&acc)[2][2][4][2], const int wave) {
;     ...
; #pragma unroll
;       for (int n = 0; n < 2; ++n)
; #pragma unroll
;       for (int bj = 0; bj < 2; ++bj) {
;         f32x4 v = acc[ai][bj][m][n];
;         const int col = bcol + bj * HALF + wc * 32 + n * 16 + fq * 4;
;         if (MODE == G_WO) {
;           const f32x4 xv = *(const f32x4*)(xseq + (long)row * DM + col);
;           v[0] += xv[0]; v[1] += xv[1]; v[2] += xv[2]; v[3] += xv[3];
;           *(f32x4*)(oseq + (long)row * DM + col) = v;
;         } else {
;           float* op = oseq + (long)row * DM + col;
;           const f32x4 xv = *(const f32x4*)op;
;           v[0] += xv[0]; v[1] += xv[1]; v[2] += xv[2]; v[3] += xv[3];
;           *(f32x4*)op = v;
;         }
; template <int MODE>
; __device__ __forceinline__ void gemm_phase(int s, char* lds, const int wave) {
;     ...
;       if (ntile >= nwg) break;
;       tile = ntile; pm = pm2; pn = pn2; Acur = Anext; Bcur = Bnext;
;     }
;     WAIT_V(0);
;     if (wr == 0) BAR;
;   }
	v_pk_add_f32 v[212:213], v[68:69], v[212:213]
	v_pk_add_f32 v[210:211], v[66:67], v[210:211]
	global_store_dwordx4 v[164:165], v[198:201], off
	global_store_dwordx4 v[164:165], v[202:205], off offset:512
	global_store_dwordx4 v[164:165], v[206:209], off offset:64
	global_store_dwordx4 v[164:165], v[210:213], off offset:576
	v_add_u32_e32 v176, 0xa0, v140
	v_ashrrev_i32_e32 v177, 31, v176
	v_lshlrev_b64 v[178:179], 13, v[176:177]
	v_lshl_add_u64 v[164:165], s[4:5], 0, v[178:179]
	v_lshl_add_u64 v[164:165], v[164:165], 0, v[138:139]
	global_load_dwordx4 v[198:201], v[164:165], off
	global_load_dwordx4 v[202:205], v[164:165], off offset:512
	global_load_dwordx4 v[206:209], v[164:165], off offset:64
	global_load_dwordx4 v[210:213], v[164:165], off offset:576
	s_waitcnt vmcnt(19)
	v_pk_add_f32 v[216:217], v[64:65], v[216:217]
	v_pk_add_f32 v[214:215], v[62:63], v[214:215]
	s_waitcnt vmcnt(18)
	v_pk_add_f32 v[220:221], v[56:57], v[220:221]
	v_pk_add_f32 v[218:219], v[54:55], v[218:219]
	s_waitcnt vmcnt(17)
	v_pk_add_f32 v[224:225], v[60:61], v[224:225]
	v_pk_add_f32 v[222:223], v[58:59], v[222:223]
	s_waitcnt vmcnt(16)
	v_pk_add_f32 v[228:229], v[52:53], v[228:229]
	v_pk_add_f32 v[226:227], v[50:51], v[226:227]
	global_store_dwordx4 v[168:169], v[214:217], off
	global_store_dwordx4 v[168:169], v[218:221], off offset:512
	global_store_dwordx4 v[168:169], v[222:225], off offset:64
	global_store_dwordx4 v[168:169], v[226:229], off offset:576
	v_add_u32_e32 v176, 0xb0, v140
	v_ashrrev_i32_e32 v177, 31, v176
	v_lshlrev_b64 v[178:179], 13, v[176:177]
	v_lshl_add_u64 v[168:169], s[4:5], 0, v[178:179]
	v_lshl_add_u64 v[168:169], v[168:169], 0, v[138:139]
	global_load_dwordx4 v[214:217], v[168:169], off
	global_load_dwordx4 v[218:221], v[168:169], off offset:512
	global_load_dwordx4 v[222:225], v[168:169], off offset:64
	global_load_dwordx4 v[226:229], v[168:169], off offset:576
	s_waitcnt vmcnt(19)
	v_pk_add_f32 v[232:233], v[48:49], v[232:233]
	v_pk_add_f32 v[230:231], v[46:47], v[230:231]
	s_waitcnt vmcnt(18)
	v_pk_add_f32 v[236:237], v[40:41], v[236:237]
	v_pk_add_f32 v[234:235], v[38:39], v[234:235]
	s_waitcnt vmcnt(17)
	v_pk_add_f32 v[240:241], v[44:45], v[240:241]
	v_pk_add_f32 v[238:239], v[42:43], v[238:239]
	s_waitcnt vmcnt(16)
	v_pk_add_f32 v[244:245], v[36:37], v[244:245]
	v_pk_add_f32 v[242:243], v[34:35], v[242:243]
	global_store_dwordx4 v[172:173], v[230:233], off
	global_store_dwordx4 v[172:173], v[234:237], off offset:512
	global_store_dwordx4 v[172:173], v[238:241], off offset:64
	global_store_dwordx4 v[172:173], v[242:245], off offset:576
	s_waitcnt vmcnt(15)
	v_pk_add_f32 v[200:201], v[32:33], v[200:201]
	v_pk_add_f32 v[198:199], v[30:31], v[198:199]
	s_waitcnt vmcnt(14)
	v_pk_add_f32 v[204:205], v[24:25], v[204:205]
	v_pk_add_f32 v[202:203], v[22:23], v[202:203]
	s_waitcnt vmcnt(13)
	v_pk_add_f32 v[208:209], v[28:29], v[208:209]
	v_pk_add_f32 v[206:207], v[26:27], v[206:207]
	s_waitcnt vmcnt(12)
	v_pk_add_f32 v[212:213], v[20:21], v[212:213]
	v_pk_add_f32 v[210:211], v[18:19], v[210:211]
	global_store_dwordx4 v[164:165], v[198:201], off
	global_store_dwordx4 v[164:165], v[202:205], off offset:512
	global_store_dwordx4 v[164:165], v[206:209], off offset:64
	global_store_dwordx4 v[164:165], v[210:213], off offset:576
	s_waitcnt vmcnt(11)
	v_pk_add_f32 v[216:217], v[16:17], v[216:217]
	v_pk_add_f32 v[214:215], v[14:15], v[214:215]
	s_waitcnt vmcnt(10)
	v_pk_add_f32 v[220:221], v[8:9], v[220:221]
	v_pk_add_f32 v[218:219], v[6:7], v[218:219]
	s_waitcnt vmcnt(9)
	v_pk_add_f32 v[224:225], v[12:13], v[224:225]
	v_pk_add_f32 v[222:223], v[10:11], v[222:223]
	s_waitcnt vmcnt(8)
	v_pk_add_f32 v[228:229], v[4:5], v[228:229]
	v_pk_add_f32 v[226:227], v[2:3], v[226:227]
	global_store_dwordx4 v[168:169], v[214:217], off
	global_store_dwordx4 v[168:169], v[218:221], off offset:512
	global_store_dwordx4 v[168:169], v[222:225], off offset:64
	global_store_dwordx4 v[168:169], v[226:229], off offset:576
	s_cbranch_scc0 .LBB0_642
	s_waitcnt vmcnt(0)
	s_movk_i32 s2, 0x100
	v_cmp_gt_u32_e32 vcc, s2, v142
	s_and_saveexec_b64 s[4:5], vcc
	s_cbranch_execz .LBB0_649
	s_barrier
